# K-loops: s_waitcnt vmcnt(8) + s_waitcnt lgkmcnt(0) before each load-segment barrier merged into one instruction (strategy 1)
# speedup vs baseline: 1.0041x; 1.0041x over previous
.LBB0_354:
	s_ashr_i32 s13, s12, 31
	s_lshl_b64 s[14:15], s[12:13], 20
	s_add_u32 s14, s41, s14
	s_addc_u32 s15, s42, s15
	s_and_b64 s[16:17], s[4:5], exec
	s_cselect_b32 s13, s15, s23
	s_cselect_b32 s91, s14, s22
	s_ashr_i32 s11, s10, 31
	s_lshl_b64 s[16:17], s[10:11], 20
	s_add_u32 s16, s45, s16
	s_addc_u32 s17, s65, s17
	s_and_b64 s[54:55], s[4:5], exec
	s_cselect_b32 s11, s17, s53
	s_cselect_b32 s92, s16, s52
	s_add_u32 s22, s22, 0x80080
	s_addc_u32 s23, s23, 0
	s_add_u32 s93, s52, 0x100
	v_mov_b32_e32 v4, 0
	s_addc_u32 s94, s53, 0
	s_mov_b32 s95, -2
	s_add_u32 s52, s22, 0xfff80080
	s_addc_u32 s53, s23, -1
	s_add_i32 s58, 0, 0x10000
	s_cmp_eq_u32 s95, 28
	s_cselect_b32 s55, s13, s53
	s_cselect_b32 s54, s91, s52
	v_add_u32_e32 v138, s58, v141
	s_cselect_b32 s53, s11, s94
	s_cselect_b32 s52, s92, s93
	s_add_i32 s59, 0, 0x14000
	ds_read_b128 v[144:147], v138
	ds_read_b128 v[148:151], v138 offset:1024
	ds_read_b128 v[152:155], v138 offset:2048
	ds_read_b128 v[156:159], v138 offset:3072
	v_add_u32_e32 v138, s59, v141
	ds_read_b128 v[160:163], v138
	ds_read_b128 v[164:167], v138 offset:1024
	ds_read_b128 v[168:171], v138 offset:2048
	ds_read_b128 v[172:175], v138 offset:3072
	v_lshl_add_u64 v[138:139], s[22:23], 0, v[134:135]
	s_add_i32 m0, s76, 0xc000
	ds_read_b128 v[176:179], v143
	ds_read_b128 v[180:183], v143 offset:1024
	ds_read_b128 v[184:187], v143 offset:2048
	ds_read_b128 v[188:191], v143 offset:3072
	ds_read_b128 v[196:199], v143 offset:4096
	ds_read_b128 v[200:203], v143 offset:5120
	ds_read_b128 v[204:207], v143 offset:6144
	ds_read_b128 v[208:211], v143 offset:7168
	global_load_lds_dwordx4 v[138:139], off
	v_lshl_add_u64 v[138:139], s[22:23], 0, v[136:137]
	s_add_i32 m0, s76, 0xe000
	s_nop 0
	global_load_lds_dwordx4 v[138:139], off
	s_waitcnt vmcnt(8) lgkmcnt(0)
	s_barrier
	v_mfma_f32_16x16x32_bf16 v[120:123], v[144:147], v[176:179], 0
	v_mfma_f32_16x16x32_bf16 v[120:123], v[148:151], v[180:183], v[120:123]
	v_mfma_f32_16x16x32_bf16 v[104:107], v[144:147], v[184:187], 0
	v_mfma_f32_16x16x32_bf16 v[104:107], v[148:151], v[188:191], v[104:107]
	v_mfma_f32_16x16x32_bf16 v[88:91], v[144:147], v[196:199], 0
	v_mfma_f32_16x16x32_bf16 v[88:91], v[148:151], v[200:203], v[88:91]
	v_mfma_f32_16x16x32_bf16 v[72:75], v[144:147], v[204:207], 0
	v_mfma_f32_16x16x32_bf16 v[72:75], v[148:151], v[208:211], v[72:75]
	v_mfma_f32_16x16x32_bf16 v[112:115], v[152:155], v[176:179], 0
	v_mfma_f32_16x16x32_bf16 v[112:115], v[156:159], v[180:183], v[112:115]
	v_mfma_f32_16x16x32_bf16 v[96:99], v[152:155], v[184:187], 0
	v_mfma_f32_16x16x32_bf16 v[96:99], v[156:159], v[188:191], v[96:99]
	v_mfma_f32_16x16x32_bf16 v[80:83], v[152:155], v[196:199], 0
	v_mfma_f32_16x16x32_bf16 v[80:83], v[156:159], v[200:203], v[80:83]
	v_mfma_f32_16x16x32_bf16 v[64:67], v[152:155], v[204:207], 0
	v_mfma_f32_16x16x32_bf16 v[64:67], v[156:159], v[208:211], v[64:67]
	v_mfma_f32_16x16x32_bf16 v[124:127], v[160:163], v[176:179], 0
	v_mfma_f32_16x16x32_bf16 v[124:127], v[164:167], v[180:183], v[124:127]
	v_mfma_f32_16x16x32_bf16 v[108:111], v[160:163], v[184:187], 0
	v_mfma_f32_16x16x32_bf16 v[108:111], v[164:167], v[188:191], v[108:111]
	v_mfma_f32_16x16x32_bf16 v[92:95], v[160:163], v[196:199], 0
	v_mfma_f32_16x16x32_bf16 v[92:95], v[164:167], v[200:203], v[92:95]
	v_mfma_f32_16x16x32_bf16 v[76:79], v[160:163], v[204:207], 0
	v_mfma_f32_16x16x32_bf16 v[76:79], v[164:167], v[208:211], v[76:79]
	v_mfma_f32_16x16x32_bf16 v[116:119], v[168:171], v[176:179], 0
	v_mfma_f32_16x16x32_bf16 v[116:119], v[172:175], v[180:183], v[116:119]
	v_mfma_f32_16x16x32_bf16 v[100:103], v[168:171], v[184:187], 0
	v_mfma_f32_16x16x32_bf16 v[100:103], v[172:175], v[188:191], v[100:103]
	v_mfma_f32_16x16x32_bf16 v[84:87], v[168:171], v[196:199], 0
	v_mfma_f32_16x16x32_bf16 v[84:87], v[172:175], v[200:203], v[84:87]
	v_mfma_f32_16x16x32_bf16 v[68:71], v[168:171], v[204:207], 0
	v_mfma_f32_16x16x32_bf16 v[68:71], v[172:175], v[208:211], v[68:71]
	s_barrier
	s_add_i32 s58, s58, s50
	v_lshl_add_u64 v[138:139], s[52:53], 0, v[216:217]
	s_mov_b32 m0, s58
	ds_read_b128 v[176:179], v143 offset:16384
	ds_read_b128 v[180:183], v143 offset:17408
	ds_read_b128 v[184:187], v143 offset:18432
	ds_read_b128 v[188:191], v143 offset:19456
	ds_read_b128 v[196:199], v143 offset:20480
	ds_read_b128 v[200:203], v143 offset:21504
	ds_read_b128 v[204:207], v143 offset:22528
	ds_read_b128 v[208:211], v143 offset:23552
	global_load_lds_dwordx4 v[138:139], off
	s_add_i32 m0, s58, 0x2000
	s_add_u32 s96, s52, 0x80000
	v_lshl_add_u64 v[192:193], s[52:53], 0, v[132:133]
	s_addc_u32 s97, s53, 0
	s_add_i32 s58, s59, s50
	global_load_lds_dwordx4 v[192:193], off
	v_lshl_add_u64 v[212:213], s[96:97], 0, v[216:217]
	s_mov_b32 m0, s58
	v_lshl_add_u64 v[214:215], s[54:55], 0, v[130:131]
	global_load_lds_dwordx4 v[212:213], off
	v_lshl_add_u64 v[212:213], s[96:97], 0, v[132:133]
	s_add_i32 m0, s58, 0x2000
	s_nop 0
	global_load_lds_dwordx4 v[212:213], off
	v_lshl_add_u64 v[212:213], s[54:55], 0, v[128:129]
	s_mov_b32 m0, s76
	s_nop 0
	global_load_lds_dwordx4 v[212:213], off
	s_mov_b32 m0, s74
	s_nop 0
	global_load_lds_dwordx4 v[214:215], off
	s_waitcnt vmcnt(8) lgkmcnt(0)
	s_barrier
	v_mfma_f32_16x16x32_bf16 v[56:59], v[144:147], v[176:179], 0
	v_mfma_f32_16x16x32_bf16 v[56:59], v[148:151], v[180:183], v[56:59]
	v_mfma_f32_16x16x32_bf16 v[40:43], v[144:147], v[184:187], 0
	v_mfma_f32_16x16x32_bf16 v[40:43], v[148:151], v[188:191], v[40:43]
	v_mfma_f32_16x16x32_bf16 v[24:27], v[144:147], v[196:199], 0
	v_mfma_f32_16x16x32_bf16 v[24:27], v[148:151], v[200:203], v[24:27]
	v_mfma_f32_16x16x32_bf16 v[8:11], v[144:147], v[204:207], 0
	v_mfma_f32_16x16x32_bf16 v[8:11], v[148:151], v[208:211], v[8:11]
	v_mfma_f32_16x16x32_bf16 v[48:51], v[152:155], v[176:179], 0
	v_mfma_f32_16x16x32_bf16 v[48:51], v[156:159], v[180:183], v[48:51]
	v_mfma_f32_16x16x32_bf16 v[32:35], v[152:155], v[184:187], 0
	v_mfma_f32_16x16x32_bf16 v[32:35], v[156:159], v[188:191], v[32:35]
	v_mfma_f32_16x16x32_bf16 v[16:19], v[152:155], v[196:199], 0
	v_mfma_f32_16x16x32_bf16 v[16:19], v[156:159], v[200:203], v[16:19]
	v_mfma_f32_16x16x32_bf16 v[0:3], v[152:155], v[204:207], 0
	v_mfma_f32_16x16x32_bf16 v[0:3], v[156:159], v[208:211], v[0:3]
	v_mfma_f32_16x16x32_bf16 v[60:63], v[160:163], v[176:179], 0
	v_mfma_f32_16x16x32_bf16 v[60:63], v[164:167], v[180:183], v[60:63]
	v_mfma_f32_16x16x32_bf16 v[44:47], v[160:163], v[184:187], 0
	v_mfma_f32_16x16x32_bf16 v[44:47], v[164:167], v[188:191], v[44:47]
	v_mfma_f32_16x16x32_bf16 v[28:31], v[160:163], v[196:199], 0
	v_mfma_f32_16x16x32_bf16 v[28:31], v[164:167], v[200:203], v[28:31]
	v_mfma_f32_16x16x32_bf16 v[12:15], v[160:163], v[204:207], 0
	v_mfma_f32_16x16x32_bf16 v[12:15], v[164:167], v[208:211], v[12:15]
	v_mfma_f32_16x16x32_bf16 v[52:55], v[168:171], v[176:179], 0
	v_mfma_f32_16x16x32_bf16 v[52:55], v[172:175], v[180:183], v[52:55]
	v_mfma_f32_16x16x32_bf16 v[36:39], v[168:171], v[184:187], 0
	v_mfma_f32_16x16x32_bf16 v[36:39], v[172:175], v[188:191], v[36:39]
	v_mfma_f32_16x16x32_bf16 v[20:23], v[168:171], v[196:199], 0
	v_mfma_f32_16x16x32_bf16 v[20:23], v[172:175], v[200:203], v[20:23]
	v_mfma_f32_16x16x32_bf16 v[4:7], v[168:171], v[204:207], 0
	v_mfma_f32_16x16x32_bf16 v[4:7], v[172:175], v[208:211], v[4:7]
	s_barrier
	s_add_i32 s58, 0, 0x18000
	s_add_i32 s59, 0, 0x1c000
	v_add_u32_e32 v156, s58, v141
	v_add_u32_e32 v172, s59, v141
	ds_read_b128 v[144:147], v156
	ds_read_b128 v[148:151], v156 offset:1024
	ds_read_b128 v[152:155], v156 offset:2048
	ds_read_b128 v[156:159], v156 offset:3072
	ds_read_b128 v[160:163], v172
	ds_read_b128 v[164:167], v172 offset:1024
	ds_read_b128 v[168:171], v172 offset:2048
	ds_read_b128 v[172:175], v172 offset:3072
	s_add_u32 s54, s54, 0x80000
	s_addc_u32 s55, s55, 0
	s_mov_b32 m0, s85
	v_lshl_add_u64 v[218:219], s[54:55], 0, v[128:129]
	ds_read_b128 v[176:179], v143 offset:32768
	ds_read_b128 v[180:183], v143 offset:33792
	ds_read_b128 v[184:187], v143 offset:34816
	ds_read_b128 v[188:191], v143 offset:35840
	ds_read_b128 v[196:199], v143 offset:36864
	ds_read_b128 v[200:203], v143 offset:37888
	ds_read_b128 v[204:207], v143 offset:38912
	ds_read_b128 v[208:211], v143 offset:39936
	global_load_lds_dwordx4 v[218:219], off
	v_lshl_add_u64 v[218:219], s[54:55], 0, v[130:131]
	s_mov_b32 m0, s86
	s_nop 0
	global_load_lds_dwordx4 v[218:219], off
	s_waitcnt vmcnt(8) lgkmcnt(0)
	s_barrier
	v_mfma_f32_16x16x32_bf16 v[120:123], v[144:147], v[176:179], v[120:123]
	v_mfma_f32_16x16x32_bf16 v[120:123], v[148:151], v[180:183], v[120:123]
	v_mfma_f32_16x16x32_bf16 v[104:107], v[144:147], v[184:187], v[104:107]
	v_mfma_f32_16x16x32_bf16 v[104:107], v[148:151], v[188:191], v[104:107]
	v_mfma_f32_16x16x32_bf16 v[88:91], v[144:147], v[196:199], v[88:91]
	v_mfma_f32_16x16x32_bf16 v[88:91], v[148:151], v[200:203], v[88:91]
	v_mfma_f32_16x16x32_bf16 v[72:75], v[144:147], v[204:207], v[72:75]
	v_mfma_f32_16x16x32_bf16 v[72:75], v[148:151], v[208:211], v[72:75]
	v_mfma_f32_16x16x32_bf16 v[112:115], v[152:155], v[176:179], v[112:115]
	v_mfma_f32_16x16x32_bf16 v[112:115], v[156:159], v[180:183], v[112:115]
	v_mfma_f32_16x16x32_bf16 v[96:99], v[152:155], v[184:187], v[96:99]
	v_mfma_f32_16x16x32_bf16 v[96:99], v[156:159], v[188:191], v[96:99]
	v_mfma_f32_16x16x32_bf16 v[80:83], v[152:155], v[196:199], v[80:83]
	v_mfma_f32_16x16x32_bf16 v[80:83], v[156:159], v[200:203], v[80:83]
	v_mfma_f32_16x16x32_bf16 v[64:67], v[152:155], v[204:207], v[64:67]
	v_mfma_f32_16x16x32_bf16 v[64:67], v[156:159], v[208:211], v[64:67]
	v_mfma_f32_16x16x32_bf16 v[124:127], v[160:163], v[176:179], v[124:127]
	v_mfma_f32_16x16x32_bf16 v[124:127], v[164:167], v[180:183], v[124:127]
	v_mfma_f32_16x16x32_bf16 v[108:111], v[160:163], v[184:187], v[108:111]
	v_mfma_f32_16x16x32_bf16 v[108:111], v[164:167], v[188:191], v[108:111]
	v_mfma_f32_16x16x32_bf16 v[92:95], v[160:163], v[196:199], v[92:95]
	v_mfma_f32_16x16x32_bf16 v[92:95], v[164:167], v[200:203], v[92:95]
	v_mfma_f32_16x16x32_bf16 v[76:79], v[160:163], v[204:207], v[76:79]
	v_mfma_f32_16x16x32_bf16 v[76:79], v[164:167], v[208:211], v[76:79]
	v_mfma_f32_16x16x32_bf16 v[116:119], v[168:171], v[176:179], v[116:119]
	v_mfma_f32_16x16x32_bf16 v[116:119], v[172:175], v[180:183], v[116:119]
	v_mfma_f32_16x16x32_bf16 v[100:103], v[168:171], v[184:187], v[100:103]
	v_mfma_f32_16x16x32_bf16 v[100:103], v[172:175], v[188:191], v[100:103]
	v_mfma_f32_16x16x32_bf16 v[84:87], v[168:171], v[196:199], v[84:87]
	v_mfma_f32_16x16x32_bf16 v[84:87], v[172:175], v[200:203], v[84:87]
	v_mfma_f32_16x16x32_bf16 v[68:71], v[168:171], v[204:207], v[68:71]
	v_mfma_f32_16x16x32_bf16 v[68:71], v[172:175], v[208:211], v[68:71]
	s_barrier
	s_add_i32 s54, s58, s50
	v_lshl_add_u64 v[138:139], v[138:139], 0, s[60:61]
	s_mov_b32 m0, s54
	ds_read_b128 v[176:179], v143 offset:49152
	ds_read_b128 v[180:183], v143 offset:50176
	ds_read_b128 v[184:187], v143 offset:51200
	ds_read_b128 v[188:191], v143 offset:52224
	ds_read_b128 v[196:199], v143 offset:53248
	ds_read_b128 v[200:203], v143 offset:54272
	ds_read_b128 v[204:207], v143 offset:55296
	ds_read_b128 v[208:211], v143 offset:56320
	global_load_lds_dwordx4 v[138:139], off
	s_add_i32 m0, s54, 0x2000
	s_add_u32 s52, s52, 0x80080
	v_lshl_add_u64 v[138:139], v[192:193], 0, s[60:61]
	s_addc_u32 s53, s53, 0
	s_add_i32 s54, s59, s50
	global_load_lds_dwordx4 v[138:139], off
	v_lshl_add_u64 v[138:139], s[52:53], 0, v[216:217]
	s_mov_b32 m0, s54
	s_nop 0
	global_load_lds_dwordx4 v[138:139], off
	v_lshl_add_u64 v[138:139], s[52:53], 0, v[132:133]
	s_add_i32 m0, s54, 0x2000
	s_nop 0
	global_load_lds_dwordx4 v[138:139], off
	v_lshl_add_u64 v[138:139], v[212:213], 0, s[60:61]
	s_mov_b32 m0, s87
	s_nop 0
	global_load_lds_dwordx4 v[138:139], off
	v_lshl_add_u64 v[138:139], v[214:215], 0, s[60:61]
	s_mov_b32 m0, s88
	s_nop 0
	global_load_lds_dwordx4 v[138:139], off
	s_waitcnt vmcnt(8) lgkmcnt(0)
	s_barrier
	v_mfma_f32_16x16x32_bf16 v[56:59], v[144:147], v[176:179], v[56:59]
	v_mfma_f32_16x16x32_bf16 v[56:59], v[148:151], v[180:183], v[56:59]
	v_mfma_f32_16x16x32_bf16 v[40:43], v[144:147], v[184:187], v[40:43]
	v_mfma_f32_16x16x32_bf16 v[40:43], v[148:151], v[188:191], v[40:43]
	v_mfma_f32_16x16x32_bf16 v[24:27], v[144:147], v[196:199], v[24:27]
	v_mfma_f32_16x16x32_bf16 v[24:27], v[148:151], v[200:203], v[24:27]
	v_mfma_f32_16x16x32_bf16 v[8:11], v[144:147], v[204:207], v[8:11]
	v_mfma_f32_16x16x32_bf16 v[8:11], v[148:151], v[208:211], v[8:11]
	v_mfma_f32_16x16x32_bf16 v[48:51], v[152:155], v[176:179], v[48:51]
	v_mfma_f32_16x16x32_bf16 v[48:51], v[156:159], v[180:183], v[48:51]
	v_mfma_f32_16x16x32_bf16 v[32:35], v[152:155], v[184:187], v[32:35]
	v_mfma_f32_16x16x32_bf16 v[32:35], v[156:159], v[188:191], v[32:35]
	v_mfma_f32_16x16x32_bf16 v[16:19], v[152:155], v[196:199], v[16:19]
	v_mfma_f32_16x16x32_bf16 v[16:19], v[156:159], v[200:203], v[16:19]
	v_mfma_f32_16x16x32_bf16 v[0:3], v[152:155], v[204:207], v[0:3]
	v_mfma_f32_16x16x32_bf16 v[0:3], v[156:159], v[208:211], v[0:3]
	v_mfma_f32_16x16x32_bf16 v[60:63], v[160:163], v[176:179], v[60:63]
	v_mfma_f32_16x16x32_bf16 v[60:63], v[164:167], v[180:183], v[60:63]
	v_mfma_f32_16x16x32_bf16 v[44:47], v[160:163], v[184:187], v[44:47]
	v_mfma_f32_16x16x32_bf16 v[44:47], v[164:167], v[188:191], v[44:47]
	v_mfma_f32_16x16x32_bf16 v[28:31], v[160:163], v[196:199], v[28:31]
	v_mfma_f32_16x16x32_bf16 v[28:31], v[164:167], v[200:203], v[28:31]
	v_mfma_f32_16x16x32_bf16 v[12:15], v[160:163], v[204:207], v[12:15]
	v_mfma_f32_16x16x32_bf16 v[12:15], v[164:167], v[208:211], v[12:15]
	v_mfma_f32_16x16x32_bf16 v[52:55], v[168:171], v[176:179], v[52:55]
	v_mfma_f32_16x16x32_bf16 v[52:55], v[172:175], v[180:183], v[52:55]
	v_mfma_f32_16x16x32_bf16 v[36:39], v[168:171], v[184:187], v[36:39]
	v_mfma_f32_16x16x32_bf16 v[36:39], v[172:175], v[188:191], v[36:39]
	v_mfma_f32_16x16x32_bf16 v[20:23], v[168:171], v[196:199], v[20:23]
	v_mfma_f32_16x16x32_bf16 v[20:23], v[172:175], v[200:203], v[20:23]
	v_mfma_f32_16x16x32_bf16 v[4:7], v[168:171], v[204:207], v[4:7]
	v_mfma_f32_16x16x32_bf16 v[4:7], v[172:175], v[208:211], v[4:7]
	s_barrier
	s_add_i32 s95, s95, 2
	s_add_u32 s22, s22, 0x100
	s_addc_u32 s23, s23, 0
	s_add_u32 s93, s93, 0x100
	s_addc_u32 s94, s94, 0
	s_cmp_gt_u32 s95, 29
	s_cbranch_scc0 .LBB0_355
	s_branch .Lzexit_0
.LBB0_355:
	s_add_u32 s52, s22, 0xfff80080
	s_addc_u32 s53, s23, -1
	s_add_i32 s58, 0, 0x10000
	s_cmp_eq_u32 s95, 28
	s_cselect_b32 s55, s13, s53
	s_cselect_b32 s54, s91, s52
	v_add_u32_e32 v138, s58, v141
	s_cselect_b32 s53, s11, s94
	s_cselect_b32 s52, s92, s93
	s_add_i32 s59, 0, 0x14000
	ds_read_b128 v[144:147], v138
	ds_read_b128 v[148:151], v138 offset:1024
	ds_read_b128 v[152:155], v138 offset:2048
	ds_read_b128 v[156:159], v138 offset:3072
	v_add_u32_e32 v138, s59, v141
	ds_read_b128 v[160:163], v138
	ds_read_b128 v[164:167], v138 offset:1024
	ds_read_b128 v[168:171], v138 offset:2048
	ds_read_b128 v[172:175], v138 offset:3072
	v_lshl_add_u64 v[138:139], s[22:23], 0, v[134:135]
	s_add_i32 m0, s76, 0xc000
	ds_read_b128 v[176:179], v143
	ds_read_b128 v[180:183], v143 offset:1024
	ds_read_b128 v[184:187], v143 offset:2048
	ds_read_b128 v[188:191], v143 offset:3072
	ds_read_b128 v[196:199], v143 offset:4096
	ds_read_b128 v[200:203], v143 offset:5120
	ds_read_b128 v[204:207], v143 offset:6144
	ds_read_b128 v[208:211], v143 offset:7168
	global_load_lds_dwordx4 v[138:139], off
	v_lshl_add_u64 v[138:139], s[22:23], 0, v[136:137]
	s_add_i32 m0, s76, 0xe000
	s_nop 0
	global_load_lds_dwordx4 v[138:139], off
	s_waitcnt vmcnt(8) lgkmcnt(0)
	s_barrier
	v_mfma_f32_16x16x32_bf16 v[120:123], v[144:147], v[176:179], v[120:123]
	v_mfma_f32_16x16x32_bf16 v[120:123], v[148:151], v[180:183], v[120:123]
	v_mfma_f32_16x16x32_bf16 v[104:107], v[144:147], v[184:187], v[104:107]
	v_mfma_f32_16x16x32_bf16 v[104:107], v[148:151], v[188:191], v[104:107]
	v_mfma_f32_16x16x32_bf16 v[88:91], v[144:147], v[196:199], v[88:91]
	v_mfma_f32_16x16x32_bf16 v[88:91], v[148:151], v[200:203], v[88:91]
	v_mfma_f32_16x16x32_bf16 v[72:75], v[144:147], v[204:207], v[72:75]
	v_mfma_f32_16x16x32_bf16 v[72:75], v[148:151], v[208:211], v[72:75]
	v_mfma_f32_16x16x32_bf16 v[112:115], v[152:155], v[176:179], v[112:115]
	v_mfma_f32_16x16x32_bf16 v[112:115], v[156:159], v[180:183], v[112:115]
	v_mfma_f32_16x16x32_bf16 v[96:99], v[152:155], v[184:187], v[96:99]
	v_mfma_f32_16x16x32_bf16 v[96:99], v[156:159], v[188:191], v[96:99]
	v_mfma_f32_16x16x32_bf16 v[80:83], v[152:155], v[196:199], v[80:83]
	v_mfma_f32_16x16x32_bf16 v[80:83], v[156:159], v[200:203], v[80:83]
	v_mfma_f32_16x16x32_bf16 v[64:67], v[152:155], v[204:207], v[64:67]
	v_mfma_f32_16x16x32_bf16 v[64:67], v[156:159], v[208:211], v[64:67]
	v_mfma_f32_16x16x32_bf16 v[124:127], v[160:163], v[176:179], v[124:127]
	v_mfma_f32_16x16x32_bf16 v[124:127], v[164:167], v[180:183], v[124:127]
	v_mfma_f32_16x16x32_bf16 v[108:111], v[160:163], v[184:187], v[108:111]
	v_mfma_f32_16x16x32_bf16 v[108:111], v[164:167], v[188:191], v[108:111]
	v_mfma_f32_16x16x32_bf16 v[92:95], v[160:163], v[196:199], v[92:95]
	v_mfma_f32_16x16x32_bf16 v[92:95], v[164:167], v[200:203], v[92:95]
	v_mfma_f32_16x16x32_bf16 v[76:79], v[160:163], v[204:207], v[76:79]
	v_mfma_f32_16x16x32_bf16 v[76:79], v[164:167], v[208:211], v[76:79]
	v_mfma_f32_16x16x32_bf16 v[116:119], v[168:171], v[176:179], v[116:119]
	v_mfma_f32_16x16x32_bf16 v[116:119], v[172:175], v[180:183], v[116:119]
	v_mfma_f32_16x16x32_bf16 v[100:103], v[168:171], v[184:187], v[100:103]
	v_mfma_f32_16x16x32_bf16 v[100:103], v[172:175], v[188:191], v[100:103]
	v_mfma_f32_16x16x32_bf16 v[84:87], v[168:171], v[196:199], v[84:87]
	v_mfma_f32_16x16x32_bf16 v[84:87], v[172:175], v[200:203], v[84:87]
	v_mfma_f32_16x16x32_bf16 v[68:71], v[168:171], v[204:207], v[68:71]
	v_mfma_f32_16x16x32_bf16 v[68:71], v[172:175], v[208:211], v[68:71]
	s_barrier
	s_add_i32 s58, s58, s50
	v_lshl_add_u64 v[138:139], s[52:53], 0, v[216:217]
	s_mov_b32 m0, s58
	ds_read_b128 v[176:179], v143 offset:16384
	ds_read_b128 v[180:183], v143 offset:17408
	ds_read_b128 v[184:187], v143 offset:18432
	ds_read_b128 v[188:191], v143 offset:19456
	ds_read_b128 v[196:199], v143 offset:20480
	ds_read_b128 v[200:203], v143 offset:21504
	ds_read_b128 v[204:207], v143 offset:22528
	ds_read_b128 v[208:211], v143 offset:23552
	global_load_lds_dwordx4 v[138:139], off
	s_add_i32 m0, s58, 0x2000
	s_add_u32 s96, s52, 0x80000
	v_lshl_add_u64 v[192:193], s[52:53], 0, v[132:133]
	s_addc_u32 s97, s53, 0
	s_add_i32 s58, s59, s50
	global_load_lds_dwordx4 v[192:193], off
	v_lshl_add_u64 v[212:213], s[96:97], 0, v[216:217]
	s_mov_b32 m0, s58
	v_lshl_add_u64 v[214:215], s[54:55], 0, v[130:131]
	global_load_lds_dwordx4 v[212:213], off
	v_lshl_add_u64 v[212:213], s[96:97], 0, v[132:133]
	s_add_i32 m0, s58, 0x2000
	s_nop 0
	global_load_lds_dwordx4 v[212:213], off
	v_lshl_add_u64 v[212:213], s[54:55], 0, v[128:129]
	s_mov_b32 m0, s76
	s_nop 0
	global_load_lds_dwordx4 v[212:213], off
	s_mov_b32 m0, s74
	s_nop 0
	global_load_lds_dwordx4 v[214:215], off
	s_waitcnt vmcnt(8) lgkmcnt(0)
	s_barrier
	v_mfma_f32_16x16x32_bf16 v[56:59], v[144:147], v[176:179], v[56:59]
	v_mfma_f32_16x16x32_bf16 v[56:59], v[148:151], v[180:183], v[56:59]
	v_mfma_f32_16x16x32_bf16 v[40:43], v[144:147], v[184:187], v[40:43]
	v_mfma_f32_16x16x32_bf16 v[40:43], v[148:151], v[188:191], v[40:43]
	v_mfma_f32_16x16x32_bf16 v[24:27], v[144:147], v[196:199], v[24:27]
	v_mfma_f32_16x16x32_bf16 v[24:27], v[148:151], v[200:203], v[24:27]
	v_mfma_f32_16x16x32_bf16 v[8:11], v[144:147], v[204:207], v[8:11]
	v_mfma_f32_16x16x32_bf16 v[8:11], v[148:151], v[208:211], v[8:11]
	v_mfma_f32_16x16x32_bf16 v[48:51], v[152:155], v[176:179], v[48:51]
	v_mfma_f32_16x16x32_bf16 v[48:51], v[156:159], v[180:183], v[48:51]
	v_mfma_f32_16x16x32_bf16 v[32:35], v[152:155], v[184:187], v[32:35]
	v_mfma_f32_16x16x32_bf16 v[32:35], v[156:159], v[188:191], v[32:35]
	v_mfma_f32_16x16x32_bf16 v[16:19], v[152:155], v[196:199], v[16:19]
	v_mfma_f32_16x16x32_bf16 v[16:19], v[156:159], v[200:203], v[16:19]
	v_mfma_f32_16x16x32_bf16 v[0:3], v[152:155], v[204:207], v[0:3]
	v_mfma_f32_16x16x32_bf16 v[0:3], v[156:159], v[208:211], v[0:3]
	v_mfma_f32_16x16x32_bf16 v[60:63], v[160:163], v[176:179], v[60:63]
	v_mfma_f32_16x16x32_bf16 v[60:63], v[164:167], v[180:183], v[60:63]
	v_mfma_f32_16x16x32_bf16 v[44:47], v[160:163], v[184:187], v[44:47]
	v_mfma_f32_16x16x32_bf16 v[44:47], v[164:167], v[188:191], v[44:47]
	v_mfma_f32_16x16x32_bf16 v[28:31], v[160:163], v[196:199], v[28:31]
	v_mfma_f32_16x16x32_bf16 v[28:31], v[164:167], v[200:203], v[28:31]
	v_mfma_f32_16x16x32_bf16 v[12:15], v[160:163], v[204:207], v[12:15]
	v_mfma_f32_16x16x32_bf16 v[12:15], v[164:167], v[208:211], v[12:15]
	v_mfma_f32_16x16x32_bf16 v[52:55], v[168:171], v[176:179], v[52:55]
	v_mfma_f32_16x16x32_bf16 v[52:55], v[172:175], v[180:183], v[52:55]
	v_mfma_f32_16x16x32_bf16 v[36:39], v[168:171], v[184:187], v[36:39]
	v_mfma_f32_16x16x32_bf16 v[36:39], v[172:175], v[188:191], v[36:39]
	v_mfma_f32_16x16x32_bf16 v[20:23], v[168:171], v[196:199], v[20:23]
	v_mfma_f32_16x16x32_bf16 v[20:23], v[172:175], v[200:203], v[20:23]
	v_mfma_f32_16x16x32_bf16 v[4:7], v[168:171], v[204:207], v[4:7]
	v_mfma_f32_16x16x32_bf16 v[4:7], v[172:175], v[208:211], v[4:7]
	s_barrier
	s_add_i32 s58, 0, 0x18000
	s_add_i32 s59, 0, 0x1c000
	v_add_u32_e32 v156, s58, v141
	v_add_u32_e32 v172, s59, v141
	ds_read_b128 v[144:147], v156
	ds_read_b128 v[148:151], v156 offset:1024
	ds_read_b128 v[152:155], v156 offset:2048
	ds_read_b128 v[156:159], v156 offset:3072
	ds_read_b128 v[160:163], v172
	ds_read_b128 v[164:167], v172 offset:1024
	ds_read_b128 v[168:171], v172 offset:2048
	ds_read_b128 v[172:175], v172 offset:3072
	s_add_u32 s54, s54, 0x80000
	s_addc_u32 s55, s55, 0
	s_mov_b32 m0, s85
	v_lshl_add_u64 v[218:219], s[54:55], 0, v[128:129]
	ds_read_b128 v[176:179], v143 offset:32768
	ds_read_b128 v[180:183], v143 offset:33792
	ds_read_b128 v[184:187], v143 offset:34816
	ds_read_b128 v[188:191], v143 offset:35840
	ds_read_b128 v[196:199], v143 offset:36864
	ds_read_b128 v[200:203], v143 offset:37888
	ds_read_b128 v[204:207], v143 offset:38912
	ds_read_b128 v[208:211], v143 offset:39936
	global_load_lds_dwordx4 v[218:219], off
	v_lshl_add_u64 v[218:219], s[54:55], 0, v[130:131]
	s_mov_b32 m0, s86
	s_nop 0
	global_load_lds_dwordx4 v[218:219], off
	s_waitcnt vmcnt(8) lgkmcnt(0)
	s_barrier
	v_mfma_f32_16x16x32_bf16 v[120:123], v[144:147], v[176:179], v[120:123]
	v_mfma_f32_16x16x32_bf16 v[120:123], v[148:151], v[180:183], v[120:123]
	v_mfma_f32_16x16x32_bf16 v[104:107], v[144:147], v[184:187], v[104:107]
	v_mfma_f32_16x16x32_bf16 v[104:107], v[148:151], v[188:191], v[104:107]
	v_mfma_f32_16x16x32_bf16 v[88:91], v[144:147], v[196:199], v[88:91]
	v_mfma_f32_16x16x32_bf16 v[88:91], v[148:151], v[200:203], v[88:91]
	v_mfma_f32_16x16x32_bf16 v[72:75], v[144:147], v[204:207], v[72:75]
	v_mfma_f32_16x16x32_bf16 v[72:75], v[148:151], v[208:211], v[72:75]
	v_mfma_f32_16x16x32_bf16 v[112:115], v[152:155], v[176:179], v[112:115]
	v_mfma_f32_16x16x32_bf16 v[112:115], v[156:159], v[180:183], v[112:115]
	v_mfma_f32_16x16x32_bf16 v[96:99], v[152:155], v[184:187], v[96:99]
	v_mfma_f32_16x16x32_bf16 v[96:99], v[156:159], v[188:191], v[96:99]
	v_mfma_f32_16x16x32_bf16 v[80:83], v[152:155], v[196:199], v[80:83]
	v_mfma_f32_16x16x32_bf16 v[80:83], v[156:159], v[200:203], v[80:83]
	v_mfma_f32_16x16x32_bf16 v[64:67], v[152:155], v[204:207], v[64:67]
	v_mfma_f32_16x16x32_bf16 v[64:67], v[156:159], v[208:211], v[64:67]
	v_mfma_f32_16x16x32_bf16 v[124:127], v[160:163], v[176:179], v[124:127]
	v_mfma_f32_16x16x32_bf16 v[124:127], v[164:167], v[180:183], v[124:127]
	v_mfma_f32_16x16x32_bf16 v[108:111], v[160:163], v[184:187], v[108:111]
	v_mfma_f32_16x16x32_bf16 v[108:111], v[164:167], v[188:191], v[108:111]
	v_mfma_f32_16x16x32_bf16 v[92:95], v[160:163], v[196:199], v[92:95]
	v_mfma_f32_16x16x32_bf16 v[92:95], v[164:167], v[200:203], v[92:95]
	v_mfma_f32_16x16x32_bf16 v[76:79], v[160:163], v[204:207], v[76:79]
	v_mfma_f32_16x16x32_bf16 v[76:79], v[164:167], v[208:211], v[76:79]
	v_mfma_f32_16x16x32_bf16 v[116:119], v[168:171], v[176:179], v[116:119]
	v_mfma_f32_16x16x32_bf16 v[116:119], v[172:175], v[180:183], v[116:119]
	v_mfma_f32_16x16x32_bf16 v[100:103], v[168:171], v[184:187], v[100:103]
	v_mfma_f32_16x16x32_bf16 v[100:103], v[172:175], v[188:191], v[100:103]
	v_mfma_f32_16x16x32_bf16 v[84:87], v[168:171], v[196:199], v[84:87]
	v_mfma_f32_16x16x32_bf16 v[84:87], v[172:175], v[200:203], v[84:87]
	v_mfma_f32_16x16x32_bf16 v[68:71], v[168:171], v[204:207], v[68:71]
	v_mfma_f32_16x16x32_bf16 v[68:71], v[172:175], v[208:211], v[68:71]
	s_barrier
	s_add_i32 s54, s58, s50
	v_lshl_add_u64 v[138:139], v[138:139], 0, s[60:61]
	s_mov_b32 m0, s54
	ds_read_b128 v[176:179], v143 offset:49152
	ds_read_b128 v[180:183], v143 offset:50176
	ds_read_b128 v[184:187], v143 offset:51200
	ds_read_b128 v[188:191], v143 offset:52224
	ds_read_b128 v[196:199], v143 offset:53248
	ds_read_b128 v[200:203], v143 offset:54272
	ds_read_b128 v[204:207], v143 offset:55296
	ds_read_b128 v[208:211], v143 offset:56320
	global_load_lds_dwordx4 v[138:139], off
	s_add_i32 m0, s54, 0x2000
	s_add_u32 s52, s52, 0x80080
	v_lshl_add_u64 v[138:139], v[192:193], 0, s[60:61]
	s_addc_u32 s53, s53, 0
	s_add_i32 s54, s59, s50
	global_load_lds_dwordx4 v[138:139], off
	v_lshl_add_u64 v[138:139], s[52:53], 0, v[216:217]
	s_mov_b32 m0, s54
	s_nop 0
	global_load_lds_dwordx4 v[138:139], off
	v_lshl_add_u64 v[138:139], s[52:53], 0, v[132:133]
	s_add_i32 m0, s54, 0x2000
	s_nop 0
	global_load_lds_dwordx4 v[138:139], off
	v_lshl_add_u64 v[138:139], v[212:213], 0, s[60:61]
	s_mov_b32 m0, s87
	s_nop 0
	global_load_lds_dwordx4 v[138:139], off
	v_lshl_add_u64 v[138:139], v[214:215], 0, s[60:61]
	s_mov_b32 m0, s88
	s_nop 0
	global_load_lds_dwordx4 v[138:139], off
	s_waitcnt vmcnt(8) lgkmcnt(0)
	s_barrier
	v_mfma_f32_16x16x32_bf16 v[56:59], v[144:147], v[176:179], v[56:59]
	v_mfma_f32_16x16x32_bf16 v[56:59], v[148:151], v[180:183], v[56:59]
	v_mfma_f32_16x16x32_bf16 v[40:43], v[144:147], v[184:187], v[40:43]
	v_mfma_f32_16x16x32_bf16 v[40:43], v[148:151], v[188:191], v[40:43]
	v_mfma_f32_16x16x32_bf16 v[24:27], v[144:147], v[196:199], v[24:27]
	v_mfma_f32_16x16x32_bf16 v[24:27], v[148:151], v[200:203], v[24:27]
	v_mfma_f32_16x16x32_bf16 v[8:11], v[144:147], v[204:207], v[8:11]
	v_mfma_f32_16x16x32_bf16 v[8:11], v[148:151], v[208:211], v[8:11]
	v_mfma_f32_16x16x32_bf16 v[48:51], v[152:155], v[176:179], v[48:51]
	v_mfma_f32_16x16x32_bf16 v[48:51], v[156:159], v[180:183], v[48:51]
	v_mfma_f32_16x16x32_bf16 v[32:35], v[152:155], v[184:187], v[32:35]
	v_mfma_f32_16x16x32_bf16 v[32:35], v[156:159], v[188:191], v[32:35]
	v_mfma_f32_16x16x32_bf16 v[16:19], v[152:155], v[196:199], v[16:19]
	v_mfma_f32_16x16x32_bf16 v[16:19], v[156:159], v[200:203], v[16:19]
	v_mfma_f32_16x16x32_bf16 v[0:3], v[152:155], v[204:207], v[0:3]
	v_mfma_f32_16x16x32_bf16 v[0:3], v[156:159], v[208:211], v[0:3]
	v_mfma_f32_16x16x32_bf16 v[60:63], v[160:163], v[176:179], v[60:63]
	v_mfma_f32_16x16x32_bf16 v[60:63], v[164:167], v[180:183], v[60:63]
	v_mfma_f32_16x16x32_bf16 v[44:47], v[160:163], v[184:187], v[44:47]
	v_mfma_f32_16x16x32_bf16 v[44:47], v[164:167], v[188:191], v[44:47]
	v_mfma_f32_16x16x32_bf16 v[28:31], v[160:163], v[196:199], v[28:31]
	v_mfma_f32_16x16x32_bf16 v[28:31], v[164:167], v[200:203], v[28:31]
	v_mfma_f32_16x16x32_bf16 v[12:15], v[160:163], v[204:207], v[12:15]
	v_mfma_f32_16x16x32_bf16 v[12:15], v[164:167], v[208:211], v[12:15]
	v_mfma_f32_16x16x32_bf16 v[52:55], v[168:171], v[176:179], v[52:55]
	v_mfma_f32_16x16x32_bf16 v[52:55], v[172:175], v[180:183], v[52:55]
	v_mfma_f32_16x16x32_bf16 v[36:39], v[168:171], v[184:187], v[36:39]
	v_mfma_f32_16x16x32_bf16 v[36:39], v[172:175], v[188:191], v[36:39]
	v_mfma_f32_16x16x32_bf16 v[20:23], v[168:171], v[196:199], v[20:23]
	v_mfma_f32_16x16x32_bf16 v[20:23], v[172:175], v[200:203], v[20:23]
	v_mfma_f32_16x16x32_bf16 v[4:7], v[168:171], v[204:207], v[4:7]
	v_mfma_f32_16x16x32_bf16 v[4:7], v[172:175], v[208:211], v[4:7]
	s_barrier
	s_add_i32 s95, s95, 2
	s_add_u32 s22, s22, 0x100
	s_addc_u32 s23, s23, 0
	s_add_u32 s93, s93, 0x100
	s_addc_u32 s94, s94, 0
	s_cmp_gt_u32 s95, 29
	s_cbranch_scc0 .LBB0_355

.LBB0_559:
	s_add_u32 s94, s22, 0x100
	v_mov_b32_e32 v0, 0
	s_addc_u32 s95, s23, 0
	s_mov_b32 s96, -2
	s_add_u32 s22, s18, 0x100
	s_addc_u32 s23, s19, 0
	s_add_i32 s58, 0, 0x10000
	s_cmpk_eq_i32 s96, 0x54
	s_cselect_b32 s55, s7, s23
	s_cselect_b32 s54, s6, s22
	s_cselect_b32 s53, s17, s95
	s_cselect_b32 s52, s16, s94
	s_add_i32 s59, 0, 0x14000
	v_add_u32_e32 v140, s58, v196
	v_add_u32_e32 v166, s59, v196
	ds_read_b128 v[128:131], v140
	ds_read_b128 v[132:135], v140 offset:1024
	ds_read_b128 v[136:139], v140 offset:2048
	ds_read_b128 v[140:143], v140 offset:3072
	ds_read_b128 v[144:147], v166
	ds_read_b128 v[148:151], v166 offset:1024
	ds_read_b128 v[152:155], v166 offset:2048
	ds_read_b128 v[166:169], v166 offset:3072
	v_lshl_add_u64 v[208:209], s[18:19], 0, v[162:163]
	s_add_i32 m0, s76, 0xc000
	ds_read_b128 v[170:173], v198
	ds_read_b128 v[174:177], v198 offset:1024
	ds_read_b128 v[178:181], v198 offset:2048
	ds_read_b128 v[182:185], v198 offset:3072
	ds_read_b128 v[186:189], v198 offset:4096
	ds_read_b128 v[190:193], v198 offset:5120
	ds_read_b128 v[200:203], v198 offset:6144
	ds_read_b128 v[204:207], v198 offset:7168
	global_load_lds_dwordx4 v[208:209], off
	v_lshl_add_u64 v[208:209], s[18:19], 0, v[164:165]
	s_add_i32 m0, s76, 0xe000
	s_nop 0
	global_load_lds_dwordx4 v[208:209], off
	s_waitcnt vmcnt(8) lgkmcnt(0)
	s_barrier
	v_mfma_f32_16x16x32_bf16 v[124:127], v[128:131], v[170:173], 0
	v_mfma_f32_16x16x32_bf16 v[124:127], v[132:135], v[174:177], v[124:127]
	v_mfma_f32_16x16x32_bf16 v[108:111], v[128:131], v[178:181], 0
	v_mfma_f32_16x16x32_bf16 v[108:111], v[132:135], v[182:185], v[108:111]
	v_mfma_f32_16x16x32_bf16 v[92:95], v[128:131], v[186:189], 0
	v_mfma_f32_16x16x32_bf16 v[92:95], v[132:135], v[190:193], v[92:95]
	v_mfma_f32_16x16x32_bf16 v[76:79], v[128:131], v[200:203], 0
	v_mfma_f32_16x16x32_bf16 v[76:79], v[132:135], v[204:207], v[76:79]
	v_mfma_f32_16x16x32_bf16 v[120:123], v[136:139], v[170:173], 0
	v_mfma_f32_16x16x32_bf16 v[120:123], v[140:143], v[174:177], v[120:123]
	v_mfma_f32_16x16x32_bf16 v[104:107], v[136:139], v[178:181], 0
	v_mfma_f32_16x16x32_bf16 v[104:107], v[140:143], v[182:185], v[104:107]
	v_mfma_f32_16x16x32_bf16 v[88:91], v[136:139], v[186:189], 0
	v_mfma_f32_16x16x32_bf16 v[88:91], v[140:143], v[190:193], v[88:91]
	v_mfma_f32_16x16x32_bf16 v[72:75], v[136:139], v[200:203], 0
	v_mfma_f32_16x16x32_bf16 v[72:75], v[140:143], v[204:207], v[72:75]
	v_mfma_f32_16x16x32_bf16 v[116:119], v[144:147], v[170:173], 0
	v_mfma_f32_16x16x32_bf16 v[116:119], v[148:151], v[174:177], v[116:119]
	v_mfma_f32_16x16x32_bf16 v[100:103], v[144:147], v[178:181], 0
	v_mfma_f32_16x16x32_bf16 v[100:103], v[148:151], v[182:185], v[100:103]
	v_mfma_f32_16x16x32_bf16 v[84:87], v[144:147], v[186:189], 0
	v_mfma_f32_16x16x32_bf16 v[84:87], v[148:151], v[190:193], v[84:87]
	v_mfma_f32_16x16x32_bf16 v[68:71], v[144:147], v[200:203], 0
	v_mfma_f32_16x16x32_bf16 v[68:71], v[148:151], v[204:207], v[68:71]
	v_mfma_f32_16x16x32_bf16 v[112:115], v[152:155], v[170:173], 0
	v_mfma_f32_16x16x32_bf16 v[112:115], v[166:169], v[174:177], v[112:115]
	v_mfma_f32_16x16x32_bf16 v[96:99], v[152:155], v[178:181], 0
	v_mfma_f32_16x16x32_bf16 v[96:99], v[166:169], v[182:185], v[96:99]
	v_mfma_f32_16x16x32_bf16 v[80:83], v[152:155], v[186:189], 0
	v_mfma_f32_16x16x32_bf16 v[80:83], v[166:169], v[190:193], v[80:83]
	v_mfma_f32_16x16x32_bf16 v[64:67], v[152:155], v[200:203], 0
	v_mfma_f32_16x16x32_bf16 v[64:67], v[166:169], v[204:207], v[64:67]
	s_barrier
	s_add_i32 s18, s58, s50
	v_lshl_add_u64 v[208:209], s[52:53], 0, v[216:217]
	s_mov_b32 m0, s18
	ds_read_b128 v[170:173], v198 offset:16384
	ds_read_b128 v[174:177], v198 offset:17408
	ds_read_b128 v[178:181], v198 offset:18432
	ds_read_b128 v[182:185], v198 offset:19456
	ds_read_b128 v[186:189], v198 offset:20480
	ds_read_b128 v[190:193], v198 offset:21504
	ds_read_b128 v[200:203], v198 offset:22528
	ds_read_b128 v[204:207], v198 offset:23552
	global_load_lds_dwordx4 v[208:209], off
	s_add_i32 m0, s18, 0x2000
	s_add_u32 s18, s52, 0x164000
	v_lshl_add_u64 v[210:211], s[52:53], 0, v[160:161]
	s_addc_u32 s19, s53, 0
	s_add_i32 s58, s59, s50
	global_load_lds_dwordx4 v[210:211], off
	v_lshl_add_u64 v[212:213], s[18:19], 0, v[216:217]
	s_mov_b32 m0, s58
	v_lshl_add_u64 v[214:215], s[54:55], 0, v[158:159]
	global_load_lds_dwordx4 v[212:213], off
	v_lshl_add_u64 v[212:213], s[18:19], 0, v[160:161]
	s_add_i32 m0, s58, 0x2000
	s_nop 0
	global_load_lds_dwordx4 v[212:213], off
	v_lshl_add_u64 v[212:213], s[54:55], 0, v[156:157]
	s_mov_b32 m0, s76
	s_nop 0
	global_load_lds_dwordx4 v[212:213], off
	s_mov_b32 m0, s45
	s_nop 0
	global_load_lds_dwordx4 v[214:215], off
	s_waitcnt vmcnt(8) lgkmcnt(0)
	s_barrier
	v_mfma_f32_16x16x32_bf16 v[60:63], v[128:131], v[170:173], 0
	v_mfma_f32_16x16x32_bf16 v[60:63], v[132:135], v[174:177], v[60:63]
	v_mfma_f32_16x16x32_bf16 v[44:47], v[128:131], v[178:181], 0
	v_mfma_f32_16x16x32_bf16 v[44:47], v[132:135], v[182:185], v[44:47]
	v_mfma_f32_16x16x32_bf16 v[28:31], v[128:131], v[186:189], 0
	v_mfma_f32_16x16x32_bf16 v[28:31], v[132:135], v[190:193], v[28:31]
	v_mfma_f32_16x16x32_bf16 v[12:15], v[128:131], v[200:203], 0
	v_mfma_f32_16x16x32_bf16 v[12:15], v[132:135], v[204:207], v[12:15]
	v_mfma_f32_16x16x32_bf16 v[56:59], v[136:139], v[170:173], 0
	v_mfma_f32_16x16x32_bf16 v[56:59], v[140:143], v[174:177], v[56:59]
	v_mfma_f32_16x16x32_bf16 v[40:43], v[136:139], v[178:181], 0
	v_mfma_f32_16x16x32_bf16 v[40:43], v[140:143], v[182:185], v[40:43]
	v_mfma_f32_16x16x32_bf16 v[24:27], v[136:139], v[186:189], 0
	v_mfma_f32_16x16x32_bf16 v[24:27], v[140:143], v[190:193], v[24:27]
	v_mfma_f32_16x16x32_bf16 v[8:11], v[136:139], v[200:203], 0
	v_mfma_f32_16x16x32_bf16 v[8:11], v[140:143], v[204:207], v[8:11]
	v_mfma_f32_16x16x32_bf16 v[52:55], v[144:147], v[170:173], 0
	v_mfma_f32_16x16x32_bf16 v[52:55], v[148:151], v[174:177], v[52:55]
	v_mfma_f32_16x16x32_bf16 v[36:39], v[144:147], v[178:181], 0
	v_mfma_f32_16x16x32_bf16 v[36:39], v[148:151], v[182:185], v[36:39]
	v_mfma_f32_16x16x32_bf16 v[20:23], v[144:147], v[186:189], 0
	v_mfma_f32_16x16x32_bf16 v[20:23], v[148:151], v[190:193], v[20:23]
	v_mfma_f32_16x16x32_bf16 v[4:7], v[144:147], v[200:203], 0
	v_mfma_f32_16x16x32_bf16 v[4:7], v[148:151], v[204:207], v[4:7]
	v_mfma_f32_16x16x32_bf16 v[48:51], v[152:155], v[170:173], 0
	v_mfma_f32_16x16x32_bf16 v[48:51], v[166:169], v[174:177], v[48:51]
	v_mfma_f32_16x16x32_bf16 v[32:35], v[152:155], v[178:181], 0
	v_mfma_f32_16x16x32_bf16 v[32:35], v[166:169], v[182:185], v[32:35]
	v_mfma_f32_16x16x32_bf16 v[16:19], v[152:155], v[186:189], 0
	v_mfma_f32_16x16x32_bf16 v[16:19], v[166:169], v[190:193], v[16:19]
	v_mfma_f32_16x16x32_bf16 v[0:3], v[152:155], v[200:203], 0
	v_mfma_f32_16x16x32_bf16 v[0:3], v[166:169], v[204:207], v[0:3]
	s_barrier
	s_add_i32 s58, 0, 0x18000
	s_add_i32 s59, 0, 0x1c000
	v_add_u32_e32 v140, s58, v196
	v_add_u32_e32 v166, s59, v196
	ds_read_b128 v[128:131], v140
	ds_read_b128 v[132:135], v140 offset:1024
	ds_read_b128 v[136:139], v140 offset:2048
	ds_read_b128 v[140:143], v140 offset:3072
	ds_read_b128 v[144:147], v166
	ds_read_b128 v[148:151], v166 offset:1024
	ds_read_b128 v[152:155], v166 offset:2048
	ds_read_b128 v[166:169], v166 offset:3072
	s_add_u32 s18, s54, 0x164000
	s_addc_u32 s19, s55, 0
	s_mov_b32 m0, s65
	v_lshl_add_u64 v[218:219], s[18:19], 0, v[156:157]
	ds_read_b128 v[170:173], v198 offset:32768
	ds_read_b128 v[174:177], v198 offset:33792
	ds_read_b128 v[178:181], v198 offset:34816
	ds_read_b128 v[182:185], v198 offset:35840
	ds_read_b128 v[186:189], v198 offset:36864
	ds_read_b128 v[190:193], v198 offset:37888
	ds_read_b128 v[200:203], v198 offset:38912
	ds_read_b128 v[204:207], v198 offset:39936
	global_load_lds_dwordx4 v[218:219], off
	v_lshl_add_u64 v[218:219], s[18:19], 0, v[158:159]
	s_mov_b32 m0, s72
	s_nop 0
	global_load_lds_dwordx4 v[218:219], off
	s_waitcnt vmcnt(8) lgkmcnt(0)
	s_barrier
	v_mfma_f32_16x16x32_bf16 v[124:127], v[128:131], v[170:173], v[124:127]
	v_mfma_f32_16x16x32_bf16 v[124:127], v[132:135], v[174:177], v[124:127]
	v_mfma_f32_16x16x32_bf16 v[108:111], v[128:131], v[178:181], v[108:111]
	v_mfma_f32_16x16x32_bf16 v[108:111], v[132:135], v[182:185], v[108:111]
	v_mfma_f32_16x16x32_bf16 v[92:95], v[128:131], v[186:189], v[92:95]
	v_mfma_f32_16x16x32_bf16 v[92:95], v[132:135], v[190:193], v[92:95]
	v_mfma_f32_16x16x32_bf16 v[76:79], v[128:131], v[200:203], v[76:79]
	v_mfma_f32_16x16x32_bf16 v[76:79], v[132:135], v[204:207], v[76:79]
	v_mfma_f32_16x16x32_bf16 v[120:123], v[136:139], v[170:173], v[120:123]
	v_mfma_f32_16x16x32_bf16 v[120:123], v[140:143], v[174:177], v[120:123]
	v_mfma_f32_16x16x32_bf16 v[104:107], v[136:139], v[178:181], v[104:107]
	v_mfma_f32_16x16x32_bf16 v[104:107], v[140:143], v[182:185], v[104:107]
	v_mfma_f32_16x16x32_bf16 v[88:91], v[136:139], v[186:189], v[88:91]
	v_mfma_f32_16x16x32_bf16 v[88:91], v[140:143], v[190:193], v[88:91]
	v_mfma_f32_16x16x32_bf16 v[72:75], v[136:139], v[200:203], v[72:75]
	v_mfma_f32_16x16x32_bf16 v[72:75], v[140:143], v[204:207], v[72:75]
	v_mfma_f32_16x16x32_bf16 v[116:119], v[144:147], v[170:173], v[116:119]
	v_mfma_f32_16x16x32_bf16 v[116:119], v[148:151], v[174:177], v[116:119]
	v_mfma_f32_16x16x32_bf16 v[100:103], v[144:147], v[178:181], v[100:103]
	v_mfma_f32_16x16x32_bf16 v[100:103], v[148:151], v[182:185], v[100:103]
	v_mfma_f32_16x16x32_bf16 v[84:87], v[144:147], v[186:189], v[84:87]
	v_mfma_f32_16x16x32_bf16 v[84:87], v[148:151], v[190:193], v[84:87]
	v_mfma_f32_16x16x32_bf16 v[68:71], v[144:147], v[200:203], v[68:71]
	v_mfma_f32_16x16x32_bf16 v[68:71], v[148:151], v[204:207], v[68:71]
	v_mfma_f32_16x16x32_bf16 v[112:115], v[152:155], v[170:173], v[112:115]
	v_mfma_f32_16x16x32_bf16 v[112:115], v[166:169], v[174:177], v[112:115]
	v_mfma_f32_16x16x32_bf16 v[96:99], v[152:155], v[178:181], v[96:99]
	v_mfma_f32_16x16x32_bf16 v[96:99], v[166:169], v[182:185], v[96:99]
	v_mfma_f32_16x16x32_bf16 v[80:83], v[152:155], v[186:189], v[80:83]
	v_mfma_f32_16x16x32_bf16 v[80:83], v[166:169], v[190:193], v[80:83]
	v_mfma_f32_16x16x32_bf16 v[64:67], v[152:155], v[200:203], v[64:67]
	v_mfma_f32_16x16x32_bf16 v[64:67], v[166:169], v[204:207], v[64:67]
	s_barrier
	s_add_i32 s18, s58, s50
	v_lshl_add_u64 v[208:209], v[208:209], 0, s[60:61]
	s_mov_b32 m0, s18
	ds_read_b128 v[170:173], v198 offset:49152
	ds_read_b128 v[174:177], v198 offset:50176
	ds_read_b128 v[178:181], v198 offset:51200
	ds_read_b128 v[182:185], v198 offset:52224
	ds_read_b128 v[186:189], v198 offset:53248
	ds_read_b128 v[190:193], v198 offset:54272
	ds_read_b128 v[200:203], v198 offset:55296
	ds_read_b128 v[204:207], v198 offset:56320
	global_load_lds_dwordx4 v[208:209], off
	s_add_i32 m0, s18, 0x2000
	s_add_u32 s18, s52, 0x164080
	v_lshl_add_u64 v[208:209], v[210:211], 0, s[60:61]
	s_addc_u32 s19, s53, 0
	s_add_i32 s52, s59, s50
	global_load_lds_dwordx4 v[208:209], off
	v_lshl_add_u64 v[208:209], s[18:19], 0, v[216:217]
	s_mov_b32 m0, s52
	s_nop 0
	global_load_lds_dwordx4 v[208:209], off
	v_lshl_add_u64 v[208:209], s[18:19], 0, v[160:161]
	s_add_i32 m0, s52, 0x2000
	s_nop 0
	global_load_lds_dwordx4 v[208:209], off
	v_lshl_add_u64 v[208:209], v[212:213], 0, s[60:61]
	s_mov_b32 m0, s86
	s_nop 0
	global_load_lds_dwordx4 v[208:209], off
	v_lshl_add_u64 v[208:209], v[214:215], 0, s[60:61]
	s_mov_b32 m0, s87
	s_nop 0
	global_load_lds_dwordx4 v[208:209], off
	s_waitcnt vmcnt(8) lgkmcnt(0)
	s_barrier
	v_mfma_f32_16x16x32_bf16 v[60:63], v[128:131], v[170:173], v[60:63]
	v_mfma_f32_16x16x32_bf16 v[60:63], v[132:135], v[174:177], v[60:63]
	v_mfma_f32_16x16x32_bf16 v[44:47], v[128:131], v[178:181], v[44:47]
	v_mfma_f32_16x16x32_bf16 v[44:47], v[132:135], v[182:185], v[44:47]
	v_mfma_f32_16x16x32_bf16 v[28:31], v[128:131], v[186:189], v[28:31]
	v_mfma_f32_16x16x32_bf16 v[28:31], v[132:135], v[190:193], v[28:31]
	v_mfma_f32_16x16x32_bf16 v[12:15], v[128:131], v[200:203], v[12:15]
	v_mfma_f32_16x16x32_bf16 v[12:15], v[132:135], v[204:207], v[12:15]
	v_mfma_f32_16x16x32_bf16 v[56:59], v[136:139], v[170:173], v[56:59]
	v_mfma_f32_16x16x32_bf16 v[56:59], v[140:143], v[174:177], v[56:59]
	v_mfma_f32_16x16x32_bf16 v[40:43], v[136:139], v[178:181], v[40:43]
	v_mfma_f32_16x16x32_bf16 v[40:43], v[140:143], v[182:185], v[40:43]
	v_mfma_f32_16x16x32_bf16 v[24:27], v[136:139], v[186:189], v[24:27]
	v_mfma_f32_16x16x32_bf16 v[24:27], v[140:143], v[190:193], v[24:27]
	v_mfma_f32_16x16x32_bf16 v[8:11], v[136:139], v[200:203], v[8:11]
	v_mfma_f32_16x16x32_bf16 v[8:11], v[140:143], v[204:207], v[8:11]
	v_mfma_f32_16x16x32_bf16 v[52:55], v[144:147], v[170:173], v[52:55]
	v_mfma_f32_16x16x32_bf16 v[52:55], v[148:151], v[174:177], v[52:55]
	v_mfma_f32_16x16x32_bf16 v[36:39], v[144:147], v[178:181], v[36:39]
	v_mfma_f32_16x16x32_bf16 v[36:39], v[148:151], v[182:185], v[36:39]
	v_mfma_f32_16x16x32_bf16 v[20:23], v[144:147], v[186:189], v[20:23]
	v_mfma_f32_16x16x32_bf16 v[20:23], v[148:151], v[190:193], v[20:23]
	v_mfma_f32_16x16x32_bf16 v[4:7], v[144:147], v[200:203], v[4:7]
	v_mfma_f32_16x16x32_bf16 v[4:7], v[148:151], v[204:207], v[4:7]
	v_mfma_f32_16x16x32_bf16 v[48:51], v[152:155], v[170:173], v[48:51]
	v_mfma_f32_16x16x32_bf16 v[48:51], v[166:169], v[174:177], v[48:51]
	v_mfma_f32_16x16x32_bf16 v[32:35], v[152:155], v[178:181], v[32:35]
	v_mfma_f32_16x16x32_bf16 v[32:35], v[166:169], v[182:185], v[32:35]
	v_mfma_f32_16x16x32_bf16 v[16:19], v[152:155], v[186:189], v[16:19]
	v_mfma_f32_16x16x32_bf16 v[16:19], v[166:169], v[190:193], v[16:19]
	v_mfma_f32_16x16x32_bf16 v[0:3], v[152:155], v[200:203], v[0:3]
	v_mfma_f32_16x16x32_bf16 v[0:3], v[166:169], v[204:207], v[0:3]
	s_barrier
	s_add_i32 s96, s96, 2
	s_add_u32 s94, s94, 0x100
	s_addc_u32 s95, s95, 0
	s_cmpk_gt_u32 s96, 0x55
	s_mov_b64 s[18:19], s[22:23]
	s_cbranch_scc0 .LBB0_560
	s_branch .Lzexit_1
.LBB0_560:
	s_add_u32 s22, s18, 0x100
	s_addc_u32 s23, s19, 0
	s_add_i32 s58, 0, 0x10000
	s_cmpk_eq_i32 s96, 0x54
	s_cselect_b32 s55, s7, s23
	s_cselect_b32 s54, s6, s22
	s_cselect_b32 s53, s17, s95
	s_cselect_b32 s52, s16, s94
	s_add_i32 s59, 0, 0x14000
	v_add_u32_e32 v140, s58, v196
	v_add_u32_e32 v166, s59, v196
	ds_read_b128 v[128:131], v140
	ds_read_b128 v[132:135], v140 offset:1024
	ds_read_b128 v[136:139], v140 offset:2048
	ds_read_b128 v[140:143], v140 offset:3072
	ds_read_b128 v[144:147], v166
	ds_read_b128 v[148:151], v166 offset:1024
	ds_read_b128 v[152:155], v166 offset:2048
	ds_read_b128 v[166:169], v166 offset:3072
	v_lshl_add_u64 v[208:209], s[18:19], 0, v[162:163]
	s_add_i32 m0, s76, 0xc000
	ds_read_b128 v[170:173], v198
	ds_read_b128 v[174:177], v198 offset:1024
	ds_read_b128 v[178:181], v198 offset:2048
	ds_read_b128 v[182:185], v198 offset:3072
	ds_read_b128 v[186:189], v198 offset:4096
	ds_read_b128 v[190:193], v198 offset:5120
	ds_read_b128 v[200:203], v198 offset:6144
	ds_read_b128 v[204:207], v198 offset:7168
	global_load_lds_dwordx4 v[208:209], off
	v_lshl_add_u64 v[208:209], s[18:19], 0, v[164:165]
	s_add_i32 m0, s76, 0xe000
	s_nop 0
	global_load_lds_dwordx4 v[208:209], off
	s_waitcnt vmcnt(8) lgkmcnt(0)
	s_barrier
	v_mfma_f32_16x16x32_bf16 v[124:127], v[128:131], v[170:173], v[124:127]
	v_mfma_f32_16x16x32_bf16 v[124:127], v[132:135], v[174:177], v[124:127]
	v_mfma_f32_16x16x32_bf16 v[108:111], v[128:131], v[178:181], v[108:111]
	v_mfma_f32_16x16x32_bf16 v[108:111], v[132:135], v[182:185], v[108:111]
	v_mfma_f32_16x16x32_bf16 v[92:95], v[128:131], v[186:189], v[92:95]
	v_mfma_f32_16x16x32_bf16 v[92:95], v[132:135], v[190:193], v[92:95]
	v_mfma_f32_16x16x32_bf16 v[76:79], v[128:131], v[200:203], v[76:79]
	v_mfma_f32_16x16x32_bf16 v[76:79], v[132:135], v[204:207], v[76:79]
	v_mfma_f32_16x16x32_bf16 v[120:123], v[136:139], v[170:173], v[120:123]
	v_mfma_f32_16x16x32_bf16 v[120:123], v[140:143], v[174:177], v[120:123]
	v_mfma_f32_16x16x32_bf16 v[104:107], v[136:139], v[178:181], v[104:107]
	v_mfma_f32_16x16x32_bf16 v[104:107], v[140:143], v[182:185], v[104:107]
	v_mfma_f32_16x16x32_bf16 v[88:91], v[136:139], v[186:189], v[88:91]
	v_mfma_f32_16x16x32_bf16 v[88:91], v[140:143], v[190:193], v[88:91]
	v_mfma_f32_16x16x32_bf16 v[72:75], v[136:139], v[200:203], v[72:75]
	v_mfma_f32_16x16x32_bf16 v[72:75], v[140:143], v[204:207], v[72:75]
	v_mfma_f32_16x16x32_bf16 v[116:119], v[144:147], v[170:173], v[116:119]
	v_mfma_f32_16x16x32_bf16 v[116:119], v[148:151], v[174:177], v[116:119]
	v_mfma_f32_16x16x32_bf16 v[100:103], v[144:147], v[178:181], v[100:103]
	v_mfma_f32_16x16x32_bf16 v[100:103], v[148:151], v[182:185], v[100:103]
	v_mfma_f32_16x16x32_bf16 v[84:87], v[144:147], v[186:189], v[84:87]
	v_mfma_f32_16x16x32_bf16 v[84:87], v[148:151], v[190:193], v[84:87]
	v_mfma_f32_16x16x32_bf16 v[68:71], v[144:147], v[200:203], v[68:71]
	v_mfma_f32_16x16x32_bf16 v[68:71], v[148:151], v[204:207], v[68:71]
	v_mfma_f32_16x16x32_bf16 v[112:115], v[152:155], v[170:173], v[112:115]
	v_mfma_f32_16x16x32_bf16 v[112:115], v[166:169], v[174:177], v[112:115]
	v_mfma_f32_16x16x32_bf16 v[96:99], v[152:155], v[178:181], v[96:99]
	v_mfma_f32_16x16x32_bf16 v[96:99], v[166:169], v[182:185], v[96:99]
	v_mfma_f32_16x16x32_bf16 v[80:83], v[152:155], v[186:189], v[80:83]
	v_mfma_f32_16x16x32_bf16 v[80:83], v[166:169], v[190:193], v[80:83]
	v_mfma_f32_16x16x32_bf16 v[64:67], v[152:155], v[200:203], v[64:67]
	v_mfma_f32_16x16x32_bf16 v[64:67], v[166:169], v[204:207], v[64:67]
	s_barrier
	s_add_i32 s18, s58, s50
	v_lshl_add_u64 v[208:209], s[52:53], 0, v[216:217]
	s_mov_b32 m0, s18
	ds_read_b128 v[170:173], v198 offset:16384
	ds_read_b128 v[174:177], v198 offset:17408
	ds_read_b128 v[178:181], v198 offset:18432
	ds_read_b128 v[182:185], v198 offset:19456
	ds_read_b128 v[186:189], v198 offset:20480
	ds_read_b128 v[190:193], v198 offset:21504
	ds_read_b128 v[200:203], v198 offset:22528
	ds_read_b128 v[204:207], v198 offset:23552
	global_load_lds_dwordx4 v[208:209], off
	s_add_i32 m0, s18, 0x2000
	s_add_u32 s18, s52, 0x164000
	v_lshl_add_u64 v[210:211], s[52:53], 0, v[160:161]
	s_addc_u32 s19, s53, 0
	s_add_i32 s58, s59, s50
	global_load_lds_dwordx4 v[210:211], off
	v_lshl_add_u64 v[212:213], s[18:19], 0, v[216:217]
	s_mov_b32 m0, s58
	v_lshl_add_u64 v[214:215], s[54:55], 0, v[158:159]
	global_load_lds_dwordx4 v[212:213], off
	v_lshl_add_u64 v[212:213], s[18:19], 0, v[160:161]
	s_add_i32 m0, s58, 0x2000
	s_nop 0
	global_load_lds_dwordx4 v[212:213], off
	v_lshl_add_u64 v[212:213], s[54:55], 0, v[156:157]
	s_mov_b32 m0, s76
	s_nop 0
	global_load_lds_dwordx4 v[212:213], off
	s_mov_b32 m0, s45
	s_nop 0
	global_load_lds_dwordx4 v[214:215], off
	s_waitcnt vmcnt(8) lgkmcnt(0)
	s_barrier
	v_mfma_f32_16x16x32_bf16 v[60:63], v[128:131], v[170:173], v[60:63]
	v_mfma_f32_16x16x32_bf16 v[60:63], v[132:135], v[174:177], v[60:63]
	v_mfma_f32_16x16x32_bf16 v[44:47], v[128:131], v[178:181], v[44:47]
	v_mfma_f32_16x16x32_bf16 v[44:47], v[132:135], v[182:185], v[44:47]
	v_mfma_f32_16x16x32_bf16 v[28:31], v[128:131], v[186:189], v[28:31]
	v_mfma_f32_16x16x32_bf16 v[28:31], v[132:135], v[190:193], v[28:31]
	v_mfma_f32_16x16x32_bf16 v[12:15], v[128:131], v[200:203], v[12:15]
	v_mfma_f32_16x16x32_bf16 v[12:15], v[132:135], v[204:207], v[12:15]
	v_mfma_f32_16x16x32_bf16 v[56:59], v[136:139], v[170:173], v[56:59]
	v_mfma_f32_16x16x32_bf16 v[56:59], v[140:143], v[174:177], v[56:59]
	v_mfma_f32_16x16x32_bf16 v[40:43], v[136:139], v[178:181], v[40:43]
	v_mfma_f32_16x16x32_bf16 v[40:43], v[140:143], v[182:185], v[40:43]
	v_mfma_f32_16x16x32_bf16 v[24:27], v[136:139], v[186:189], v[24:27]
	v_mfma_f32_16x16x32_bf16 v[24:27], v[140:143], v[190:193], v[24:27]
	v_mfma_f32_16x16x32_bf16 v[8:11], v[136:139], v[200:203], v[8:11]
	v_mfma_f32_16x16x32_bf16 v[8:11], v[140:143], v[204:207], v[8:11]
	v_mfma_f32_16x16x32_bf16 v[52:55], v[144:147], v[170:173], v[52:55]
	v_mfma_f32_16x16x32_bf16 v[52:55], v[148:151], v[174:177], v[52:55]
	v_mfma_f32_16x16x32_bf16 v[36:39], v[144:147], v[178:181], v[36:39]
	v_mfma_f32_16x16x32_bf16 v[36:39], v[148:151], v[182:185], v[36:39]
	v_mfma_f32_16x16x32_bf16 v[20:23], v[144:147], v[186:189], v[20:23]
	v_mfma_f32_16x16x32_bf16 v[20:23], v[148:151], v[190:193], v[20:23]
	v_mfma_f32_16x16x32_bf16 v[4:7], v[144:147], v[200:203], v[4:7]
	v_mfma_f32_16x16x32_bf16 v[4:7], v[148:151], v[204:207], v[4:7]
	v_mfma_f32_16x16x32_bf16 v[48:51], v[152:155], v[170:173], v[48:51]
	v_mfma_f32_16x16x32_bf16 v[48:51], v[166:169], v[174:177], v[48:51]
	v_mfma_f32_16x16x32_bf16 v[32:35], v[152:155], v[178:181], v[32:35]
	v_mfma_f32_16x16x32_bf16 v[32:35], v[166:169], v[182:185], v[32:35]
	v_mfma_f32_16x16x32_bf16 v[16:19], v[152:155], v[186:189], v[16:19]
	v_mfma_f32_16x16x32_bf16 v[16:19], v[166:169], v[190:193], v[16:19]
	v_mfma_f32_16x16x32_bf16 v[0:3], v[152:155], v[200:203], v[0:3]
	v_mfma_f32_16x16x32_bf16 v[0:3], v[166:169], v[204:207], v[0:3]
	s_barrier
	s_add_i32 s58, 0, 0x18000
	s_add_i32 s59, 0, 0x1c000
	v_add_u32_e32 v140, s58, v196
	v_add_u32_e32 v166, s59, v196
	ds_read_b128 v[128:131], v140
	ds_read_b128 v[132:135], v140 offset:1024
	ds_read_b128 v[136:139], v140 offset:2048
	ds_read_b128 v[140:143], v140 offset:3072
	ds_read_b128 v[144:147], v166
	ds_read_b128 v[148:151], v166 offset:1024
	ds_read_b128 v[152:155], v166 offset:2048
	ds_read_b128 v[166:169], v166 offset:3072
	s_add_u32 s18, s54, 0x164000
	s_addc_u32 s19, s55, 0
	s_mov_b32 m0, s65
	v_lshl_add_u64 v[218:219], s[18:19], 0, v[156:157]
	ds_read_b128 v[170:173], v198 offset:32768
	ds_read_b128 v[174:177], v198 offset:33792
	ds_read_b128 v[178:181], v198 offset:34816
	ds_read_b128 v[182:185], v198 offset:35840
	ds_read_b128 v[186:189], v198 offset:36864
	ds_read_b128 v[190:193], v198 offset:37888
	ds_read_b128 v[200:203], v198 offset:38912
	ds_read_b128 v[204:207], v198 offset:39936
	global_load_lds_dwordx4 v[218:219], off
	v_lshl_add_u64 v[218:219], s[18:19], 0, v[158:159]
	s_mov_b32 m0, s72
	s_nop 0
	global_load_lds_dwordx4 v[218:219], off
	s_waitcnt vmcnt(8) lgkmcnt(0)
	s_barrier
	v_mfma_f32_16x16x32_bf16 v[124:127], v[128:131], v[170:173], v[124:127]
	v_mfma_f32_16x16x32_bf16 v[124:127], v[132:135], v[174:177], v[124:127]
	v_mfma_f32_16x16x32_bf16 v[108:111], v[128:131], v[178:181], v[108:111]
	v_mfma_f32_16x16x32_bf16 v[108:111], v[132:135], v[182:185], v[108:111]
	v_mfma_f32_16x16x32_bf16 v[92:95], v[128:131], v[186:189], v[92:95]
	v_mfma_f32_16x16x32_bf16 v[92:95], v[132:135], v[190:193], v[92:95]
	v_mfma_f32_16x16x32_bf16 v[76:79], v[128:131], v[200:203], v[76:79]
	v_mfma_f32_16x16x32_bf16 v[76:79], v[132:135], v[204:207], v[76:79]
	v_mfma_f32_16x16x32_bf16 v[120:123], v[136:139], v[170:173], v[120:123]
	v_mfma_f32_16x16x32_bf16 v[120:123], v[140:143], v[174:177], v[120:123]
	v_mfma_f32_16x16x32_bf16 v[104:107], v[136:139], v[178:181], v[104:107]
	v_mfma_f32_16x16x32_bf16 v[104:107], v[140:143], v[182:185], v[104:107]
	v_mfma_f32_16x16x32_bf16 v[88:91], v[136:139], v[186:189], v[88:91]
	v_mfma_f32_16x16x32_bf16 v[88:91], v[140:143], v[190:193], v[88:91]
	v_mfma_f32_16x16x32_bf16 v[72:75], v[136:139], v[200:203], v[72:75]
	v_mfma_f32_16x16x32_bf16 v[72:75], v[140:143], v[204:207], v[72:75]
	v_mfma_f32_16x16x32_bf16 v[116:119], v[144:147], v[170:173], v[116:119]
	v_mfma_f32_16x16x32_bf16 v[116:119], v[148:151], v[174:177], v[116:119]
	v_mfma_f32_16x16x32_bf16 v[100:103], v[144:147], v[178:181], v[100:103]
	v_mfma_f32_16x16x32_bf16 v[100:103], v[148:151], v[182:185], v[100:103]
	v_mfma_f32_16x16x32_bf16 v[84:87], v[144:147], v[186:189], v[84:87]
	v_mfma_f32_16x16x32_bf16 v[84:87], v[148:151], v[190:193], v[84:87]
	v_mfma_f32_16x16x32_bf16 v[68:71], v[144:147], v[200:203], v[68:71]
	v_mfma_f32_16x16x32_bf16 v[68:71], v[148:151], v[204:207], v[68:71]
	v_mfma_f32_16x16x32_bf16 v[112:115], v[152:155], v[170:173], v[112:115]
	v_mfma_f32_16x16x32_bf16 v[112:115], v[166:169], v[174:177], v[112:115]
	v_mfma_f32_16x16x32_bf16 v[96:99], v[152:155], v[178:181], v[96:99]
	v_mfma_f32_16x16x32_bf16 v[96:99], v[166:169], v[182:185], v[96:99]
	v_mfma_f32_16x16x32_bf16 v[80:83], v[152:155], v[186:189], v[80:83]
	v_mfma_f32_16x16x32_bf16 v[80:83], v[166:169], v[190:193], v[80:83]
	v_mfma_f32_16x16x32_bf16 v[64:67], v[152:155], v[200:203], v[64:67]
	v_mfma_f32_16x16x32_bf16 v[64:67], v[166:169], v[204:207], v[64:67]
	s_barrier
	s_add_i32 s18, s58, s50
	v_lshl_add_u64 v[208:209], v[208:209], 0, s[60:61]
	s_mov_b32 m0, s18
	ds_read_b128 v[170:173], v198 offset:49152
	ds_read_b128 v[174:177], v198 offset:50176
	ds_read_b128 v[178:181], v198 offset:51200
	ds_read_b128 v[182:185], v198 offset:52224
	ds_read_b128 v[186:189], v198 offset:53248
	ds_read_b128 v[190:193], v198 offset:54272
	ds_read_b128 v[200:203], v198 offset:55296
	ds_read_b128 v[204:207], v198 offset:56320
	global_load_lds_dwordx4 v[208:209], off
	s_add_i32 m0, s18, 0x2000
	s_add_u32 s18, s52, 0x164080
	v_lshl_add_u64 v[208:209], v[210:211], 0, s[60:61]
	s_addc_u32 s19, s53, 0
	s_add_i32 s52, s59, s50
	global_load_lds_dwordx4 v[208:209], off
	v_lshl_add_u64 v[208:209], s[18:19], 0, v[216:217]
	s_mov_b32 m0, s52
	s_nop 0
	global_load_lds_dwordx4 v[208:209], off
	v_lshl_add_u64 v[208:209], s[18:19], 0, v[160:161]
	s_add_i32 m0, s52, 0x2000
	s_nop 0
	global_load_lds_dwordx4 v[208:209], off
	v_lshl_add_u64 v[208:209], v[212:213], 0, s[60:61]
	s_mov_b32 m0, s86
	s_nop 0
	global_load_lds_dwordx4 v[208:209], off
	v_lshl_add_u64 v[208:209], v[214:215], 0, s[60:61]
	s_mov_b32 m0, s87
	s_nop 0
	global_load_lds_dwordx4 v[208:209], off
	s_waitcnt vmcnt(8) lgkmcnt(0)
	s_barrier
	v_mfma_f32_16x16x32_bf16 v[60:63], v[128:131], v[170:173], v[60:63]
	v_mfma_f32_16x16x32_bf16 v[60:63], v[132:135], v[174:177], v[60:63]
	v_mfma_f32_16x16x32_bf16 v[44:47], v[128:131], v[178:181], v[44:47]
	v_mfma_f32_16x16x32_bf16 v[44:47], v[132:135], v[182:185], v[44:47]
	v_mfma_f32_16x16x32_bf16 v[28:31], v[128:131], v[186:189], v[28:31]
	v_mfma_f32_16x16x32_bf16 v[28:31], v[132:135], v[190:193], v[28:31]
	v_mfma_f32_16x16x32_bf16 v[12:15], v[128:131], v[200:203], v[12:15]
	v_mfma_f32_16x16x32_bf16 v[12:15], v[132:135], v[204:207], v[12:15]
	v_mfma_f32_16x16x32_bf16 v[56:59], v[136:139], v[170:173], v[56:59]
	v_mfma_f32_16x16x32_bf16 v[56:59], v[140:143], v[174:177], v[56:59]
	v_mfma_f32_16x16x32_bf16 v[40:43], v[136:139], v[178:181], v[40:43]
	v_mfma_f32_16x16x32_bf16 v[40:43], v[140:143], v[182:185], v[40:43]
	v_mfma_f32_16x16x32_bf16 v[24:27], v[136:139], v[186:189], v[24:27]
	v_mfma_f32_16x16x32_bf16 v[24:27], v[140:143], v[190:193], v[24:27]
	v_mfma_f32_16x16x32_bf16 v[8:11], v[136:139], v[200:203], v[8:11]
	v_mfma_f32_16x16x32_bf16 v[8:11], v[140:143], v[204:207], v[8:11]
	v_mfma_f32_16x16x32_bf16 v[52:55], v[144:147], v[170:173], v[52:55]
	v_mfma_f32_16x16x32_bf16 v[52:55], v[148:151], v[174:177], v[52:55]
	v_mfma_f32_16x16x32_bf16 v[36:39], v[144:147], v[178:181], v[36:39]
	v_mfma_f32_16x16x32_bf16 v[36:39], v[148:151], v[182:185], v[36:39]
	v_mfma_f32_16x16x32_bf16 v[20:23], v[144:147], v[186:189], v[20:23]
	v_mfma_f32_16x16x32_bf16 v[20:23], v[148:151], v[190:193], v[20:23]
	v_mfma_f32_16x16x32_bf16 v[4:7], v[144:147], v[200:203], v[4:7]
	v_mfma_f32_16x16x32_bf16 v[4:7], v[148:151], v[204:207], v[4:7]
	v_mfma_f32_16x16x32_bf16 v[48:51], v[152:155], v[170:173], v[48:51]
	v_mfma_f32_16x16x32_bf16 v[48:51], v[166:169], v[174:177], v[48:51]
	v_mfma_f32_16x16x32_bf16 v[32:35], v[152:155], v[178:181], v[32:35]
	v_mfma_f32_16x16x32_bf16 v[32:35], v[166:169], v[182:185], v[32:35]
	v_mfma_f32_16x16x32_bf16 v[16:19], v[152:155], v[186:189], v[16:19]
	v_mfma_f32_16x16x32_bf16 v[16:19], v[166:169], v[190:193], v[16:19]
	v_mfma_f32_16x16x32_bf16 v[0:3], v[152:155], v[200:203], v[0:3]
	v_mfma_f32_16x16x32_bf16 v[0:3], v[166:169], v[204:207], v[0:3]
	s_barrier
	s_add_i32 s96, s96, 2
	s_add_u32 s94, s94, 0x100
	s_addc_u32 s95, s95, 0
	s_cmpk_gt_u32 s96, 0x55
	s_mov_b64 s[18:19], s[22:23]
	s_cbranch_scc0 .LBB0_560

.LBB0_826:
	s_ashr_i32 s17, s16, 31
	s_lshl_b64 s[18:19], s[16:17], 20
	s_add_u32 s18, s41, s18
	s_addc_u32 s19, s45, s19
	s_and_b64 s[22:23], s[4:5], exec
	s_cselect_b32 s7, s19, s53
	s_cselect_b32 s17, s18, s52
	s_ashr_i32 s15, s14, 31
	s_lshl_b64 s[22:23], s[14:15], 20
	s_add_u32 s22, s65, s22
	s_addc_u32 s23, s85, s23
	s_and_b64 s[54:55], s[4:5], exec
	s_cselect_b32 s15, s23, s91
	s_cselect_b32 vcc_lo, s22, s90
	s_add_u32 s88, s52, 0x80080
	s_addc_u32 s89, s53, 0
	s_add_u32 s90, s90, 0x100
	v_mov_b32_e32 v0, 0
	s_addc_u32 s91, s91, 0
	s_mov_b32 vcc_hi, -2
	s_add_u32 s52, s88, 0xfff80080
	s_addc_u32 s53, s89, -1
	s_add_i32 s58, 0, 0x10000
	s_cmp_eq_u32 vcc_hi, 28
	s_cselect_b32 s55, s7, s53
	s_cselect_b32 s54, s17, s52
	s_cselect_b32 s53, s15, s91
	s_cselect_b32 s52, vcc_lo, s90
	s_add_i32 s81, 0, 0x14000
	v_add_u32_e32 v140, s58, v197
	v_add_u32_e32 v156, s81, v197
	ds_read_b128 v[128:131], v140
	ds_read_b128 v[132:135], v140 offset:1024
	ds_read_b128 v[136:139], v140 offset:2048
	ds_read_b128 v[140:143], v140 offset:3072
	ds_read_b128 v[144:147], v156
	ds_read_b128 v[148:151], v156 offset:1024
	ds_read_b128 v[152:155], v156 offset:2048
	ds_read_b128 v[156:159], v156 offset:3072
	v_lshl_add_u64 v[198:199], s[88:89], 0, v[192:193]
	s_add_i32 m0, s76, 0xc000
	ds_read_b128 v[160:163], v203
	ds_read_b128 v[164:167], v203 offset:1024
	ds_read_b128 v[168:171], v203 offset:2048
	ds_read_b128 v[172:175], v203 offset:3072
	ds_read_b128 v[204:207], v203 offset:4096
	ds_read_b128 v[208:211], v203 offset:5120
	ds_read_b128 v[212:215], v203 offset:6144
	ds_read_b128 v[218:221], v203 offset:7168
	global_load_lds_dwordx4 v[198:199], off
	v_lshl_add_u64 v[198:199], s[88:89], 0, v[194:195]
	s_add_i32 m0, s76, 0xe000
	s_nop 0
	global_load_lds_dwordx4 v[198:199], off
	s_waitcnt vmcnt(8) lgkmcnt(0)
	s_barrier
	v_mfma_f32_16x16x32_bf16 v[124:127], v[128:131], v[160:163], 0
	v_mfma_f32_16x16x32_bf16 v[124:127], v[132:135], v[164:167], v[124:127]
	v_mfma_f32_16x16x32_bf16 v[108:111], v[128:131], v[168:171], 0
	v_mfma_f32_16x16x32_bf16 v[108:111], v[132:135], v[172:175], v[108:111]
	v_mfma_f32_16x16x32_bf16 v[92:95], v[128:131], v[204:207], 0
	v_mfma_f32_16x16x32_bf16 v[92:95], v[132:135], v[208:211], v[92:95]
	v_mfma_f32_16x16x32_bf16 v[76:79], v[128:131], v[212:215], 0
	v_mfma_f32_16x16x32_bf16 v[76:79], v[132:135], v[218:221], v[76:79]
	v_mfma_f32_16x16x32_bf16 v[120:123], v[136:139], v[160:163], 0
	v_mfma_f32_16x16x32_bf16 v[120:123], v[140:143], v[164:167], v[120:123]
	v_mfma_f32_16x16x32_bf16 v[104:107], v[136:139], v[168:171], 0
	v_mfma_f32_16x16x32_bf16 v[104:107], v[140:143], v[172:175], v[104:107]
	v_mfma_f32_16x16x32_bf16 v[88:91], v[136:139], v[204:207], 0
	v_mfma_f32_16x16x32_bf16 v[88:91], v[140:143], v[208:211], v[88:91]
	v_mfma_f32_16x16x32_bf16 v[72:75], v[136:139], v[212:215], 0
	v_mfma_f32_16x16x32_bf16 v[72:75], v[140:143], v[218:221], v[72:75]
	v_mfma_f32_16x16x32_bf16 v[116:119], v[144:147], v[160:163], 0
	v_mfma_f32_16x16x32_bf16 v[116:119], v[148:151], v[164:167], v[116:119]
	v_mfma_f32_16x16x32_bf16 v[100:103], v[144:147], v[168:171], 0
	v_mfma_f32_16x16x32_bf16 v[100:103], v[148:151], v[172:175], v[100:103]
	v_mfma_f32_16x16x32_bf16 v[84:87], v[144:147], v[204:207], 0
	v_mfma_f32_16x16x32_bf16 v[84:87], v[148:151], v[208:211], v[84:87]
	v_mfma_f32_16x16x32_bf16 v[68:71], v[144:147], v[212:215], 0
	v_mfma_f32_16x16x32_bf16 v[68:71], v[148:151], v[218:221], v[68:71]
	v_mfma_f32_16x16x32_bf16 v[112:115], v[152:155], v[160:163], 0
	v_mfma_f32_16x16x32_bf16 v[112:115], v[156:159], v[164:167], v[112:115]
	v_mfma_f32_16x16x32_bf16 v[96:99], v[152:155], v[168:171], 0
	v_mfma_f32_16x16x32_bf16 v[96:99], v[156:159], v[172:175], v[96:99]
	v_mfma_f32_16x16x32_bf16 v[80:83], v[152:155], v[204:207], 0
	v_mfma_f32_16x16x32_bf16 v[80:83], v[156:159], v[208:211], v[80:83]
	v_mfma_f32_16x16x32_bf16 v[64:67], v[152:155], v[212:215], 0
	v_mfma_f32_16x16x32_bf16 v[64:67], v[156:159], v[218:221], v[64:67]
	s_barrier
	s_add_i32 s58, s58, s50
	v_lshl_add_u64 v[198:199], s[52:53], 0, v[178:179]
	s_mov_b32 m0, s58
	ds_read_b128 v[160:163], v203 offset:16384
	ds_read_b128 v[164:167], v203 offset:17408
	ds_read_b128 v[168:171], v203 offset:18432
	ds_read_b128 v[172:175], v203 offset:19456
	ds_read_b128 v[204:207], v203 offset:20480
	ds_read_b128 v[208:211], v203 offset:21504
	ds_read_b128 v[212:215], v203 offset:22528
	ds_read_b128 v[218:221], v203 offset:23552
	global_load_lds_dwordx4 v[198:199], off
	s_add_i32 m0, s58, 0x2000
	s_add_u32 s58, s52, 0x80000
	v_lshl_add_u64 v[222:223], s[52:53], 0, v[182:183]
	s_addc_u32 s59, s53, 0
	s_add_i32 s81, s81, s50
	global_load_lds_dwordx4 v[222:223], off
	v_lshl_add_u64 v[224:225], s[58:59], 0, v[178:179]
	s_mov_b32 m0, s81
	v_lshl_add_u64 v[226:227], s[54:55], 0, v[180:181]
	global_load_lds_dwordx4 v[224:225], off
	v_lshl_add_u64 v[224:225], s[58:59], 0, v[182:183]
	s_add_i32 m0, s81, 0x2000
	s_nop 0
	global_load_lds_dwordx4 v[224:225], off
	v_lshl_add_u64 v[224:225], s[54:55], 0, v[176:177]
	s_mov_b32 m0, s76
	s_nop 0
	global_load_lds_dwordx4 v[224:225], off
	s_mov_b32 m0, s87
	s_nop 0
	global_load_lds_dwordx4 v[226:227], off
	s_waitcnt vmcnt(8) lgkmcnt(0)
	s_barrier
	v_mfma_f32_16x16x32_bf16 v[60:63], v[128:131], v[160:163], 0
	v_mfma_f32_16x16x32_bf16 v[60:63], v[132:135], v[164:167], v[60:63]
	v_mfma_f32_16x16x32_bf16 v[44:47], v[128:131], v[168:171], 0
	v_mfma_f32_16x16x32_bf16 v[44:47], v[132:135], v[172:175], v[44:47]
	v_mfma_f32_16x16x32_bf16 v[28:31], v[128:131], v[204:207], 0
	v_mfma_f32_16x16x32_bf16 v[28:31], v[132:135], v[208:211], v[28:31]
	v_mfma_f32_16x16x32_bf16 v[12:15], v[128:131], v[212:215], 0
	v_mfma_f32_16x16x32_bf16 v[12:15], v[132:135], v[218:221], v[12:15]
	v_mfma_f32_16x16x32_bf16 v[56:59], v[136:139], v[160:163], 0
	v_mfma_f32_16x16x32_bf16 v[56:59], v[140:143], v[164:167], v[56:59]
	v_mfma_f32_16x16x32_bf16 v[40:43], v[136:139], v[168:171], 0
	v_mfma_f32_16x16x32_bf16 v[40:43], v[140:143], v[172:175], v[40:43]
	v_mfma_f32_16x16x32_bf16 v[24:27], v[136:139], v[204:207], 0
	v_mfma_f32_16x16x32_bf16 v[24:27], v[140:143], v[208:211], v[24:27]
	v_mfma_f32_16x16x32_bf16 v[8:11], v[136:139], v[212:215], 0
	v_mfma_f32_16x16x32_bf16 v[8:11], v[140:143], v[218:221], v[8:11]
	v_mfma_f32_16x16x32_bf16 v[52:55], v[144:147], v[160:163], 0
	v_mfma_f32_16x16x32_bf16 v[52:55], v[148:151], v[164:167], v[52:55]
	v_mfma_f32_16x16x32_bf16 v[36:39], v[144:147], v[168:171], 0
	v_mfma_f32_16x16x32_bf16 v[36:39], v[148:151], v[172:175], v[36:39]
	v_mfma_f32_16x16x32_bf16 v[20:23], v[144:147], v[204:207], 0
	v_mfma_f32_16x16x32_bf16 v[20:23], v[148:151], v[208:211], v[20:23]
	v_mfma_f32_16x16x32_bf16 v[4:7], v[144:147], v[212:215], 0
	v_mfma_f32_16x16x32_bf16 v[4:7], v[148:151], v[218:221], v[4:7]
	v_mfma_f32_16x16x32_bf16 v[48:51], v[152:155], v[160:163], 0
	v_mfma_f32_16x16x32_bf16 v[48:51], v[156:159], v[164:167], v[48:51]
	v_mfma_f32_16x16x32_bf16 v[32:35], v[152:155], v[168:171], 0
	v_mfma_f32_16x16x32_bf16 v[32:35], v[156:159], v[172:175], v[32:35]
	v_mfma_f32_16x16x32_bf16 v[16:19], v[152:155], v[204:207], 0
	v_mfma_f32_16x16x32_bf16 v[16:19], v[156:159], v[208:211], v[16:19]
	v_mfma_f32_16x16x32_bf16 v[0:3], v[152:155], v[212:215], 0
	v_mfma_f32_16x16x32_bf16 v[0:3], v[156:159], v[218:221], v[0:3]
	s_barrier
	s_add_i32 s58, 0, 0x18000
	s_add_i32 s59, 0, 0x1c000
	v_add_u32_e32 v140, s58, v197
	v_add_u32_e32 v156, s59, v197
	ds_read_b128 v[128:131], v140
	ds_read_b128 v[132:135], v140 offset:1024
	ds_read_b128 v[136:139], v140 offset:2048
	ds_read_b128 v[140:143], v140 offset:3072
	ds_read_b128 v[144:147], v156
	ds_read_b128 v[148:151], v156 offset:1024
	ds_read_b128 v[152:155], v156 offset:2048
	ds_read_b128 v[156:159], v156 offset:3072
	s_add_u32 s54, s54, 0x80000
	s_addc_u32 s55, s55, 0
	s_mov_b32 m0, s92
	v_lshl_add_u64 v[228:229], s[54:55], 0, v[176:177]
	ds_read_b128 v[160:163], v203 offset:32768
	ds_read_b128 v[164:167], v203 offset:33792
	ds_read_b128 v[168:171], v203 offset:34816
	ds_read_b128 v[172:175], v203 offset:35840
	ds_read_b128 v[204:207], v203 offset:36864
	ds_read_b128 v[208:211], v203 offset:37888
	ds_read_b128 v[212:215], v203 offset:38912
	ds_read_b128 v[218:221], v203 offset:39936
	global_load_lds_dwordx4 v[228:229], off
	v_lshl_add_u64 v[228:229], s[54:55], 0, v[180:181]
	s_mov_b32 m0, s93
	s_nop 0
	global_load_lds_dwordx4 v[228:229], off
	s_waitcnt vmcnt(8) lgkmcnt(0)
	s_barrier
	v_mfma_f32_16x16x32_bf16 v[124:127], v[128:131], v[160:163], v[124:127]
	v_mfma_f32_16x16x32_bf16 v[124:127], v[132:135], v[164:167], v[124:127]
	v_mfma_f32_16x16x32_bf16 v[108:111], v[128:131], v[168:171], v[108:111]
	v_mfma_f32_16x16x32_bf16 v[108:111], v[132:135], v[172:175], v[108:111]
	v_mfma_f32_16x16x32_bf16 v[92:95], v[128:131], v[204:207], v[92:95]
	v_mfma_f32_16x16x32_bf16 v[92:95], v[132:135], v[208:211], v[92:95]
	v_mfma_f32_16x16x32_bf16 v[76:79], v[128:131], v[212:215], v[76:79]
	v_mfma_f32_16x16x32_bf16 v[76:79], v[132:135], v[218:221], v[76:79]
	v_mfma_f32_16x16x32_bf16 v[120:123], v[136:139], v[160:163], v[120:123]
	v_mfma_f32_16x16x32_bf16 v[120:123], v[140:143], v[164:167], v[120:123]
	v_mfma_f32_16x16x32_bf16 v[104:107], v[136:139], v[168:171], v[104:107]
	v_mfma_f32_16x16x32_bf16 v[104:107], v[140:143], v[172:175], v[104:107]
	v_mfma_f32_16x16x32_bf16 v[88:91], v[136:139], v[204:207], v[88:91]
	v_mfma_f32_16x16x32_bf16 v[88:91], v[140:143], v[208:211], v[88:91]
	v_mfma_f32_16x16x32_bf16 v[72:75], v[136:139], v[212:215], v[72:75]
	v_mfma_f32_16x16x32_bf16 v[72:75], v[140:143], v[218:221], v[72:75]
	v_mfma_f32_16x16x32_bf16 v[116:119], v[144:147], v[160:163], v[116:119]
	v_mfma_f32_16x16x32_bf16 v[116:119], v[148:151], v[164:167], v[116:119]
	v_mfma_f32_16x16x32_bf16 v[100:103], v[144:147], v[168:171], v[100:103]
	v_mfma_f32_16x16x32_bf16 v[100:103], v[148:151], v[172:175], v[100:103]
	v_mfma_f32_16x16x32_bf16 v[84:87], v[144:147], v[204:207], v[84:87]
	v_mfma_f32_16x16x32_bf16 v[84:87], v[148:151], v[208:211], v[84:87]
	v_mfma_f32_16x16x32_bf16 v[68:71], v[144:147], v[212:215], v[68:71]
	v_mfma_f32_16x16x32_bf16 v[68:71], v[148:151], v[218:221], v[68:71]
	v_mfma_f32_16x16x32_bf16 v[112:115], v[152:155], v[160:163], v[112:115]
	v_mfma_f32_16x16x32_bf16 v[112:115], v[156:159], v[164:167], v[112:115]
	v_mfma_f32_16x16x32_bf16 v[96:99], v[152:155], v[168:171], v[96:99]
	v_mfma_f32_16x16x32_bf16 v[96:99], v[156:159], v[172:175], v[96:99]
	v_mfma_f32_16x16x32_bf16 v[80:83], v[152:155], v[204:207], v[80:83]
	v_mfma_f32_16x16x32_bf16 v[80:83], v[156:159], v[208:211], v[80:83]
	v_mfma_f32_16x16x32_bf16 v[64:67], v[152:155], v[212:215], v[64:67]
	v_mfma_f32_16x16x32_bf16 v[64:67], v[156:159], v[218:221], v[64:67]
	s_barrier
	s_add_i32 s54, s58, s50
	v_lshl_add_u64 v[198:199], v[198:199], 0, s[60:61]
	s_mov_b32 m0, s54
	ds_read_b128 v[160:163], v203 offset:49152
	ds_read_b128 v[164:167], v203 offset:50176
	ds_read_b128 v[168:171], v203 offset:51200
	ds_read_b128 v[172:175], v203 offset:52224
	ds_read_b128 v[204:207], v203 offset:53248
	ds_read_b128 v[208:211], v203 offset:54272
	ds_read_b128 v[212:215], v203 offset:55296
	ds_read_b128 v[218:221], v203 offset:56320
	global_load_lds_dwordx4 v[198:199], off
	s_add_i32 m0, s54, 0x2000
	s_add_u32 s52, s52, 0x80080
	v_lshl_add_u64 v[198:199], v[222:223], 0, s[60:61]
	s_addc_u32 s53, s53, 0
	s_add_i32 s54, s59, s50
	global_load_lds_dwordx4 v[198:199], off
	v_lshl_add_u64 v[198:199], s[52:53], 0, v[178:179]
	s_mov_b32 m0, s54
	s_nop 0
	global_load_lds_dwordx4 v[198:199], off
	v_lshl_add_u64 v[198:199], s[52:53], 0, v[182:183]
	s_add_i32 m0, s54, 0x2000
	s_nop 0
	global_load_lds_dwordx4 v[198:199], off
	v_lshl_add_u64 v[198:199], v[224:225], 0, s[60:61]
	s_mov_b32 m0, s94
	s_nop 0
	global_load_lds_dwordx4 v[198:199], off
	v_lshl_add_u64 v[198:199], v[226:227], 0, s[60:61]
	s_mov_b32 m0, s95
	s_nop 0
	global_load_lds_dwordx4 v[198:199], off
	s_waitcnt vmcnt(8) lgkmcnt(0)
	s_barrier
	v_mfma_f32_16x16x32_bf16 v[60:63], v[128:131], v[160:163], v[60:63]
	v_mfma_f32_16x16x32_bf16 v[60:63], v[132:135], v[164:167], v[60:63]
	v_mfma_f32_16x16x32_bf16 v[44:47], v[128:131], v[168:171], v[44:47]
	v_mfma_f32_16x16x32_bf16 v[44:47], v[132:135], v[172:175], v[44:47]
	v_mfma_f32_16x16x32_bf16 v[28:31], v[128:131], v[204:207], v[28:31]
	v_mfma_f32_16x16x32_bf16 v[28:31], v[132:135], v[208:211], v[28:31]
	v_mfma_f32_16x16x32_bf16 v[12:15], v[128:131], v[212:215], v[12:15]
	v_mfma_f32_16x16x32_bf16 v[12:15], v[132:135], v[218:221], v[12:15]
	v_mfma_f32_16x16x32_bf16 v[56:59], v[136:139], v[160:163], v[56:59]
	v_mfma_f32_16x16x32_bf16 v[56:59], v[140:143], v[164:167], v[56:59]
	v_mfma_f32_16x16x32_bf16 v[40:43], v[136:139], v[168:171], v[40:43]
	v_mfma_f32_16x16x32_bf16 v[40:43], v[140:143], v[172:175], v[40:43]
	v_mfma_f32_16x16x32_bf16 v[24:27], v[136:139], v[204:207], v[24:27]
	v_mfma_f32_16x16x32_bf16 v[24:27], v[140:143], v[208:211], v[24:27]
	v_mfma_f32_16x16x32_bf16 v[8:11], v[136:139], v[212:215], v[8:11]
	v_mfma_f32_16x16x32_bf16 v[8:11], v[140:143], v[218:221], v[8:11]
	v_mfma_f32_16x16x32_bf16 v[52:55], v[144:147], v[160:163], v[52:55]
	v_mfma_f32_16x16x32_bf16 v[52:55], v[148:151], v[164:167], v[52:55]
	v_mfma_f32_16x16x32_bf16 v[36:39], v[144:147], v[168:171], v[36:39]
	v_mfma_f32_16x16x32_bf16 v[36:39], v[148:151], v[172:175], v[36:39]
	v_mfma_f32_16x16x32_bf16 v[20:23], v[144:147], v[204:207], v[20:23]
	v_mfma_f32_16x16x32_bf16 v[20:23], v[148:151], v[208:211], v[20:23]
	v_mfma_f32_16x16x32_bf16 v[4:7], v[144:147], v[212:215], v[4:7]
	v_mfma_f32_16x16x32_bf16 v[4:7], v[148:151], v[218:221], v[4:7]
	v_mfma_f32_16x16x32_bf16 v[48:51], v[152:155], v[160:163], v[48:51]
	v_mfma_f32_16x16x32_bf16 v[48:51], v[156:159], v[164:167], v[48:51]
	v_mfma_f32_16x16x32_bf16 v[32:35], v[152:155], v[168:171], v[32:35]
	v_mfma_f32_16x16x32_bf16 v[32:35], v[156:159], v[172:175], v[32:35]
	v_mfma_f32_16x16x32_bf16 v[16:19], v[152:155], v[204:207], v[16:19]
	v_mfma_f32_16x16x32_bf16 v[16:19], v[156:159], v[208:211], v[16:19]
	v_mfma_f32_16x16x32_bf16 v[0:3], v[152:155], v[212:215], v[0:3]
	v_mfma_f32_16x16x32_bf16 v[0:3], v[156:159], v[218:221], v[0:3]
	s_barrier
	s_add_i32 vcc_hi, vcc_hi, 2
	s_add_u32 s88, s88, 0x100
	s_addc_u32 s89, s89, 0
	s_add_u32 s90, s90, 0x100
	s_addc_u32 s91, s91, 0
	s_cmp_gt_u32 vcc_hi, 29
	s_cbranch_scc0 .LBB0_827
	s_branch .Lzexit_2
.LBB0_827:
	s_add_u32 s52, s88, 0xfff80080
	s_addc_u32 s53, s89, -1
	s_add_i32 s58, 0, 0x10000
	s_cmp_eq_u32 vcc_hi, 28
	s_cselect_b32 s55, s7, s53
	s_cselect_b32 s54, s17, s52
	s_cselect_b32 s53, s15, s91
	s_cselect_b32 s52, vcc_lo, s90
	s_add_i32 s81, 0, 0x14000
	v_add_u32_e32 v140, s58, v197
	v_add_u32_e32 v156, s81, v197
	ds_read_b128 v[128:131], v140
	ds_read_b128 v[132:135], v140 offset:1024
	ds_read_b128 v[136:139], v140 offset:2048
	ds_read_b128 v[140:143], v140 offset:3072
	ds_read_b128 v[144:147], v156
	ds_read_b128 v[148:151], v156 offset:1024
	ds_read_b128 v[152:155], v156 offset:2048
	ds_read_b128 v[156:159], v156 offset:3072
	v_lshl_add_u64 v[198:199], s[88:89], 0, v[192:193]
	s_add_i32 m0, s76, 0xc000
	ds_read_b128 v[160:163], v203
	ds_read_b128 v[164:167], v203 offset:1024
	ds_read_b128 v[168:171], v203 offset:2048
	ds_read_b128 v[172:175], v203 offset:3072
	ds_read_b128 v[204:207], v203 offset:4096
	ds_read_b128 v[208:211], v203 offset:5120
	ds_read_b128 v[212:215], v203 offset:6144
	ds_read_b128 v[218:221], v203 offset:7168
	global_load_lds_dwordx4 v[198:199], off
	v_lshl_add_u64 v[198:199], s[88:89], 0, v[194:195]
	s_add_i32 m0, s76, 0xe000
	s_nop 0
	global_load_lds_dwordx4 v[198:199], off
	s_waitcnt vmcnt(8) lgkmcnt(0)
	s_barrier
	v_mfma_f32_16x16x32_bf16 v[124:127], v[128:131], v[160:163], v[124:127]
	v_mfma_f32_16x16x32_bf16 v[124:127], v[132:135], v[164:167], v[124:127]
	v_mfma_f32_16x16x32_bf16 v[108:111], v[128:131], v[168:171], v[108:111]
	v_mfma_f32_16x16x32_bf16 v[108:111], v[132:135], v[172:175], v[108:111]
	v_mfma_f32_16x16x32_bf16 v[92:95], v[128:131], v[204:207], v[92:95]
	v_mfma_f32_16x16x32_bf16 v[92:95], v[132:135], v[208:211], v[92:95]
	v_mfma_f32_16x16x32_bf16 v[76:79], v[128:131], v[212:215], v[76:79]
	v_mfma_f32_16x16x32_bf16 v[76:79], v[132:135], v[218:221], v[76:79]
	v_mfma_f32_16x16x32_bf16 v[120:123], v[136:139], v[160:163], v[120:123]
	v_mfma_f32_16x16x32_bf16 v[120:123], v[140:143], v[164:167], v[120:123]
	v_mfma_f32_16x16x32_bf16 v[104:107], v[136:139], v[168:171], v[104:107]
	v_mfma_f32_16x16x32_bf16 v[104:107], v[140:143], v[172:175], v[104:107]
	v_mfma_f32_16x16x32_bf16 v[88:91], v[136:139], v[204:207], v[88:91]
	v_mfma_f32_16x16x32_bf16 v[88:91], v[140:143], v[208:211], v[88:91]
	v_mfma_f32_16x16x32_bf16 v[72:75], v[136:139], v[212:215], v[72:75]
	v_mfma_f32_16x16x32_bf16 v[72:75], v[140:143], v[218:221], v[72:75]
	v_mfma_f32_16x16x32_bf16 v[116:119], v[144:147], v[160:163], v[116:119]
	v_mfma_f32_16x16x32_bf16 v[116:119], v[148:151], v[164:167], v[116:119]
	v_mfma_f32_16x16x32_bf16 v[100:103], v[144:147], v[168:171], v[100:103]
	v_mfma_f32_16x16x32_bf16 v[100:103], v[148:151], v[172:175], v[100:103]
	v_mfma_f32_16x16x32_bf16 v[84:87], v[144:147], v[204:207], v[84:87]
	v_mfma_f32_16x16x32_bf16 v[84:87], v[148:151], v[208:211], v[84:87]
	v_mfma_f32_16x16x32_bf16 v[68:71], v[144:147], v[212:215], v[68:71]
	v_mfma_f32_16x16x32_bf16 v[68:71], v[148:151], v[218:221], v[68:71]
	v_mfma_f32_16x16x32_bf16 v[112:115], v[152:155], v[160:163], v[112:115]
	v_mfma_f32_16x16x32_bf16 v[112:115], v[156:159], v[164:167], v[112:115]
	v_mfma_f32_16x16x32_bf16 v[96:99], v[152:155], v[168:171], v[96:99]
	v_mfma_f32_16x16x32_bf16 v[96:99], v[156:159], v[172:175], v[96:99]
	v_mfma_f32_16x16x32_bf16 v[80:83], v[152:155], v[204:207], v[80:83]
	v_mfma_f32_16x16x32_bf16 v[80:83], v[156:159], v[208:211], v[80:83]
	v_mfma_f32_16x16x32_bf16 v[64:67], v[152:155], v[212:215], v[64:67]
	v_mfma_f32_16x16x32_bf16 v[64:67], v[156:159], v[218:221], v[64:67]
	s_barrier
	s_add_i32 s58, s58, s50
	v_lshl_add_u64 v[198:199], s[52:53], 0, v[178:179]
	s_mov_b32 m0, s58
	ds_read_b128 v[160:163], v203 offset:16384
	ds_read_b128 v[164:167], v203 offset:17408
	ds_read_b128 v[168:171], v203 offset:18432
	ds_read_b128 v[172:175], v203 offset:19456
	ds_read_b128 v[204:207], v203 offset:20480
	ds_read_b128 v[208:211], v203 offset:21504
	ds_read_b128 v[212:215], v203 offset:22528
	ds_read_b128 v[218:221], v203 offset:23552
	global_load_lds_dwordx4 v[198:199], off
	s_add_i32 m0, s58, 0x2000
	s_add_u32 s58, s52, 0x80000
	v_lshl_add_u64 v[222:223], s[52:53], 0, v[182:183]
	s_addc_u32 s59, s53, 0
	s_add_i32 s81, s81, s50
	global_load_lds_dwordx4 v[222:223], off
	v_lshl_add_u64 v[224:225], s[58:59], 0, v[178:179]
	s_mov_b32 m0, s81
	v_lshl_add_u64 v[226:227], s[54:55], 0, v[180:181]
	global_load_lds_dwordx4 v[224:225], off
	v_lshl_add_u64 v[224:225], s[58:59], 0, v[182:183]
	s_add_i32 m0, s81, 0x2000
	s_nop 0
	global_load_lds_dwordx4 v[224:225], off
	v_lshl_add_u64 v[224:225], s[54:55], 0, v[176:177]
	s_mov_b32 m0, s76
	s_nop 0
	global_load_lds_dwordx4 v[224:225], off
	s_mov_b32 m0, s87
	s_nop 0
	global_load_lds_dwordx4 v[226:227], off
	s_waitcnt vmcnt(8) lgkmcnt(0)
	s_barrier
	v_mfma_f32_16x16x32_bf16 v[60:63], v[128:131], v[160:163], v[60:63]
	v_mfma_f32_16x16x32_bf16 v[60:63], v[132:135], v[164:167], v[60:63]
	v_mfma_f32_16x16x32_bf16 v[44:47], v[128:131], v[168:171], v[44:47]
	v_mfma_f32_16x16x32_bf16 v[44:47], v[132:135], v[172:175], v[44:47]
	v_mfma_f32_16x16x32_bf16 v[28:31], v[128:131], v[204:207], v[28:31]
	v_mfma_f32_16x16x32_bf16 v[28:31], v[132:135], v[208:211], v[28:31]
	v_mfma_f32_16x16x32_bf16 v[12:15], v[128:131], v[212:215], v[12:15]
	v_mfma_f32_16x16x32_bf16 v[12:15], v[132:135], v[218:221], v[12:15]
	v_mfma_f32_16x16x32_bf16 v[56:59], v[136:139], v[160:163], v[56:59]
	v_mfma_f32_16x16x32_bf16 v[56:59], v[140:143], v[164:167], v[56:59]
	v_mfma_f32_16x16x32_bf16 v[40:43], v[136:139], v[168:171], v[40:43]
	v_mfma_f32_16x16x32_bf16 v[40:43], v[140:143], v[172:175], v[40:43]
	v_mfma_f32_16x16x32_bf16 v[24:27], v[136:139], v[204:207], v[24:27]
	v_mfma_f32_16x16x32_bf16 v[24:27], v[140:143], v[208:211], v[24:27]
	v_mfma_f32_16x16x32_bf16 v[8:11], v[136:139], v[212:215], v[8:11]
	v_mfma_f32_16x16x32_bf16 v[8:11], v[140:143], v[218:221], v[8:11]
	v_mfma_f32_16x16x32_bf16 v[52:55], v[144:147], v[160:163], v[52:55]
	v_mfma_f32_16x16x32_bf16 v[52:55], v[148:151], v[164:167], v[52:55]
	v_mfma_f32_16x16x32_bf16 v[36:39], v[144:147], v[168:171], v[36:39]
	v_mfma_f32_16x16x32_bf16 v[36:39], v[148:151], v[172:175], v[36:39]
	v_mfma_f32_16x16x32_bf16 v[20:23], v[144:147], v[204:207], v[20:23]
	v_mfma_f32_16x16x32_bf16 v[20:23], v[148:151], v[208:211], v[20:23]
	v_mfma_f32_16x16x32_bf16 v[4:7], v[144:147], v[212:215], v[4:7]
	v_mfma_f32_16x16x32_bf16 v[4:7], v[148:151], v[218:221], v[4:7]
	v_mfma_f32_16x16x32_bf16 v[48:51], v[152:155], v[160:163], v[48:51]
	v_mfma_f32_16x16x32_bf16 v[48:51], v[156:159], v[164:167], v[48:51]
	v_mfma_f32_16x16x32_bf16 v[32:35], v[152:155], v[168:171], v[32:35]
	v_mfma_f32_16x16x32_bf16 v[32:35], v[156:159], v[172:175], v[32:35]
	v_mfma_f32_16x16x32_bf16 v[16:19], v[152:155], v[204:207], v[16:19]
	v_mfma_f32_16x16x32_bf16 v[16:19], v[156:159], v[208:211], v[16:19]
	v_mfma_f32_16x16x32_bf16 v[0:3], v[152:155], v[212:215], v[0:3]
	v_mfma_f32_16x16x32_bf16 v[0:3], v[156:159], v[218:221], v[0:3]
	s_barrier
	s_add_i32 s58, 0, 0x18000
	s_add_i32 s59, 0, 0x1c000
	v_add_u32_e32 v140, s58, v197
	v_add_u32_e32 v156, s59, v197
	ds_read_b128 v[128:131], v140
	ds_read_b128 v[132:135], v140 offset:1024
	ds_read_b128 v[136:139], v140 offset:2048
	ds_read_b128 v[140:143], v140 offset:3072
	ds_read_b128 v[144:147], v156
	ds_read_b128 v[148:151], v156 offset:1024
	ds_read_b128 v[152:155], v156 offset:2048
	ds_read_b128 v[156:159], v156 offset:3072
	s_add_u32 s54, s54, 0x80000
	s_addc_u32 s55, s55, 0
	s_mov_b32 m0, s92
	v_lshl_add_u64 v[228:229], s[54:55], 0, v[176:177]
	ds_read_b128 v[160:163], v203 offset:32768
	ds_read_b128 v[164:167], v203 offset:33792
	ds_read_b128 v[168:171], v203 offset:34816
	ds_read_b128 v[172:175], v203 offset:35840
	ds_read_b128 v[204:207], v203 offset:36864
	ds_read_b128 v[208:211], v203 offset:37888
	ds_read_b128 v[212:215], v203 offset:38912
	ds_read_b128 v[218:221], v203 offset:39936
	global_load_lds_dwordx4 v[228:229], off
	v_lshl_add_u64 v[228:229], s[54:55], 0, v[180:181]
	s_mov_b32 m0, s93
	s_nop 0
	global_load_lds_dwordx4 v[228:229], off
	s_waitcnt vmcnt(8) lgkmcnt(0)
	s_barrier
	v_mfma_f32_16x16x32_bf16 v[124:127], v[128:131], v[160:163], v[124:127]
	v_mfma_f32_16x16x32_bf16 v[124:127], v[132:135], v[164:167], v[124:127]
	v_mfma_f32_16x16x32_bf16 v[108:111], v[128:131], v[168:171], v[108:111]
	v_mfma_f32_16x16x32_bf16 v[108:111], v[132:135], v[172:175], v[108:111]
	v_mfma_f32_16x16x32_bf16 v[92:95], v[128:131], v[204:207], v[92:95]
	v_mfma_f32_16x16x32_bf16 v[92:95], v[132:135], v[208:211], v[92:95]
	v_mfma_f32_16x16x32_bf16 v[76:79], v[128:131], v[212:215], v[76:79]
	v_mfma_f32_16x16x32_bf16 v[76:79], v[132:135], v[218:221], v[76:79]
	v_mfma_f32_16x16x32_bf16 v[120:123], v[136:139], v[160:163], v[120:123]
	v_mfma_f32_16x16x32_bf16 v[120:123], v[140:143], v[164:167], v[120:123]
	v_mfma_f32_16x16x32_bf16 v[104:107], v[136:139], v[168:171], v[104:107]
	v_mfma_f32_16x16x32_bf16 v[104:107], v[140:143], v[172:175], v[104:107]
	v_mfma_f32_16x16x32_bf16 v[88:91], v[136:139], v[204:207], v[88:91]
	v_mfma_f32_16x16x32_bf16 v[88:91], v[140:143], v[208:211], v[88:91]
	v_mfma_f32_16x16x32_bf16 v[72:75], v[136:139], v[212:215], v[72:75]
	v_mfma_f32_16x16x32_bf16 v[72:75], v[140:143], v[218:221], v[72:75]
	v_mfma_f32_16x16x32_bf16 v[116:119], v[144:147], v[160:163], v[116:119]
	v_mfma_f32_16x16x32_bf16 v[116:119], v[148:151], v[164:167], v[116:119]
	v_mfma_f32_16x16x32_bf16 v[100:103], v[144:147], v[168:171], v[100:103]
	v_mfma_f32_16x16x32_bf16 v[100:103], v[148:151], v[172:175], v[100:103]
	v_mfma_f32_16x16x32_bf16 v[84:87], v[144:147], v[204:207], v[84:87]
	v_mfma_f32_16x16x32_bf16 v[84:87], v[148:151], v[208:211], v[84:87]
	v_mfma_f32_16x16x32_bf16 v[68:71], v[144:147], v[212:215], v[68:71]
	v_mfma_f32_16x16x32_bf16 v[68:71], v[148:151], v[218:221], v[68:71]
	v_mfma_f32_16x16x32_bf16 v[112:115], v[152:155], v[160:163], v[112:115]
	v_mfma_f32_16x16x32_bf16 v[112:115], v[156:159], v[164:167], v[112:115]
	v_mfma_f32_16x16x32_bf16 v[96:99], v[152:155], v[168:171], v[96:99]
	v_mfma_f32_16x16x32_bf16 v[96:99], v[156:159], v[172:175], v[96:99]
	v_mfma_f32_16x16x32_bf16 v[80:83], v[152:155], v[204:207], v[80:83]
	v_mfma_f32_16x16x32_bf16 v[80:83], v[156:159], v[208:211], v[80:83]
	v_mfma_f32_16x16x32_bf16 v[64:67], v[152:155], v[212:215], v[64:67]
	v_mfma_f32_16x16x32_bf16 v[64:67], v[156:159], v[218:221], v[64:67]
	s_barrier
	s_add_i32 s54, s58, s50
	v_lshl_add_u64 v[198:199], v[198:199], 0, s[60:61]
	s_mov_b32 m0, s54
	ds_read_b128 v[160:163], v203 offset:49152
	ds_read_b128 v[164:167], v203 offset:50176
	ds_read_b128 v[168:171], v203 offset:51200
	ds_read_b128 v[172:175], v203 offset:52224
	ds_read_b128 v[204:207], v203 offset:53248
	ds_read_b128 v[208:211], v203 offset:54272
	ds_read_b128 v[212:215], v203 offset:55296
	ds_read_b128 v[218:221], v203 offset:56320
	global_load_lds_dwordx4 v[198:199], off
	s_add_i32 m0, s54, 0x2000
	s_add_u32 s52, s52, 0x80080
	v_lshl_add_u64 v[198:199], v[222:223], 0, s[60:61]
	s_addc_u32 s53, s53, 0
	s_add_i32 s54, s59, s50
	global_load_lds_dwordx4 v[198:199], off
	v_lshl_add_u64 v[198:199], s[52:53], 0, v[178:179]
	s_mov_b32 m0, s54
	s_nop 0
	global_load_lds_dwordx4 v[198:199], off
	v_lshl_add_u64 v[198:199], s[52:53], 0, v[182:183]
	s_add_i32 m0, s54, 0x2000
	s_nop 0
	global_load_lds_dwordx4 v[198:199], off
	v_lshl_add_u64 v[198:199], v[224:225], 0, s[60:61]
	s_mov_b32 m0, s94
	s_nop 0
	global_load_lds_dwordx4 v[198:199], off
	v_lshl_add_u64 v[198:199], v[226:227], 0, s[60:61]
	s_mov_b32 m0, s95
	s_nop 0
	global_load_lds_dwordx4 v[198:199], off
	s_waitcnt vmcnt(8) lgkmcnt(0)
	s_barrier
	v_mfma_f32_16x16x32_bf16 v[60:63], v[128:131], v[160:163], v[60:63]
	v_mfma_f32_16x16x32_bf16 v[60:63], v[132:135], v[164:167], v[60:63]
	v_mfma_f32_16x16x32_bf16 v[44:47], v[128:131], v[168:171], v[44:47]
	v_mfma_f32_16x16x32_bf16 v[44:47], v[132:135], v[172:175], v[44:47]
	v_mfma_f32_16x16x32_bf16 v[28:31], v[128:131], v[204:207], v[28:31]
	v_mfma_f32_16x16x32_bf16 v[28:31], v[132:135], v[208:211], v[28:31]
	v_mfma_f32_16x16x32_bf16 v[12:15], v[128:131], v[212:215], v[12:15]
	v_mfma_f32_16x16x32_bf16 v[12:15], v[132:135], v[218:221], v[12:15]
	v_mfma_f32_16x16x32_bf16 v[56:59], v[136:139], v[160:163], v[56:59]
	v_mfma_f32_16x16x32_bf16 v[56:59], v[140:143], v[164:167], v[56:59]
	v_mfma_f32_16x16x32_bf16 v[40:43], v[136:139], v[168:171], v[40:43]
	v_mfma_f32_16x16x32_bf16 v[40:43], v[140:143], v[172:175], v[40:43]
	v_mfma_f32_16x16x32_bf16 v[24:27], v[136:139], v[204:207], v[24:27]
	v_mfma_f32_16x16x32_bf16 v[24:27], v[140:143], v[208:211], v[24:27]
	v_mfma_f32_16x16x32_bf16 v[8:11], v[136:139], v[212:215], v[8:11]
	v_mfma_f32_16x16x32_bf16 v[8:11], v[140:143], v[218:221], v[8:11]
	v_mfma_f32_16x16x32_bf16 v[52:55], v[144:147], v[160:163], v[52:55]
	v_mfma_f32_16x16x32_bf16 v[52:55], v[148:151], v[164:167], v[52:55]
	v_mfma_f32_16x16x32_bf16 v[36:39], v[144:147], v[168:171], v[36:39]
	v_mfma_f32_16x16x32_bf16 v[36:39], v[148:151], v[172:175], v[36:39]
	v_mfma_f32_16x16x32_bf16 v[20:23], v[144:147], v[204:207], v[20:23]
	v_mfma_f32_16x16x32_bf16 v[20:23], v[148:151], v[208:211], v[20:23]
	v_mfma_f32_16x16x32_bf16 v[4:7], v[144:147], v[212:215], v[4:7]
	v_mfma_f32_16x16x32_bf16 v[4:7], v[148:151], v[218:221], v[4:7]
	v_mfma_f32_16x16x32_bf16 v[48:51], v[152:155], v[160:163], v[48:51]
	v_mfma_f32_16x16x32_bf16 v[48:51], v[156:159], v[164:167], v[48:51]
	v_mfma_f32_16x16x32_bf16 v[32:35], v[152:155], v[168:171], v[32:35]
	v_mfma_f32_16x16x32_bf16 v[32:35], v[156:159], v[172:175], v[32:35]
	v_mfma_f32_16x16x32_bf16 v[16:19], v[152:155], v[204:207], v[16:19]
	v_mfma_f32_16x16x32_bf16 v[16:19], v[156:159], v[208:211], v[16:19]
	v_mfma_f32_16x16x32_bf16 v[0:3], v[152:155], v[212:215], v[0:3]
	v_mfma_f32_16x16x32_bf16 v[0:3], v[156:159], v[218:221], v[0:3]
	s_barrier
	s_add_i32 vcc_hi, vcc_hi, 2
	s_add_u32 s88, s88, 0x100
	s_addc_u32 s89, s89, 0
	s_add_u32 s90, s90, 0x100
	s_addc_u32 s91, s91, 0
	s_cmp_gt_u32 vcc_hi, 29
	s_cbranch_scc0 .LBB0_827

.LBB0_1008:
	s_lshl_b64 s[2:3], s[8:9], 18
	s_add_u32 s7, s41, s2
	s_addc_u32 s9, s42, s3
	s_and_b64 s[2:3], s[10:11], exec
	s_cselect_b32 s15, s9, s19
	s_cselect_b32 s14, s7, s18
	s_add_u32 s7, s18, 0x100
	v_mov_b32_e32 v0, 0
	s_addc_u32 s9, s19, 0
	s_mov_b32 s93, -2
	s_add_u32 s18, s16, 0x100
	s_addc_u32 s19, s17, 0
	s_add_i32 s2, 0, 0x10000
	s_cmp_eq_u32 s93, 4
	s_cselect_b32 s53, s13, s19
	s_cselect_b32 s52, s12, s18
	s_cselect_b32 s23, s15, s9
	s_cselect_b32 s22, s14, s7
	s_add_i32 s58, 0, 0x14000
	v_add_u32_e32 v156, s2, v142
	v_add_u32_e32 v172, s58, v142
	ds_read_b128 v[144:147], v156
	ds_read_b128 v[148:151], v156 offset:1024
	ds_read_b128 v[152:155], v156 offset:2048
	ds_read_b128 v[156:159], v156 offset:3072
	ds_read_b128 v[160:163], v172
	ds_read_b128 v[164:167], v172 offset:1024
	ds_read_b128 v[168:171], v172 offset:2048
	ds_read_b128 v[172:175], v172 offset:3072
	v_lshl_add_u64 v[208:209], s[16:17], 0, v[136:137]
	s_add_i32 m0, s76, 0xc000
	ds_read_b128 v[176:179], v143
	ds_read_b128 v[180:183], v143 offset:1024
	ds_read_b128 v[184:187], v143 offset:2048
	ds_read_b128 v[188:191], v143 offset:3072
	ds_read_b128 v[192:195], v143 offset:4096
	ds_read_b128 v[196:199], v143 offset:5120
	ds_read_b128 v[200:203], v143 offset:6144
	ds_read_b128 v[204:207], v143 offset:7168
	global_load_lds_dwordx4 v[208:209], off
	v_lshl_add_u64 v[208:209], s[16:17], 0, v[138:139]
	s_add_i32 m0, s76, 0xe000
	s_nop 0
	global_load_lds_dwordx4 v[208:209], off
	s_waitcnt vmcnt(8) lgkmcnt(0)
	s_barrier
	v_mfma_f32_16x16x32_bf16 v[124:127], v[144:147], v[176:179], 0
	v_mfma_f32_16x16x32_bf16 v[124:127], v[148:151], v[180:183], v[124:127]
	v_mfma_f32_16x16x32_bf16 v[116:119], v[144:147], v[184:187], 0
	v_mfma_f32_16x16x32_bf16 v[116:119], v[148:151], v[188:191], v[116:119]
	v_mfma_f32_16x16x32_bf16 v[104:107], v[144:147], v[192:195], 0
	v_mfma_f32_16x16x32_bf16 v[104:107], v[148:151], v[196:199], v[104:107]
	v_mfma_f32_16x16x32_bf16 v[88:91], v[144:147], v[200:203], 0
	v_mfma_f32_16x16x32_bf16 v[88:91], v[148:151], v[204:207], v[88:91]
	v_mfma_f32_16x16x32_bf16 v[120:123], v[152:155], v[176:179], 0
	v_mfma_f32_16x16x32_bf16 v[120:123], v[156:159], v[180:183], v[120:123]
	v_mfma_f32_16x16x32_bf16 v[112:115], v[152:155], v[184:187], 0
	v_mfma_f32_16x16x32_bf16 v[112:115], v[156:159], v[188:191], v[112:115]
	v_mfma_f32_16x16x32_bf16 v[96:99], v[152:155], v[192:195], 0
	v_mfma_f32_16x16x32_bf16 v[96:99], v[156:159], v[196:199], v[96:99]
	v_mfma_f32_16x16x32_bf16 v[80:83], v[152:155], v[200:203], 0
	v_mfma_f32_16x16x32_bf16 v[80:83], v[156:159], v[204:207], v[80:83]
	v_mfma_f32_16x16x32_bf16 v[108:111], v[160:163], v[176:179], 0
	v_mfma_f32_16x16x32_bf16 v[108:111], v[164:167], v[180:183], v[108:111]
	v_mfma_f32_16x16x32_bf16 v[92:95], v[160:163], v[184:187], 0
	v_mfma_f32_16x16x32_bf16 v[92:95], v[164:167], v[188:191], v[92:95]
	v_mfma_f32_16x16x32_bf16 v[76:79], v[160:163], v[192:195], 0
	v_mfma_f32_16x16x32_bf16 v[76:79], v[164:167], v[196:199], v[76:79]
	v_mfma_f32_16x16x32_bf16 v[68:71], v[160:163], v[200:203], 0
	v_mfma_f32_16x16x32_bf16 v[68:71], v[164:167], v[204:207], v[68:71]
	v_mfma_f32_16x16x32_bf16 v[100:103], v[168:171], v[176:179], 0
	v_mfma_f32_16x16x32_bf16 v[100:103], v[172:175], v[180:183], v[100:103]
	v_mfma_f32_16x16x32_bf16 v[84:87], v[168:171], v[184:187], 0
	v_mfma_f32_16x16x32_bf16 v[84:87], v[172:175], v[188:191], v[84:87]
	v_mfma_f32_16x16x32_bf16 v[72:75], v[168:171], v[192:195], 0
	v_mfma_f32_16x16x32_bf16 v[72:75], v[172:175], v[196:199], v[72:75]
	v_mfma_f32_16x16x32_bf16 v[64:67], v[168:171], v[200:203], 0
	v_mfma_f32_16x16x32_bf16 v[64:67], v[172:175], v[204:207], v[64:67]
	s_barrier
	s_add_i32 s2, s2, s50
	v_lshl_add_u64 v[208:209], s[22:23], 0, v[216:217]
	s_mov_b32 m0, s2
	ds_read_b128 v[176:179], v143 offset:16384
	ds_read_b128 v[180:183], v143 offset:17408
	ds_read_b128 v[184:187], v143 offset:18432
	ds_read_b128 v[188:191], v143 offset:19456
	ds_read_b128 v[192:195], v143 offset:20480
	ds_read_b128 v[196:199], v143 offset:21504
	ds_read_b128 v[200:203], v143 offset:22528
	ds_read_b128 v[204:207], v143 offset:23552
	global_load_lds_dwordx4 v[208:209], off
	s_add_i32 m0, s2, 0x2000
	s_add_u32 s2, s22, 0x20000
	v_lshl_add_u64 v[210:211], s[22:23], 0, v[128:129]
	s_addc_u32 s3, s23, 0
	s_add_i32 s16, s58, s50
	global_load_lds_dwordx4 v[210:211], off
	v_lshl_add_u64 v[212:213], s[2:3], 0, v[216:217]
	s_mov_b32 m0, s16
	v_lshl_add_u64 v[214:215], s[52:53], 0, v[130:131]
	global_load_lds_dwordx4 v[212:213], off
	v_lshl_add_u64 v[212:213], s[2:3], 0, v[128:129]
	s_add_i32 m0, s16, 0x2000
	s_nop 0
	global_load_lds_dwordx4 v[212:213], off
	v_lshl_add_u64 v[212:213], s[52:53], 0, v[132:133]
	s_mov_b32 m0, s76
	s_nop 0
	global_load_lds_dwordx4 v[212:213], off
	s_mov_b32 m0, s72
	s_nop 0
	global_load_lds_dwordx4 v[214:215], off
	s_waitcnt vmcnt(8) lgkmcnt(0)
	s_barrier
	v_mfma_f32_16x16x32_bf16 v[60:63], v[144:147], v[176:179], 0
	v_mfma_f32_16x16x32_bf16 v[60:63], v[148:151], v[180:183], v[60:63]
	v_mfma_f32_16x16x32_bf16 v[52:55], v[144:147], v[184:187], 0
	v_mfma_f32_16x16x32_bf16 v[52:55], v[148:151], v[188:191], v[52:55]
	v_mfma_f32_16x16x32_bf16 v[36:39], v[144:147], v[192:195], 0
	v_mfma_f32_16x16x32_bf16 v[36:39], v[148:151], v[196:199], v[36:39]
	v_mfma_f32_16x16x32_bf16 v[20:23], v[144:147], v[200:203], 0
	v_mfma_f32_16x16x32_bf16 v[20:23], v[148:151], v[204:207], v[20:23]
	v_mfma_f32_16x16x32_bf16 v[56:59], v[152:155], v[176:179], 0
	v_mfma_f32_16x16x32_bf16 v[56:59], v[156:159], v[180:183], v[56:59]
	v_mfma_f32_16x16x32_bf16 v[48:51], v[152:155], v[184:187], 0
	v_mfma_f32_16x16x32_bf16 v[48:51], v[156:159], v[188:191], v[48:51]
	v_mfma_f32_16x16x32_bf16 v[32:35], v[152:155], v[192:195], 0
	v_mfma_f32_16x16x32_bf16 v[32:35], v[156:159], v[196:199], v[32:35]
	v_mfma_f32_16x16x32_bf16 v[16:19], v[152:155], v[200:203], 0
	v_mfma_f32_16x16x32_bf16 v[16:19], v[156:159], v[204:207], v[16:19]
	v_mfma_f32_16x16x32_bf16 v[44:47], v[160:163], v[176:179], 0
	v_mfma_f32_16x16x32_bf16 v[44:47], v[164:167], v[180:183], v[44:47]
	v_mfma_f32_16x16x32_bf16 v[28:31], v[160:163], v[184:187], 0
	v_mfma_f32_16x16x32_bf16 v[28:31], v[164:167], v[188:191], v[28:31]
	v_mfma_f32_16x16x32_bf16 v[12:15], v[160:163], v[192:195], 0
	v_mfma_f32_16x16x32_bf16 v[12:15], v[164:167], v[196:199], v[12:15]
	v_mfma_f32_16x16x32_bf16 v[4:7], v[160:163], v[200:203], 0
	v_mfma_f32_16x16x32_bf16 v[4:7], v[164:167], v[204:207], v[4:7]
	v_mfma_f32_16x16x32_bf16 v[40:43], v[168:171], v[176:179], 0
	v_mfma_f32_16x16x32_bf16 v[40:43], v[172:175], v[180:183], v[40:43]
	v_mfma_f32_16x16x32_bf16 v[24:27], v[168:171], v[184:187], 0
	v_mfma_f32_16x16x32_bf16 v[24:27], v[172:175], v[188:191], v[24:27]
	v_mfma_f32_16x16x32_bf16 v[8:11], v[168:171], v[192:195], 0
	v_mfma_f32_16x16x32_bf16 v[8:11], v[172:175], v[196:199], v[8:11]
	v_mfma_f32_16x16x32_bf16 v[0:3], v[168:171], v[200:203], 0
	v_mfma_f32_16x16x32_bf16 v[0:3], v[172:175], v[204:207], v[0:3]
	s_barrier
	s_add_i32 s16, 0, 0x18000
	s_add_i32 s17, 0, 0x1c000
	v_add_u32_e32 v156, s16, v142
	v_add_u32_e32 v172, s17, v142
	ds_read_b128 v[144:147], v156
	ds_read_b128 v[148:151], v156 offset:1024
	ds_read_b128 v[152:155], v156 offset:2048
	ds_read_b128 v[156:159], v156 offset:3072
	ds_read_b128 v[160:163], v172
	ds_read_b128 v[164:167], v172 offset:1024
	ds_read_b128 v[168:171], v172 offset:2048
	ds_read_b128 v[172:175], v172 offset:3072
	s_add_u32 s2, s52, 0x30000
	s_addc_u32 s3, s53, 0
	s_mov_b32 m0, s74
	v_lshl_add_u64 v[218:219], s[2:3], 0, v[132:133]
	ds_read_b128 v[176:179], v143 offset:32768
	ds_read_b128 v[180:183], v143 offset:33792
	ds_read_b128 v[184:187], v143 offset:34816
	ds_read_b128 v[188:191], v143 offset:35840
	ds_read_b128 v[192:195], v143 offset:36864
	ds_read_b128 v[196:199], v143 offset:37888
	ds_read_b128 v[200:203], v143 offset:38912
	ds_read_b128 v[204:207], v143 offset:39936
	global_load_lds_dwordx4 v[218:219], off
	v_lshl_add_u64 v[218:219], s[2:3], 0, v[130:131]
	s_mov_b32 m0, s85
	s_nop 0
	global_load_lds_dwordx4 v[218:219], off
	s_waitcnt vmcnt(8) lgkmcnt(0)
	s_barrier
	v_mfma_f32_16x16x32_bf16 v[124:127], v[144:147], v[176:179], v[124:127]
	v_mfma_f32_16x16x32_bf16 v[124:127], v[148:151], v[180:183], v[124:127]
	v_mfma_f32_16x16x32_bf16 v[116:119], v[144:147], v[184:187], v[116:119]
	v_mfma_f32_16x16x32_bf16 v[116:119], v[148:151], v[188:191], v[116:119]
	v_mfma_f32_16x16x32_bf16 v[104:107], v[144:147], v[192:195], v[104:107]
	v_mfma_f32_16x16x32_bf16 v[104:107], v[148:151], v[196:199], v[104:107]
	v_mfma_f32_16x16x32_bf16 v[88:91], v[144:147], v[200:203], v[88:91]
	v_mfma_f32_16x16x32_bf16 v[88:91], v[148:151], v[204:207], v[88:91]
	v_mfma_f32_16x16x32_bf16 v[120:123], v[152:155], v[176:179], v[120:123]
	v_mfma_f32_16x16x32_bf16 v[120:123], v[156:159], v[180:183], v[120:123]
	v_mfma_f32_16x16x32_bf16 v[112:115], v[152:155], v[184:187], v[112:115]
	v_mfma_f32_16x16x32_bf16 v[112:115], v[156:159], v[188:191], v[112:115]
	v_mfma_f32_16x16x32_bf16 v[96:99], v[152:155], v[192:195], v[96:99]
	v_mfma_f32_16x16x32_bf16 v[96:99], v[156:159], v[196:199], v[96:99]
	v_mfma_f32_16x16x32_bf16 v[80:83], v[152:155], v[200:203], v[80:83]
	v_mfma_f32_16x16x32_bf16 v[80:83], v[156:159], v[204:207], v[80:83]
	v_mfma_f32_16x16x32_bf16 v[108:111], v[160:163], v[176:179], v[108:111]
	v_mfma_f32_16x16x32_bf16 v[108:111], v[164:167], v[180:183], v[108:111]
	v_mfma_f32_16x16x32_bf16 v[92:95], v[160:163], v[184:187], v[92:95]
	v_mfma_f32_16x16x32_bf16 v[92:95], v[164:167], v[188:191], v[92:95]
	v_mfma_f32_16x16x32_bf16 v[76:79], v[160:163], v[192:195], v[76:79]
	v_mfma_f32_16x16x32_bf16 v[76:79], v[164:167], v[196:199], v[76:79]
	v_mfma_f32_16x16x32_bf16 v[68:71], v[160:163], v[200:203], v[68:71]
	v_mfma_f32_16x16x32_bf16 v[68:71], v[164:167], v[204:207], v[68:71]
	v_mfma_f32_16x16x32_bf16 v[100:103], v[168:171], v[176:179], v[100:103]
	v_mfma_f32_16x16x32_bf16 v[100:103], v[172:175], v[180:183], v[100:103]
	v_mfma_f32_16x16x32_bf16 v[84:87], v[168:171], v[184:187], v[84:87]
	v_mfma_f32_16x16x32_bf16 v[84:87], v[172:175], v[188:191], v[84:87]
	v_mfma_f32_16x16x32_bf16 v[72:75], v[168:171], v[192:195], v[72:75]
	v_mfma_f32_16x16x32_bf16 v[72:75], v[172:175], v[196:199], v[72:75]
	v_mfma_f32_16x16x32_bf16 v[64:67], v[168:171], v[200:203], v[64:67]
	v_mfma_f32_16x16x32_bf16 v[64:67], v[172:175], v[204:207], v[64:67]
	s_barrier
	s_add_i32 s2, s16, s50
	v_lshl_add_u64 v[208:209], v[208:209], 0, s[60:61]
	s_mov_b32 m0, s2
	ds_read_b128 v[176:179], v143 offset:49152
	ds_read_b128 v[180:183], v143 offset:50176
	ds_read_b128 v[184:187], v143 offset:51200
	ds_read_b128 v[188:191], v143 offset:52224
	ds_read_b128 v[192:195], v143 offset:53248
	ds_read_b128 v[196:199], v143 offset:54272
	ds_read_b128 v[200:203], v143 offset:55296
	ds_read_b128 v[204:207], v143 offset:56320
	global_load_lds_dwordx4 v[208:209], off
	s_add_i32 m0, s2, 0x2000
	s_add_u32 s2, s22, 0x20080
	v_lshl_add_u64 v[208:209], v[210:211], 0, s[60:61]
	s_addc_u32 s3, s23, 0
	s_add_i32 s16, s17, s50
	global_load_lds_dwordx4 v[208:209], off
	v_lshl_add_u64 v[208:209], s[2:3], 0, v[216:217]
	s_mov_b32 m0, s16
	s_nop 0
	global_load_lds_dwordx4 v[208:209], off
	v_lshl_add_u64 v[208:209], s[2:3], 0, v[128:129]
	s_add_i32 m0, s16, 0x2000
	s_nop 0
	global_load_lds_dwordx4 v[208:209], off
	v_lshl_add_u64 v[208:209], v[212:213], 0, s[60:61]
	s_mov_b32 m0, s89
	s_nop 0
	global_load_lds_dwordx4 v[208:209], off
	v_lshl_add_u64 v[208:209], v[214:215], 0, s[60:61]
	s_mov_b32 m0, s90
	s_nop 0
	global_load_lds_dwordx4 v[208:209], off
	s_waitcnt vmcnt(8) lgkmcnt(0)
	s_barrier
	v_mfma_f32_16x16x32_bf16 v[60:63], v[144:147], v[176:179], v[60:63]
	v_mfma_f32_16x16x32_bf16 v[60:63], v[148:151], v[180:183], v[60:63]
	v_mfma_f32_16x16x32_bf16 v[52:55], v[144:147], v[184:187], v[52:55]
	v_mfma_f32_16x16x32_bf16 v[52:55], v[148:151], v[188:191], v[52:55]
	v_mfma_f32_16x16x32_bf16 v[36:39], v[144:147], v[192:195], v[36:39]
	v_mfma_f32_16x16x32_bf16 v[36:39], v[148:151], v[196:199], v[36:39]
	v_mfma_f32_16x16x32_bf16 v[20:23], v[144:147], v[200:203], v[20:23]
	v_mfma_f32_16x16x32_bf16 v[20:23], v[148:151], v[204:207], v[20:23]
	v_mfma_f32_16x16x32_bf16 v[56:59], v[152:155], v[176:179], v[56:59]
	v_mfma_f32_16x16x32_bf16 v[56:59], v[156:159], v[180:183], v[56:59]
	v_mfma_f32_16x16x32_bf16 v[48:51], v[152:155], v[184:187], v[48:51]
	v_mfma_f32_16x16x32_bf16 v[48:51], v[156:159], v[188:191], v[48:51]
	v_mfma_f32_16x16x32_bf16 v[32:35], v[152:155], v[192:195], v[32:35]
	v_mfma_f32_16x16x32_bf16 v[32:35], v[156:159], v[196:199], v[32:35]
	v_mfma_f32_16x16x32_bf16 v[16:19], v[152:155], v[200:203], v[16:19]
	v_mfma_f32_16x16x32_bf16 v[16:19], v[156:159], v[204:207], v[16:19]
	v_mfma_f32_16x16x32_bf16 v[44:47], v[160:163], v[176:179], v[44:47]
	v_mfma_f32_16x16x32_bf16 v[44:47], v[164:167], v[180:183], v[44:47]
	v_mfma_f32_16x16x32_bf16 v[28:31], v[160:163], v[184:187], v[28:31]
	v_mfma_f32_16x16x32_bf16 v[28:31], v[164:167], v[188:191], v[28:31]
	v_mfma_f32_16x16x32_bf16 v[12:15], v[160:163], v[192:195], v[12:15]
	v_mfma_f32_16x16x32_bf16 v[12:15], v[164:167], v[196:199], v[12:15]
	v_mfma_f32_16x16x32_bf16 v[4:7], v[160:163], v[200:203], v[4:7]
	v_mfma_f32_16x16x32_bf16 v[4:7], v[164:167], v[204:207], v[4:7]
	v_mfma_f32_16x16x32_bf16 v[40:43], v[168:171], v[176:179], v[40:43]
	v_mfma_f32_16x16x32_bf16 v[40:43], v[172:175], v[180:183], v[40:43]
	v_mfma_f32_16x16x32_bf16 v[24:27], v[168:171], v[184:187], v[24:27]
	v_mfma_f32_16x16x32_bf16 v[24:27], v[172:175], v[188:191], v[24:27]
	v_mfma_f32_16x16x32_bf16 v[8:11], v[168:171], v[192:195], v[8:11]
	v_mfma_f32_16x16x32_bf16 v[8:11], v[172:175], v[196:199], v[8:11]
	v_mfma_f32_16x16x32_bf16 v[0:3], v[168:171], v[200:203], v[0:3]
	v_mfma_f32_16x16x32_bf16 v[0:3], v[172:175], v[204:207], v[0:3]
	s_barrier
	s_add_i32 s93, s93, 2
	s_add_u32 s7, s7, 0x100
	s_addc_u32 s9, s9, 0
	s_cmp_gt_u32 s93, 5
	s_mov_b64 s[16:17], s[18:19]
	s_cbranch_scc0 .LBB0_1009
	s_branch .Lzexit_3
.LBB0_1009:
	s_add_u32 s18, s16, 0x100
	s_addc_u32 s19, s17, 0
	s_add_i32 s2, 0, 0x10000
	s_cmp_eq_u32 s93, 4
	s_cselect_b32 s53, s13, s19
	s_cselect_b32 s52, s12, s18
	s_cselect_b32 s23, s15, s9
	s_cselect_b32 s22, s14, s7
	s_add_i32 s58, 0, 0x14000
	v_add_u32_e32 v156, s2, v142
	v_add_u32_e32 v172, s58, v142
	ds_read_b128 v[144:147], v156
	ds_read_b128 v[148:151], v156 offset:1024
	ds_read_b128 v[152:155], v156 offset:2048
	ds_read_b128 v[156:159], v156 offset:3072
	ds_read_b128 v[160:163], v172
	ds_read_b128 v[164:167], v172 offset:1024
	ds_read_b128 v[168:171], v172 offset:2048
	ds_read_b128 v[172:175], v172 offset:3072
	v_lshl_add_u64 v[208:209], s[16:17], 0, v[136:137]
	s_add_i32 m0, s76, 0xc000
	ds_read_b128 v[176:179], v143
	ds_read_b128 v[180:183], v143 offset:1024
	ds_read_b128 v[184:187], v143 offset:2048
	ds_read_b128 v[188:191], v143 offset:3072
	ds_read_b128 v[192:195], v143 offset:4096
	ds_read_b128 v[196:199], v143 offset:5120
	ds_read_b128 v[200:203], v143 offset:6144
	ds_read_b128 v[204:207], v143 offset:7168
	global_load_lds_dwordx4 v[208:209], off
	v_lshl_add_u64 v[208:209], s[16:17], 0, v[138:139]
	s_add_i32 m0, s76, 0xe000
	s_nop 0
	global_load_lds_dwordx4 v[208:209], off
	s_waitcnt vmcnt(8) lgkmcnt(0)
	s_barrier
	v_mfma_f32_16x16x32_bf16 v[124:127], v[144:147], v[176:179], v[124:127]
	v_mfma_f32_16x16x32_bf16 v[124:127], v[148:151], v[180:183], v[124:127]
	v_mfma_f32_16x16x32_bf16 v[116:119], v[144:147], v[184:187], v[116:119]
	v_mfma_f32_16x16x32_bf16 v[116:119], v[148:151], v[188:191], v[116:119]
	v_mfma_f32_16x16x32_bf16 v[104:107], v[144:147], v[192:195], v[104:107]
	v_mfma_f32_16x16x32_bf16 v[104:107], v[148:151], v[196:199], v[104:107]
	v_mfma_f32_16x16x32_bf16 v[88:91], v[144:147], v[200:203], v[88:91]
	v_mfma_f32_16x16x32_bf16 v[88:91], v[148:151], v[204:207], v[88:91]
	v_mfma_f32_16x16x32_bf16 v[120:123], v[152:155], v[176:179], v[120:123]
	v_mfma_f32_16x16x32_bf16 v[120:123], v[156:159], v[180:183], v[120:123]
	v_mfma_f32_16x16x32_bf16 v[112:115], v[152:155], v[184:187], v[112:115]
	v_mfma_f32_16x16x32_bf16 v[112:115], v[156:159], v[188:191], v[112:115]
	v_mfma_f32_16x16x32_bf16 v[96:99], v[152:155], v[192:195], v[96:99]
	v_mfma_f32_16x16x32_bf16 v[96:99], v[156:159], v[196:199], v[96:99]
	v_mfma_f32_16x16x32_bf16 v[80:83], v[152:155], v[200:203], v[80:83]
	v_mfma_f32_16x16x32_bf16 v[80:83], v[156:159], v[204:207], v[80:83]
	v_mfma_f32_16x16x32_bf16 v[108:111], v[160:163], v[176:179], v[108:111]
	v_mfma_f32_16x16x32_bf16 v[108:111], v[164:167], v[180:183], v[108:111]
	v_mfma_f32_16x16x32_bf16 v[92:95], v[160:163], v[184:187], v[92:95]
	v_mfma_f32_16x16x32_bf16 v[92:95], v[164:167], v[188:191], v[92:95]
	v_mfma_f32_16x16x32_bf16 v[76:79], v[160:163], v[192:195], v[76:79]
	v_mfma_f32_16x16x32_bf16 v[76:79], v[164:167], v[196:199], v[76:79]
	v_mfma_f32_16x16x32_bf16 v[68:71], v[160:163], v[200:203], v[68:71]
	v_mfma_f32_16x16x32_bf16 v[68:71], v[164:167], v[204:207], v[68:71]
	v_mfma_f32_16x16x32_bf16 v[100:103], v[168:171], v[176:179], v[100:103]
	v_mfma_f32_16x16x32_bf16 v[100:103], v[172:175], v[180:183], v[100:103]
	v_mfma_f32_16x16x32_bf16 v[84:87], v[168:171], v[184:187], v[84:87]
	v_mfma_f32_16x16x32_bf16 v[84:87], v[172:175], v[188:191], v[84:87]
	v_mfma_f32_16x16x32_bf16 v[72:75], v[168:171], v[192:195], v[72:75]
	v_mfma_f32_16x16x32_bf16 v[72:75], v[172:175], v[196:199], v[72:75]
	v_mfma_f32_16x16x32_bf16 v[64:67], v[168:171], v[200:203], v[64:67]
	v_mfma_f32_16x16x32_bf16 v[64:67], v[172:175], v[204:207], v[64:67]
	s_barrier
	s_add_i32 s2, s2, s50
	v_lshl_add_u64 v[208:209], s[22:23], 0, v[216:217]
	s_mov_b32 m0, s2
	ds_read_b128 v[176:179], v143 offset:16384
	ds_read_b128 v[180:183], v143 offset:17408
	ds_read_b128 v[184:187], v143 offset:18432
	ds_read_b128 v[188:191], v143 offset:19456
	ds_read_b128 v[192:195], v143 offset:20480
	ds_read_b128 v[196:199], v143 offset:21504
	ds_read_b128 v[200:203], v143 offset:22528
	ds_read_b128 v[204:207], v143 offset:23552
	global_load_lds_dwordx4 v[208:209], off
	s_add_i32 m0, s2, 0x2000
	s_add_u32 s2, s22, 0x20000
	v_lshl_add_u64 v[210:211], s[22:23], 0, v[128:129]
	s_addc_u32 s3, s23, 0
	s_add_i32 s16, s58, s50
	global_load_lds_dwordx4 v[210:211], off
	v_lshl_add_u64 v[212:213], s[2:3], 0, v[216:217]
	s_mov_b32 m0, s16
	v_lshl_add_u64 v[214:215], s[52:53], 0, v[130:131]
	global_load_lds_dwordx4 v[212:213], off
	v_lshl_add_u64 v[212:213], s[2:3], 0, v[128:129]
	s_add_i32 m0, s16, 0x2000
	s_nop 0
	global_load_lds_dwordx4 v[212:213], off
	v_lshl_add_u64 v[212:213], s[52:53], 0, v[132:133]
	s_mov_b32 m0, s76
	s_nop 0
	global_load_lds_dwordx4 v[212:213], off
	s_mov_b32 m0, s72
	s_nop 0
	global_load_lds_dwordx4 v[214:215], off
	s_waitcnt vmcnt(8) lgkmcnt(0)
	s_barrier
	v_mfma_f32_16x16x32_bf16 v[60:63], v[144:147], v[176:179], v[60:63]
	v_mfma_f32_16x16x32_bf16 v[60:63], v[148:151], v[180:183], v[60:63]
	v_mfma_f32_16x16x32_bf16 v[52:55], v[144:147], v[184:187], v[52:55]
	v_mfma_f32_16x16x32_bf16 v[52:55], v[148:151], v[188:191], v[52:55]
	v_mfma_f32_16x16x32_bf16 v[36:39], v[144:147], v[192:195], v[36:39]
	v_mfma_f32_16x16x32_bf16 v[36:39], v[148:151], v[196:199], v[36:39]
	v_mfma_f32_16x16x32_bf16 v[20:23], v[144:147], v[200:203], v[20:23]
	v_mfma_f32_16x16x32_bf16 v[20:23], v[148:151], v[204:207], v[20:23]
	v_mfma_f32_16x16x32_bf16 v[56:59], v[152:155], v[176:179], v[56:59]
	v_mfma_f32_16x16x32_bf16 v[56:59], v[156:159], v[180:183], v[56:59]
	v_mfma_f32_16x16x32_bf16 v[48:51], v[152:155], v[184:187], v[48:51]
	v_mfma_f32_16x16x32_bf16 v[48:51], v[156:159], v[188:191], v[48:51]
	v_mfma_f32_16x16x32_bf16 v[32:35], v[152:155], v[192:195], v[32:35]
	v_mfma_f32_16x16x32_bf16 v[32:35], v[156:159], v[196:199], v[32:35]
	v_mfma_f32_16x16x32_bf16 v[16:19], v[152:155], v[200:203], v[16:19]
	v_mfma_f32_16x16x32_bf16 v[16:19], v[156:159], v[204:207], v[16:19]
	v_mfma_f32_16x16x32_bf16 v[44:47], v[160:163], v[176:179], v[44:47]
	v_mfma_f32_16x16x32_bf16 v[44:47], v[164:167], v[180:183], v[44:47]
	v_mfma_f32_16x16x32_bf16 v[28:31], v[160:163], v[184:187], v[28:31]
	v_mfma_f32_16x16x32_bf16 v[28:31], v[164:167], v[188:191], v[28:31]
	v_mfma_f32_16x16x32_bf16 v[12:15], v[160:163], v[192:195], v[12:15]
	v_mfma_f32_16x16x32_bf16 v[12:15], v[164:167], v[196:199], v[12:15]
	v_mfma_f32_16x16x32_bf16 v[4:7], v[160:163], v[200:203], v[4:7]
	v_mfma_f32_16x16x32_bf16 v[4:7], v[164:167], v[204:207], v[4:7]
	v_mfma_f32_16x16x32_bf16 v[40:43], v[168:171], v[176:179], v[40:43]
	v_mfma_f32_16x16x32_bf16 v[40:43], v[172:175], v[180:183], v[40:43]
	v_mfma_f32_16x16x32_bf16 v[24:27], v[168:171], v[184:187], v[24:27]
	v_mfma_f32_16x16x32_bf16 v[24:27], v[172:175], v[188:191], v[24:27]
	v_mfma_f32_16x16x32_bf16 v[8:11], v[168:171], v[192:195], v[8:11]
	v_mfma_f32_16x16x32_bf16 v[8:11], v[172:175], v[196:199], v[8:11]
	v_mfma_f32_16x16x32_bf16 v[0:3], v[168:171], v[200:203], v[0:3]
	v_mfma_f32_16x16x32_bf16 v[0:3], v[172:175], v[204:207], v[0:3]
	s_barrier
	s_add_i32 s16, 0, 0x18000
	s_add_i32 s17, 0, 0x1c000
	v_add_u32_e32 v156, s16, v142
	v_add_u32_e32 v172, s17, v142
	ds_read_b128 v[144:147], v156
	ds_read_b128 v[148:151], v156 offset:1024
	ds_read_b128 v[152:155], v156 offset:2048
	ds_read_b128 v[156:159], v156 offset:3072
	ds_read_b128 v[160:163], v172
	ds_read_b128 v[164:167], v172 offset:1024
	ds_read_b128 v[168:171], v172 offset:2048
	ds_read_b128 v[172:175], v172 offset:3072
	s_add_u32 s2, s52, 0x30000
	s_addc_u32 s3, s53, 0
	s_mov_b32 m0, s74
	v_lshl_add_u64 v[218:219], s[2:3], 0, v[132:133]
	ds_read_b128 v[176:179], v143 offset:32768
	ds_read_b128 v[180:183], v143 offset:33792
	ds_read_b128 v[184:187], v143 offset:34816
	ds_read_b128 v[188:191], v143 offset:35840
	ds_read_b128 v[192:195], v143 offset:36864
	ds_read_b128 v[196:199], v143 offset:37888
	ds_read_b128 v[200:203], v143 offset:38912
	ds_read_b128 v[204:207], v143 offset:39936
	global_load_lds_dwordx4 v[218:219], off
	v_lshl_add_u64 v[218:219], s[2:3], 0, v[130:131]
	s_mov_b32 m0, s85
	s_nop 0
	global_load_lds_dwordx4 v[218:219], off
	s_waitcnt vmcnt(8) lgkmcnt(0)
	s_barrier
	v_mfma_f32_16x16x32_bf16 v[124:127], v[144:147], v[176:179], v[124:127]
	v_mfma_f32_16x16x32_bf16 v[124:127], v[148:151], v[180:183], v[124:127]
	v_mfma_f32_16x16x32_bf16 v[116:119], v[144:147], v[184:187], v[116:119]
	v_mfma_f32_16x16x32_bf16 v[116:119], v[148:151], v[188:191], v[116:119]
	v_mfma_f32_16x16x32_bf16 v[104:107], v[144:147], v[192:195], v[104:107]
	v_mfma_f32_16x16x32_bf16 v[104:107], v[148:151], v[196:199], v[104:107]
	v_mfma_f32_16x16x32_bf16 v[88:91], v[144:147], v[200:203], v[88:91]
	v_mfma_f32_16x16x32_bf16 v[88:91], v[148:151], v[204:207], v[88:91]
	v_mfma_f32_16x16x32_bf16 v[120:123], v[152:155], v[176:179], v[120:123]
	v_mfma_f32_16x16x32_bf16 v[120:123], v[156:159], v[180:183], v[120:123]
	v_mfma_f32_16x16x32_bf16 v[112:115], v[152:155], v[184:187], v[112:115]
	v_mfma_f32_16x16x32_bf16 v[112:115], v[156:159], v[188:191], v[112:115]
	v_mfma_f32_16x16x32_bf16 v[96:99], v[152:155], v[192:195], v[96:99]
	v_mfma_f32_16x16x32_bf16 v[96:99], v[156:159], v[196:199], v[96:99]
	v_mfma_f32_16x16x32_bf16 v[80:83], v[152:155], v[200:203], v[80:83]
	v_mfma_f32_16x16x32_bf16 v[80:83], v[156:159], v[204:207], v[80:83]
	v_mfma_f32_16x16x32_bf16 v[108:111], v[160:163], v[176:179], v[108:111]
	v_mfma_f32_16x16x32_bf16 v[108:111], v[164:167], v[180:183], v[108:111]
	v_mfma_f32_16x16x32_bf16 v[92:95], v[160:163], v[184:187], v[92:95]
	v_mfma_f32_16x16x32_bf16 v[92:95], v[164:167], v[188:191], v[92:95]
	v_mfma_f32_16x16x32_bf16 v[76:79], v[160:163], v[192:195], v[76:79]
	v_mfma_f32_16x16x32_bf16 v[76:79], v[164:167], v[196:199], v[76:79]
	v_mfma_f32_16x16x32_bf16 v[68:71], v[160:163], v[200:203], v[68:71]
	v_mfma_f32_16x16x32_bf16 v[68:71], v[164:167], v[204:207], v[68:71]
	v_mfma_f32_16x16x32_bf16 v[100:103], v[168:171], v[176:179], v[100:103]
	v_mfma_f32_16x16x32_bf16 v[100:103], v[172:175], v[180:183], v[100:103]
	v_mfma_f32_16x16x32_bf16 v[84:87], v[168:171], v[184:187], v[84:87]
	v_mfma_f32_16x16x32_bf16 v[84:87], v[172:175], v[188:191], v[84:87]
	v_mfma_f32_16x16x32_bf16 v[72:75], v[168:171], v[192:195], v[72:75]
	v_mfma_f32_16x16x32_bf16 v[72:75], v[172:175], v[196:199], v[72:75]
	v_mfma_f32_16x16x32_bf16 v[64:67], v[168:171], v[200:203], v[64:67]
	v_mfma_f32_16x16x32_bf16 v[64:67], v[172:175], v[204:207], v[64:67]
	s_barrier
	s_add_i32 s2, s16, s50
	v_lshl_add_u64 v[208:209], v[208:209], 0, s[60:61]
	s_mov_b32 m0, s2
	ds_read_b128 v[176:179], v143 offset:49152
	ds_read_b128 v[180:183], v143 offset:50176
	ds_read_b128 v[184:187], v143 offset:51200
	ds_read_b128 v[188:191], v143 offset:52224
	ds_read_b128 v[192:195], v143 offset:53248
	ds_read_b128 v[196:199], v143 offset:54272
	ds_read_b128 v[200:203], v143 offset:55296
	ds_read_b128 v[204:207], v143 offset:56320
	global_load_lds_dwordx4 v[208:209], off
	s_add_i32 m0, s2, 0x2000
	s_add_u32 s2, s22, 0x20080
	v_lshl_add_u64 v[208:209], v[210:211], 0, s[60:61]
	s_addc_u32 s3, s23, 0
	s_add_i32 s16, s17, s50
	global_load_lds_dwordx4 v[208:209], off
	v_lshl_add_u64 v[208:209], s[2:3], 0, v[216:217]
	s_mov_b32 m0, s16
	s_nop 0
	global_load_lds_dwordx4 v[208:209], off
	v_lshl_add_u64 v[208:209], s[2:3], 0, v[128:129]
	s_add_i32 m0, s16, 0x2000
	s_nop 0
	global_load_lds_dwordx4 v[208:209], off
	v_lshl_add_u64 v[208:209], v[212:213], 0, s[60:61]
	s_mov_b32 m0, s89
	s_nop 0
	global_load_lds_dwordx4 v[208:209], off
	v_lshl_add_u64 v[208:209], v[214:215], 0, s[60:61]
	s_mov_b32 m0, s90
	s_nop 0
	global_load_lds_dwordx4 v[208:209], off
	s_waitcnt vmcnt(8) lgkmcnt(0)
	s_barrier
	v_mfma_f32_16x16x32_bf16 v[60:63], v[144:147], v[176:179], v[60:63]
	v_mfma_f32_16x16x32_bf16 v[60:63], v[148:151], v[180:183], v[60:63]
	v_mfma_f32_16x16x32_bf16 v[52:55], v[144:147], v[184:187], v[52:55]
	v_mfma_f32_16x16x32_bf16 v[52:55], v[148:151], v[188:191], v[52:55]
	v_mfma_f32_16x16x32_bf16 v[36:39], v[144:147], v[192:195], v[36:39]
	v_mfma_f32_16x16x32_bf16 v[36:39], v[148:151], v[196:199], v[36:39]
	v_mfma_f32_16x16x32_bf16 v[20:23], v[144:147], v[200:203], v[20:23]
	v_mfma_f32_16x16x32_bf16 v[20:23], v[148:151], v[204:207], v[20:23]
	v_mfma_f32_16x16x32_bf16 v[56:59], v[152:155], v[176:179], v[56:59]
	v_mfma_f32_16x16x32_bf16 v[56:59], v[156:159], v[180:183], v[56:59]
	v_mfma_f32_16x16x32_bf16 v[48:51], v[152:155], v[184:187], v[48:51]
	v_mfma_f32_16x16x32_bf16 v[48:51], v[156:159], v[188:191], v[48:51]
	v_mfma_f32_16x16x32_bf16 v[32:35], v[152:155], v[192:195], v[32:35]
	v_mfma_f32_16x16x32_bf16 v[32:35], v[156:159], v[196:199], v[32:35]
	v_mfma_f32_16x16x32_bf16 v[16:19], v[152:155], v[200:203], v[16:19]
	v_mfma_f32_16x16x32_bf16 v[16:19], v[156:159], v[204:207], v[16:19]
	v_mfma_f32_16x16x32_bf16 v[44:47], v[160:163], v[176:179], v[44:47]
	v_mfma_f32_16x16x32_bf16 v[44:47], v[164:167], v[180:183], v[44:47]
	v_mfma_f32_16x16x32_bf16 v[28:31], v[160:163], v[184:187], v[28:31]
	v_mfma_f32_16x16x32_bf16 v[28:31], v[164:167], v[188:191], v[28:31]
	v_mfma_f32_16x16x32_bf16 v[12:15], v[160:163], v[192:195], v[12:15]
	v_mfma_f32_16x16x32_bf16 v[12:15], v[164:167], v[196:199], v[12:15]
	v_mfma_f32_16x16x32_bf16 v[4:7], v[160:163], v[200:203], v[4:7]
	v_mfma_f32_16x16x32_bf16 v[4:7], v[164:167], v[204:207], v[4:7]
	v_mfma_f32_16x16x32_bf16 v[40:43], v[168:171], v[176:179], v[40:43]
	v_mfma_f32_16x16x32_bf16 v[40:43], v[172:175], v[180:183], v[40:43]
	v_mfma_f32_16x16x32_bf16 v[24:27], v[168:171], v[184:187], v[24:27]
	v_mfma_f32_16x16x32_bf16 v[24:27], v[172:175], v[188:191], v[24:27]
	v_mfma_f32_16x16x32_bf16 v[8:11], v[168:171], v[192:195], v[8:11]
	v_mfma_f32_16x16x32_bf16 v[8:11], v[172:175], v[196:199], v[8:11]
	v_mfma_f32_16x16x32_bf16 v[0:3], v[168:171], v[200:203], v[0:3]
	v_mfma_f32_16x16x32_bf16 v[0:3], v[172:175], v[204:207], v[0:3]
	s_barrier
	s_add_i32 s93, s93, 2
	s_add_u32 s7, s7, 0x100
	s_addc_u32 s9, s9, 0
	s_cmp_gt_u32 s93, 5
	s_mov_b64 s[16:17], s[18:19]
	s_cbranch_scc0 .LBB0_1009

.LBB0_1325:
	s_add_u32 s74, s16, 0x100
	v_mov_b32_e32 v0, 0
	s_addc_u32 s94, s17, 0
	s_mov_b32 s95, -2
	s_add_u32 s16, s14, 0x100
	s_addc_u32 s17, s15, 0
	s_add_i32 s2, 0, 0x10000
	s_cmp_eq_u32 s95, 8
	s_cselect_b32 s23, s11, s17
	s_cselect_b32 s22, s10, s16
	v_add_u32_e32 v140, s2, v143
	s_cselect_b32 s19, s13, s94
	s_cselect_b32 s18, s12, s74
	s_add_i32 s58, 0, 0x14000
	ds_read_b128 v[146:149], v140
	ds_read_b128 v[150:153], v140 offset:1024
	ds_read_b128 v[154:157], v140 offset:2048
	ds_read_b128 v[158:161], v140 offset:3072
	v_add_u32_e32 v140, s58, v143
	ds_read_b128 v[162:165], v140
	ds_read_b128 v[166:169], v140 offset:1024
	ds_read_b128 v[170:173], v140 offset:2048
	ds_read_b128 v[174:177], v140 offset:3072
	v_lshl_add_u64 v[140:141], s[14:15], 0, v[136:137]
	s_add_i32 m0, s76, 0xc000
	ds_read_b128 v[178:181], v145
	ds_read_b128 v[182:185], v145 offset:1024
	ds_read_b128 v[186:189], v145 offset:2048
	ds_read_b128 v[190:193], v145 offset:3072
	ds_read_b128 v[194:197], v145 offset:4096
	ds_read_b128 v[198:201], v145 offset:5120
	ds_read_b128 v[202:205], v145 offset:6144
	ds_read_b128 v[206:209], v145 offset:7168
	global_load_lds_dwordx4 v[140:141], off
	v_lshl_add_u64 v[140:141], s[14:15], 0, v[138:139]
	s_add_i32 m0, s76, 0xe000
	s_nop 0
	global_load_lds_dwordx4 v[140:141], off
	s_waitcnt vmcnt(8) lgkmcnt(0)
	s_barrier
	v_mfma_f32_16x16x32_bf16 v[124:127], v[146:149], v[178:181], 0
	v_mfma_f32_16x16x32_bf16 v[124:127], v[150:153], v[182:185], v[124:127]
	v_mfma_f32_16x16x32_bf16 v[108:111], v[146:149], v[186:189], 0
	v_mfma_f32_16x16x32_bf16 v[108:111], v[150:153], v[190:193], v[108:111]
	v_mfma_f32_16x16x32_bf16 v[92:95], v[146:149], v[194:197], 0
	v_mfma_f32_16x16x32_bf16 v[92:95], v[150:153], v[198:201], v[92:95]
	v_mfma_f32_16x16x32_bf16 v[76:79], v[146:149], v[202:205], 0
	v_mfma_f32_16x16x32_bf16 v[76:79], v[150:153], v[206:209], v[76:79]
	v_mfma_f32_16x16x32_bf16 v[120:123], v[154:157], v[178:181], 0
	v_mfma_f32_16x16x32_bf16 v[120:123], v[158:161], v[182:185], v[120:123]
	v_mfma_f32_16x16x32_bf16 v[104:107], v[154:157], v[186:189], 0
	v_mfma_f32_16x16x32_bf16 v[104:107], v[158:161], v[190:193], v[104:107]
	v_mfma_f32_16x16x32_bf16 v[88:91], v[154:157], v[194:197], 0
	v_mfma_f32_16x16x32_bf16 v[88:91], v[158:161], v[198:201], v[88:91]
	v_mfma_f32_16x16x32_bf16 v[72:75], v[154:157], v[202:205], 0
	v_mfma_f32_16x16x32_bf16 v[72:75], v[158:161], v[206:209], v[72:75]
	v_mfma_f32_16x16x32_bf16 v[116:119], v[162:165], v[178:181], 0
	v_mfma_f32_16x16x32_bf16 v[116:119], v[166:169], v[182:185], v[116:119]
	v_mfma_f32_16x16x32_bf16 v[100:103], v[162:165], v[186:189], 0
	v_mfma_f32_16x16x32_bf16 v[100:103], v[166:169], v[190:193], v[100:103]
	v_mfma_f32_16x16x32_bf16 v[84:87], v[162:165], v[194:197], 0
	v_mfma_f32_16x16x32_bf16 v[84:87], v[166:169], v[198:201], v[84:87]
	v_mfma_f32_16x16x32_bf16 v[68:71], v[162:165], v[202:205], 0
	v_mfma_f32_16x16x32_bf16 v[68:71], v[166:169], v[206:209], v[68:71]
	v_mfma_f32_16x16x32_bf16 v[112:115], v[170:173], v[178:181], 0
	v_mfma_f32_16x16x32_bf16 v[112:115], v[174:177], v[182:185], v[112:115]
	v_mfma_f32_16x16x32_bf16 v[96:99], v[170:173], v[186:189], 0
	v_mfma_f32_16x16x32_bf16 v[96:99], v[174:177], v[190:193], v[96:99]
	v_mfma_f32_16x16x32_bf16 v[80:83], v[170:173], v[194:197], 0
	v_mfma_f32_16x16x32_bf16 v[80:83], v[174:177], v[198:201], v[80:83]
	v_mfma_f32_16x16x32_bf16 v[64:67], v[170:173], v[202:205], 0
	v_mfma_f32_16x16x32_bf16 v[64:67], v[174:177], v[206:209], v[64:67]
	s_barrier
	s_add_i32 s2, s2, s50
	v_lshl_add_u64 v[140:141], s[18:19], 0, v[132:133]
	s_mov_b32 m0, s2
	ds_read_b128 v[178:181], v145 offset:16384
	ds_read_b128 v[182:185], v145 offset:17408
	ds_read_b128 v[186:189], v145 offset:18432
	ds_read_b128 v[190:193], v145 offset:19456
	ds_read_b128 v[194:197], v145 offset:20480
	ds_read_b128 v[198:201], v145 offset:21504
	ds_read_b128 v[202:205], v145 offset:22528
	ds_read_b128 v[206:209], v145 offset:23552
	global_load_lds_dwordx4 v[140:141], off
	s_add_i32 m0, s2, 0x2000
	s_add_u32 s2, s18, 0x30000
	v_lshl_add_u64 v[210:211], s[18:19], 0, v[128:129]
	s_addc_u32 s3, s19, 0
	s_add_i32 s14, s58, s50
	global_load_lds_dwordx4 v[210:211], off
	v_lshl_add_u64 v[212:213], s[2:3], 0, v[132:133]
	s_mov_b32 m0, s14
	v_lshl_add_u64 v[214:215], s[22:23], 0, v[130:131]
	global_load_lds_dwordx4 v[212:213], off
	v_lshl_add_u64 v[212:213], s[2:3], 0, v[128:129]
	s_add_i32 m0, s14, 0x2000
	s_nop 0
	global_load_lds_dwordx4 v[212:213], off
	v_lshl_add_u64 v[212:213], s[22:23], 0, v[134:135]
	s_mov_b32 m0, s76
	s_nop 0
	global_load_lds_dwordx4 v[212:213], off
	s_mov_b32 m0, s85
	s_nop 0
	global_load_lds_dwordx4 v[214:215], off
	s_waitcnt vmcnt(8) lgkmcnt(0)
	s_barrier
	v_mfma_f32_16x16x32_bf16 v[60:63], v[146:149], v[178:181], 0
	v_mfma_f32_16x16x32_bf16 v[60:63], v[150:153], v[182:185], v[60:63]
	v_mfma_f32_16x16x32_bf16 v[44:47], v[146:149], v[186:189], 0
	v_mfma_f32_16x16x32_bf16 v[44:47], v[150:153], v[190:193], v[44:47]
	v_mfma_f32_16x16x32_bf16 v[28:31], v[146:149], v[194:197], 0
	v_mfma_f32_16x16x32_bf16 v[28:31], v[150:153], v[198:201], v[28:31]
	v_mfma_f32_16x16x32_bf16 v[12:15], v[146:149], v[202:205], 0
	v_mfma_f32_16x16x32_bf16 v[12:15], v[150:153], v[206:209], v[12:15]
	v_mfma_f32_16x16x32_bf16 v[56:59], v[154:157], v[178:181], 0
	v_mfma_f32_16x16x32_bf16 v[56:59], v[158:161], v[182:185], v[56:59]
	v_mfma_f32_16x16x32_bf16 v[40:43], v[154:157], v[186:189], 0
	v_mfma_f32_16x16x32_bf16 v[40:43], v[158:161], v[190:193], v[40:43]
	v_mfma_f32_16x16x32_bf16 v[24:27], v[154:157], v[194:197], 0
	v_mfma_f32_16x16x32_bf16 v[24:27], v[158:161], v[198:201], v[24:27]
	v_mfma_f32_16x16x32_bf16 v[8:11], v[154:157], v[202:205], 0
	v_mfma_f32_16x16x32_bf16 v[8:11], v[158:161], v[206:209], v[8:11]
	v_mfma_f32_16x16x32_bf16 v[52:55], v[162:165], v[178:181], 0
	v_mfma_f32_16x16x32_bf16 v[52:55], v[166:169], v[182:185], v[52:55]
	v_mfma_f32_16x16x32_bf16 v[36:39], v[162:165], v[186:189], 0
	v_mfma_f32_16x16x32_bf16 v[36:39], v[166:169], v[190:193], v[36:39]
	v_mfma_f32_16x16x32_bf16 v[20:23], v[162:165], v[194:197], 0
	v_mfma_f32_16x16x32_bf16 v[20:23], v[166:169], v[198:201], v[20:23]
	v_mfma_f32_16x16x32_bf16 v[4:7], v[162:165], v[202:205], 0
	v_mfma_f32_16x16x32_bf16 v[4:7], v[166:169], v[206:209], v[4:7]
	v_mfma_f32_16x16x32_bf16 v[48:51], v[170:173], v[178:181], 0
	v_mfma_f32_16x16x32_bf16 v[48:51], v[174:177], v[182:185], v[48:51]
	v_mfma_f32_16x16x32_bf16 v[32:35], v[170:173], v[186:189], 0
	v_mfma_f32_16x16x32_bf16 v[32:35], v[174:177], v[190:193], v[32:35]
	v_mfma_f32_16x16x32_bf16 v[16:19], v[170:173], v[194:197], 0
	v_mfma_f32_16x16x32_bf16 v[16:19], v[174:177], v[198:201], v[16:19]
	v_mfma_f32_16x16x32_bf16 v[0:3], v[170:173], v[202:205], 0
	v_mfma_f32_16x16x32_bf16 v[0:3], v[174:177], v[206:209], v[0:3]
	s_barrier
	s_add_i32 s14, 0, 0x18000
	s_add_i32 s15, 0, 0x1c000
	v_add_u32_e32 v158, s14, v143
	v_add_u32_e32 v174, s15, v143
	ds_read_b128 v[146:149], v158
	ds_read_b128 v[150:153], v158 offset:1024
	ds_read_b128 v[154:157], v158 offset:2048
	ds_read_b128 v[158:161], v158 offset:3072
	ds_read_b128 v[162:165], v174
	ds_read_b128 v[166:169], v174 offset:1024
	ds_read_b128 v[170:173], v174 offset:2048
	ds_read_b128 v[174:177], v174 offset:3072
	s_add_u32 s2, s22, 0x30000
	s_addc_u32 s3, s23, 0
	s_mov_b32 m0, s86
	v_lshl_add_u64 v[218:219], s[2:3], 0, v[134:135]
	ds_read_b128 v[178:181], v145 offset:32768
	ds_read_b128 v[182:185], v145 offset:33792
	ds_read_b128 v[186:189], v145 offset:34816
	ds_read_b128 v[190:193], v145 offset:35840
	ds_read_b128 v[194:197], v145 offset:36864
	ds_read_b128 v[198:201], v145 offset:37888
	ds_read_b128 v[202:205], v145 offset:38912
	ds_read_b128 v[206:209], v145 offset:39936
	global_load_lds_dwordx4 v[218:219], off
	v_lshl_add_u64 v[218:219], s[2:3], 0, v[130:131]
	s_mov_b32 m0, s87
	s_nop 0
	global_load_lds_dwordx4 v[218:219], off
	s_waitcnt vmcnt(8) lgkmcnt(0)
	s_barrier
	v_mfma_f32_16x16x32_bf16 v[124:127], v[146:149], v[178:181], v[124:127]
	v_mfma_f32_16x16x32_bf16 v[124:127], v[150:153], v[182:185], v[124:127]
	v_mfma_f32_16x16x32_bf16 v[108:111], v[146:149], v[186:189], v[108:111]
	v_mfma_f32_16x16x32_bf16 v[108:111], v[150:153], v[190:193], v[108:111]
	v_mfma_f32_16x16x32_bf16 v[92:95], v[146:149], v[194:197], v[92:95]
	v_mfma_f32_16x16x32_bf16 v[92:95], v[150:153], v[198:201], v[92:95]
	v_mfma_f32_16x16x32_bf16 v[76:79], v[146:149], v[202:205], v[76:79]
	v_mfma_f32_16x16x32_bf16 v[76:79], v[150:153], v[206:209], v[76:79]
	v_mfma_f32_16x16x32_bf16 v[120:123], v[154:157], v[178:181], v[120:123]
	v_mfma_f32_16x16x32_bf16 v[120:123], v[158:161], v[182:185], v[120:123]
	v_mfma_f32_16x16x32_bf16 v[104:107], v[154:157], v[186:189], v[104:107]
	v_mfma_f32_16x16x32_bf16 v[104:107], v[158:161], v[190:193], v[104:107]
	v_mfma_f32_16x16x32_bf16 v[88:91], v[154:157], v[194:197], v[88:91]
	v_mfma_f32_16x16x32_bf16 v[88:91], v[158:161], v[198:201], v[88:91]
	v_mfma_f32_16x16x32_bf16 v[72:75], v[154:157], v[202:205], v[72:75]
	v_mfma_f32_16x16x32_bf16 v[72:75], v[158:161], v[206:209], v[72:75]
	v_mfma_f32_16x16x32_bf16 v[116:119], v[162:165], v[178:181], v[116:119]
	v_mfma_f32_16x16x32_bf16 v[116:119], v[166:169], v[182:185], v[116:119]
	v_mfma_f32_16x16x32_bf16 v[100:103], v[162:165], v[186:189], v[100:103]
	v_mfma_f32_16x16x32_bf16 v[100:103], v[166:169], v[190:193], v[100:103]
	v_mfma_f32_16x16x32_bf16 v[84:87], v[162:165], v[194:197], v[84:87]
	v_mfma_f32_16x16x32_bf16 v[84:87], v[166:169], v[198:201], v[84:87]
	v_mfma_f32_16x16x32_bf16 v[68:71], v[162:165], v[202:205], v[68:71]
	v_mfma_f32_16x16x32_bf16 v[68:71], v[166:169], v[206:209], v[68:71]
	v_mfma_f32_16x16x32_bf16 v[112:115], v[170:173], v[178:181], v[112:115]
	v_mfma_f32_16x16x32_bf16 v[112:115], v[174:177], v[182:185], v[112:115]
	v_mfma_f32_16x16x32_bf16 v[96:99], v[170:173], v[186:189], v[96:99]
	v_mfma_f32_16x16x32_bf16 v[96:99], v[174:177], v[190:193], v[96:99]
	v_mfma_f32_16x16x32_bf16 v[80:83], v[170:173], v[194:197], v[80:83]
	v_mfma_f32_16x16x32_bf16 v[80:83], v[174:177], v[198:201], v[80:83]
	v_mfma_f32_16x16x32_bf16 v[64:67], v[170:173], v[202:205], v[64:67]
	v_mfma_f32_16x16x32_bf16 v[64:67], v[174:177], v[206:209], v[64:67]
	s_barrier
	s_add_i32 s2, s14, s50
	v_lshl_add_u64 v[140:141], v[140:141], 0, s[60:61]
	s_mov_b32 m0, s2
	ds_read_b128 v[178:181], v145 offset:49152
	ds_read_b128 v[182:185], v145 offset:50176
	ds_read_b128 v[186:189], v145 offset:51200
	ds_read_b128 v[190:193], v145 offset:52224
	ds_read_b128 v[194:197], v145 offset:53248
	ds_read_b128 v[198:201], v145 offset:54272
	ds_read_b128 v[202:205], v145 offset:55296
	ds_read_b128 v[206:209], v145 offset:56320
	global_load_lds_dwordx4 v[140:141], off
	s_add_i32 m0, s2, 0x2000
	s_add_u32 s2, s18, 0x30080
	v_lshl_add_u64 v[140:141], v[210:211], 0, s[60:61]
	s_addc_u32 s3, s19, 0
	s_add_i32 s14, s15, s50
	global_load_lds_dwordx4 v[140:141], off
	v_lshl_add_u64 v[140:141], s[2:3], 0, v[132:133]
	s_mov_b32 m0, s14
	s_nop 0
	global_load_lds_dwordx4 v[140:141], off
	v_lshl_add_u64 v[140:141], s[2:3], 0, v[128:129]
	s_add_i32 m0, s14, 0x2000
	s_nop 0
	global_load_lds_dwordx4 v[140:141], off
	v_lshl_add_u64 v[140:141], v[212:213], 0, s[60:61]
	s_mov_b32 m0, s88
	s_nop 0
	global_load_lds_dwordx4 v[140:141], off
	v_lshl_add_u64 v[140:141], v[214:215], 0, s[60:61]
	s_mov_b32 m0, s89
	s_nop 0
	global_load_lds_dwordx4 v[140:141], off
	s_waitcnt vmcnt(8) lgkmcnt(0)
	s_barrier
	v_mfma_f32_16x16x32_bf16 v[60:63], v[146:149], v[178:181], v[60:63]
	v_mfma_f32_16x16x32_bf16 v[60:63], v[150:153], v[182:185], v[60:63]
	v_mfma_f32_16x16x32_bf16 v[44:47], v[146:149], v[186:189], v[44:47]
	v_mfma_f32_16x16x32_bf16 v[44:47], v[150:153], v[190:193], v[44:47]
	v_mfma_f32_16x16x32_bf16 v[28:31], v[146:149], v[194:197], v[28:31]
	v_mfma_f32_16x16x32_bf16 v[28:31], v[150:153], v[198:201], v[28:31]
	v_mfma_f32_16x16x32_bf16 v[12:15], v[146:149], v[202:205], v[12:15]
	v_mfma_f32_16x16x32_bf16 v[12:15], v[150:153], v[206:209], v[12:15]
	v_mfma_f32_16x16x32_bf16 v[56:59], v[154:157], v[178:181], v[56:59]
	v_mfma_f32_16x16x32_bf16 v[56:59], v[158:161], v[182:185], v[56:59]
	v_mfma_f32_16x16x32_bf16 v[40:43], v[154:157], v[186:189], v[40:43]
	v_mfma_f32_16x16x32_bf16 v[40:43], v[158:161], v[190:193], v[40:43]
	v_mfma_f32_16x16x32_bf16 v[24:27], v[154:157], v[194:197], v[24:27]
	v_mfma_f32_16x16x32_bf16 v[24:27], v[158:161], v[198:201], v[24:27]
	v_mfma_f32_16x16x32_bf16 v[8:11], v[154:157], v[202:205], v[8:11]
	v_mfma_f32_16x16x32_bf16 v[8:11], v[158:161], v[206:209], v[8:11]
	v_mfma_f32_16x16x32_bf16 v[52:55], v[162:165], v[178:181], v[52:55]
	v_mfma_f32_16x16x32_bf16 v[52:55], v[166:169], v[182:185], v[52:55]
	v_mfma_f32_16x16x32_bf16 v[36:39], v[162:165], v[186:189], v[36:39]
	v_mfma_f32_16x16x32_bf16 v[36:39], v[166:169], v[190:193], v[36:39]
	v_mfma_f32_16x16x32_bf16 v[20:23], v[162:165], v[194:197], v[20:23]
	v_mfma_f32_16x16x32_bf16 v[20:23], v[166:169], v[198:201], v[20:23]
	v_mfma_f32_16x16x32_bf16 v[4:7], v[162:165], v[202:205], v[4:7]
	v_mfma_f32_16x16x32_bf16 v[4:7], v[166:169], v[206:209], v[4:7]
	v_mfma_f32_16x16x32_bf16 v[48:51], v[170:173], v[178:181], v[48:51]
	v_mfma_f32_16x16x32_bf16 v[48:51], v[174:177], v[182:185], v[48:51]
	v_mfma_f32_16x16x32_bf16 v[32:35], v[170:173], v[186:189], v[32:35]
	v_mfma_f32_16x16x32_bf16 v[32:35], v[174:177], v[190:193], v[32:35]
	v_mfma_f32_16x16x32_bf16 v[16:19], v[170:173], v[194:197], v[16:19]
	v_mfma_f32_16x16x32_bf16 v[16:19], v[174:177], v[198:201], v[16:19]
	v_mfma_f32_16x16x32_bf16 v[0:3], v[170:173], v[202:205], v[0:3]
	v_mfma_f32_16x16x32_bf16 v[0:3], v[174:177], v[206:209], v[0:3]
	s_barrier
	s_add_i32 s95, s95, 2
	s_add_u32 s74, s74, 0x100
	s_addc_u32 s94, s94, 0
	s_cmp_gt_u32 s95, 9
	s_mov_b64 s[14:15], s[16:17]
	s_cbranch_scc0 .LBB0_1326
	s_branch .Lzexit_4
.LBB0_1326:
	s_add_u32 s16, s14, 0x100
	s_addc_u32 s17, s15, 0
	s_add_i32 s2, 0, 0x10000
	s_cmp_eq_u32 s95, 8
	s_cselect_b32 s23, s11, s17
	s_cselect_b32 s22, s10, s16
	v_add_u32_e32 v140, s2, v143
	s_cselect_b32 s19, s13, s94
	s_cselect_b32 s18, s12, s74
	s_add_i32 s58, 0, 0x14000
	ds_read_b128 v[146:149], v140
	ds_read_b128 v[150:153], v140 offset:1024
	ds_read_b128 v[154:157], v140 offset:2048
	ds_read_b128 v[158:161], v140 offset:3072
	v_add_u32_e32 v140, s58, v143
	ds_read_b128 v[162:165], v140
	ds_read_b128 v[166:169], v140 offset:1024
	ds_read_b128 v[170:173], v140 offset:2048
	ds_read_b128 v[174:177], v140 offset:3072
	v_lshl_add_u64 v[140:141], s[14:15], 0, v[136:137]
	s_add_i32 m0, s76, 0xc000
	ds_read_b128 v[178:181], v145
	ds_read_b128 v[182:185], v145 offset:1024
	ds_read_b128 v[186:189], v145 offset:2048
	ds_read_b128 v[190:193], v145 offset:3072
	ds_read_b128 v[194:197], v145 offset:4096
	ds_read_b128 v[198:201], v145 offset:5120
	ds_read_b128 v[202:205], v145 offset:6144
	ds_read_b128 v[206:209], v145 offset:7168
	global_load_lds_dwordx4 v[140:141], off
	v_lshl_add_u64 v[140:141], s[14:15], 0, v[138:139]
	s_add_i32 m0, s76, 0xe000
	s_nop 0
	global_load_lds_dwordx4 v[140:141], off
	s_waitcnt vmcnt(8) lgkmcnt(0)
	s_barrier
	v_mfma_f32_16x16x32_bf16 v[124:127], v[146:149], v[178:181], v[124:127]
	v_mfma_f32_16x16x32_bf16 v[124:127], v[150:153], v[182:185], v[124:127]
	v_mfma_f32_16x16x32_bf16 v[108:111], v[146:149], v[186:189], v[108:111]
	v_mfma_f32_16x16x32_bf16 v[108:111], v[150:153], v[190:193], v[108:111]
	v_mfma_f32_16x16x32_bf16 v[92:95], v[146:149], v[194:197], v[92:95]
	v_mfma_f32_16x16x32_bf16 v[92:95], v[150:153], v[198:201], v[92:95]
	v_mfma_f32_16x16x32_bf16 v[76:79], v[146:149], v[202:205], v[76:79]
	v_mfma_f32_16x16x32_bf16 v[76:79], v[150:153], v[206:209], v[76:79]
	v_mfma_f32_16x16x32_bf16 v[120:123], v[154:157], v[178:181], v[120:123]
	v_mfma_f32_16x16x32_bf16 v[120:123], v[158:161], v[182:185], v[120:123]
	v_mfma_f32_16x16x32_bf16 v[104:107], v[154:157], v[186:189], v[104:107]
	v_mfma_f32_16x16x32_bf16 v[104:107], v[158:161], v[190:193], v[104:107]
	v_mfma_f32_16x16x32_bf16 v[88:91], v[154:157], v[194:197], v[88:91]
	v_mfma_f32_16x16x32_bf16 v[88:91], v[158:161], v[198:201], v[88:91]
	v_mfma_f32_16x16x32_bf16 v[72:75], v[154:157], v[202:205], v[72:75]
	v_mfma_f32_16x16x32_bf16 v[72:75], v[158:161], v[206:209], v[72:75]
	v_mfma_f32_16x16x32_bf16 v[116:119], v[162:165], v[178:181], v[116:119]
	v_mfma_f32_16x16x32_bf16 v[116:119], v[166:169], v[182:185], v[116:119]
	v_mfma_f32_16x16x32_bf16 v[100:103], v[162:165], v[186:189], v[100:103]
	v_mfma_f32_16x16x32_bf16 v[100:103], v[166:169], v[190:193], v[100:103]
	v_mfma_f32_16x16x32_bf16 v[84:87], v[162:165], v[194:197], v[84:87]
	v_mfma_f32_16x16x32_bf16 v[84:87], v[166:169], v[198:201], v[84:87]
	v_mfma_f32_16x16x32_bf16 v[68:71], v[162:165], v[202:205], v[68:71]
	v_mfma_f32_16x16x32_bf16 v[68:71], v[166:169], v[206:209], v[68:71]
	v_mfma_f32_16x16x32_bf16 v[112:115], v[170:173], v[178:181], v[112:115]
	v_mfma_f32_16x16x32_bf16 v[112:115], v[174:177], v[182:185], v[112:115]
	v_mfma_f32_16x16x32_bf16 v[96:99], v[170:173], v[186:189], v[96:99]
	v_mfma_f32_16x16x32_bf16 v[96:99], v[174:177], v[190:193], v[96:99]
	v_mfma_f32_16x16x32_bf16 v[80:83], v[170:173], v[194:197], v[80:83]
	v_mfma_f32_16x16x32_bf16 v[80:83], v[174:177], v[198:201], v[80:83]
	v_mfma_f32_16x16x32_bf16 v[64:67], v[170:173], v[202:205], v[64:67]
	v_mfma_f32_16x16x32_bf16 v[64:67], v[174:177], v[206:209], v[64:67]
	s_barrier
	s_add_i32 s2, s2, s50
	v_lshl_add_u64 v[140:141], s[18:19], 0, v[132:133]
	s_mov_b32 m0, s2
	ds_read_b128 v[178:181], v145 offset:16384
	ds_read_b128 v[182:185], v145 offset:17408
	ds_read_b128 v[186:189], v145 offset:18432
	ds_read_b128 v[190:193], v145 offset:19456
	ds_read_b128 v[194:197], v145 offset:20480
	ds_read_b128 v[198:201], v145 offset:21504
	ds_read_b128 v[202:205], v145 offset:22528
	ds_read_b128 v[206:209], v145 offset:23552
	global_load_lds_dwordx4 v[140:141], off
	s_add_i32 m0, s2, 0x2000
	s_add_u32 s2, s18, 0x30000
	v_lshl_add_u64 v[210:211], s[18:19], 0, v[128:129]
	s_addc_u32 s3, s19, 0
	s_add_i32 s14, s58, s50
	global_load_lds_dwordx4 v[210:211], off
	v_lshl_add_u64 v[212:213], s[2:3], 0, v[132:133]
	s_mov_b32 m0, s14
	v_lshl_add_u64 v[214:215], s[22:23], 0, v[130:131]
	global_load_lds_dwordx4 v[212:213], off
	v_lshl_add_u64 v[212:213], s[2:3], 0, v[128:129]
	s_add_i32 m0, s14, 0x2000
	s_nop 0
	global_load_lds_dwordx4 v[212:213], off
	v_lshl_add_u64 v[212:213], s[22:23], 0, v[134:135]
	s_mov_b32 m0, s76
	s_nop 0
	global_load_lds_dwordx4 v[212:213], off
	s_mov_b32 m0, s85
	s_nop 0
	global_load_lds_dwordx4 v[214:215], off
	s_waitcnt vmcnt(8) lgkmcnt(0)
	s_barrier
	v_mfma_f32_16x16x32_bf16 v[60:63], v[146:149], v[178:181], v[60:63]
	v_mfma_f32_16x16x32_bf16 v[60:63], v[150:153], v[182:185], v[60:63]
	v_mfma_f32_16x16x32_bf16 v[44:47], v[146:149], v[186:189], v[44:47]
	v_mfma_f32_16x16x32_bf16 v[44:47], v[150:153], v[190:193], v[44:47]
	v_mfma_f32_16x16x32_bf16 v[28:31], v[146:149], v[194:197], v[28:31]
	v_mfma_f32_16x16x32_bf16 v[28:31], v[150:153], v[198:201], v[28:31]
	v_mfma_f32_16x16x32_bf16 v[12:15], v[146:149], v[202:205], v[12:15]
	v_mfma_f32_16x16x32_bf16 v[12:15], v[150:153], v[206:209], v[12:15]
	v_mfma_f32_16x16x32_bf16 v[56:59], v[154:157], v[178:181], v[56:59]
	v_mfma_f32_16x16x32_bf16 v[56:59], v[158:161], v[182:185], v[56:59]
	v_mfma_f32_16x16x32_bf16 v[40:43], v[154:157], v[186:189], v[40:43]
	v_mfma_f32_16x16x32_bf16 v[40:43], v[158:161], v[190:193], v[40:43]
	v_mfma_f32_16x16x32_bf16 v[24:27], v[154:157], v[194:197], v[24:27]
	v_mfma_f32_16x16x32_bf16 v[24:27], v[158:161], v[198:201], v[24:27]
	v_mfma_f32_16x16x32_bf16 v[8:11], v[154:157], v[202:205], v[8:11]
	v_mfma_f32_16x16x32_bf16 v[8:11], v[158:161], v[206:209], v[8:11]
	v_mfma_f32_16x16x32_bf16 v[52:55], v[162:165], v[178:181], v[52:55]
	v_mfma_f32_16x16x32_bf16 v[52:55], v[166:169], v[182:185], v[52:55]
	v_mfma_f32_16x16x32_bf16 v[36:39], v[162:165], v[186:189], v[36:39]
	v_mfma_f32_16x16x32_bf16 v[36:39], v[166:169], v[190:193], v[36:39]
	v_mfma_f32_16x16x32_bf16 v[20:23], v[162:165], v[194:197], v[20:23]
	v_mfma_f32_16x16x32_bf16 v[20:23], v[166:169], v[198:201], v[20:23]
	v_mfma_f32_16x16x32_bf16 v[4:7], v[162:165], v[202:205], v[4:7]
	v_mfma_f32_16x16x32_bf16 v[4:7], v[166:169], v[206:209], v[4:7]
	v_mfma_f32_16x16x32_bf16 v[48:51], v[170:173], v[178:181], v[48:51]
	v_mfma_f32_16x16x32_bf16 v[48:51], v[174:177], v[182:185], v[48:51]
	v_mfma_f32_16x16x32_bf16 v[32:35], v[170:173], v[186:189], v[32:35]
	v_mfma_f32_16x16x32_bf16 v[32:35], v[174:177], v[190:193], v[32:35]
	v_mfma_f32_16x16x32_bf16 v[16:19], v[170:173], v[194:197], v[16:19]
	v_mfma_f32_16x16x32_bf16 v[16:19], v[174:177], v[198:201], v[16:19]
	v_mfma_f32_16x16x32_bf16 v[0:3], v[170:173], v[202:205], v[0:3]
	v_mfma_f32_16x16x32_bf16 v[0:3], v[174:177], v[206:209], v[0:3]
	s_barrier
	s_add_i32 s14, 0, 0x18000
	s_add_i32 s15, 0, 0x1c000
	v_add_u32_e32 v158, s14, v143
	v_add_u32_e32 v174, s15, v143
	ds_read_b128 v[146:149], v158
	ds_read_b128 v[150:153], v158 offset:1024
	ds_read_b128 v[154:157], v158 offset:2048
	ds_read_b128 v[158:161], v158 offset:3072
	ds_read_b128 v[162:165], v174
	ds_read_b128 v[166:169], v174 offset:1024
	ds_read_b128 v[170:173], v174 offset:2048
	ds_read_b128 v[174:177], v174 offset:3072
	s_add_u32 s2, s22, 0x30000
	s_addc_u32 s3, s23, 0
	s_mov_b32 m0, s86
	v_lshl_add_u64 v[218:219], s[2:3], 0, v[134:135]
	ds_read_b128 v[178:181], v145 offset:32768
	ds_read_b128 v[182:185], v145 offset:33792
	ds_read_b128 v[186:189], v145 offset:34816
	ds_read_b128 v[190:193], v145 offset:35840
	ds_read_b128 v[194:197], v145 offset:36864
	ds_read_b128 v[198:201], v145 offset:37888
	ds_read_b128 v[202:205], v145 offset:38912
	ds_read_b128 v[206:209], v145 offset:39936
	global_load_lds_dwordx4 v[218:219], off
	v_lshl_add_u64 v[218:219], s[2:3], 0, v[130:131]
	s_mov_b32 m0, s87
	s_nop 0
	global_load_lds_dwordx4 v[218:219], off
	s_waitcnt vmcnt(8) lgkmcnt(0)
	s_barrier
	v_mfma_f32_16x16x32_bf16 v[124:127], v[146:149], v[178:181], v[124:127]
	v_mfma_f32_16x16x32_bf16 v[124:127], v[150:153], v[182:185], v[124:127]
	v_mfma_f32_16x16x32_bf16 v[108:111], v[146:149], v[186:189], v[108:111]
	v_mfma_f32_16x16x32_bf16 v[108:111], v[150:153], v[190:193], v[108:111]
	v_mfma_f32_16x16x32_bf16 v[92:95], v[146:149], v[194:197], v[92:95]
	v_mfma_f32_16x16x32_bf16 v[92:95], v[150:153], v[198:201], v[92:95]
	v_mfma_f32_16x16x32_bf16 v[76:79], v[146:149], v[202:205], v[76:79]
	v_mfma_f32_16x16x32_bf16 v[76:79], v[150:153], v[206:209], v[76:79]
	v_mfma_f32_16x16x32_bf16 v[120:123], v[154:157], v[178:181], v[120:123]
	v_mfma_f32_16x16x32_bf16 v[120:123], v[158:161], v[182:185], v[120:123]
	v_mfma_f32_16x16x32_bf16 v[104:107], v[154:157], v[186:189], v[104:107]
	v_mfma_f32_16x16x32_bf16 v[104:107], v[158:161], v[190:193], v[104:107]
	v_mfma_f32_16x16x32_bf16 v[88:91], v[154:157], v[194:197], v[88:91]
	v_mfma_f32_16x16x32_bf16 v[88:91], v[158:161], v[198:201], v[88:91]
	v_mfma_f32_16x16x32_bf16 v[72:75], v[154:157], v[202:205], v[72:75]
	v_mfma_f32_16x16x32_bf16 v[72:75], v[158:161], v[206:209], v[72:75]
	v_mfma_f32_16x16x32_bf16 v[116:119], v[162:165], v[178:181], v[116:119]
	v_mfma_f32_16x16x32_bf16 v[116:119], v[166:169], v[182:185], v[116:119]
	v_mfma_f32_16x16x32_bf16 v[100:103], v[162:165], v[186:189], v[100:103]
	v_mfma_f32_16x16x32_bf16 v[100:103], v[166:169], v[190:193], v[100:103]
	v_mfma_f32_16x16x32_bf16 v[84:87], v[162:165], v[194:197], v[84:87]
	v_mfma_f32_16x16x32_bf16 v[84:87], v[166:169], v[198:201], v[84:87]
	v_mfma_f32_16x16x32_bf16 v[68:71], v[162:165], v[202:205], v[68:71]
	v_mfma_f32_16x16x32_bf16 v[68:71], v[166:169], v[206:209], v[68:71]
	v_mfma_f32_16x16x32_bf16 v[112:115], v[170:173], v[178:181], v[112:115]
	v_mfma_f32_16x16x32_bf16 v[112:115], v[174:177], v[182:185], v[112:115]
	v_mfma_f32_16x16x32_bf16 v[96:99], v[170:173], v[186:189], v[96:99]
	v_mfma_f32_16x16x32_bf16 v[96:99], v[174:177], v[190:193], v[96:99]
	v_mfma_f32_16x16x32_bf16 v[80:83], v[170:173], v[194:197], v[80:83]
	v_mfma_f32_16x16x32_bf16 v[80:83], v[174:177], v[198:201], v[80:83]
	v_mfma_f32_16x16x32_bf16 v[64:67], v[170:173], v[202:205], v[64:67]
	v_mfma_f32_16x16x32_bf16 v[64:67], v[174:177], v[206:209], v[64:67]
	s_barrier
	s_add_i32 s2, s14, s50
	v_lshl_add_u64 v[140:141], v[140:141], 0, s[60:61]
	s_mov_b32 m0, s2
	ds_read_b128 v[178:181], v145 offset:49152
	ds_read_b128 v[182:185], v145 offset:50176
	ds_read_b128 v[186:189], v145 offset:51200
	ds_read_b128 v[190:193], v145 offset:52224
	ds_read_b128 v[194:197], v145 offset:53248
	ds_read_b128 v[198:201], v145 offset:54272
	ds_read_b128 v[202:205], v145 offset:55296
	ds_read_b128 v[206:209], v145 offset:56320
	global_load_lds_dwordx4 v[140:141], off
	s_add_i32 m0, s2, 0x2000
	s_add_u32 s2, s18, 0x30080
	v_lshl_add_u64 v[140:141], v[210:211], 0, s[60:61]
	s_addc_u32 s3, s19, 0
	s_add_i32 s14, s15, s50
	global_load_lds_dwordx4 v[140:141], off
	v_lshl_add_u64 v[140:141], s[2:3], 0, v[132:133]
	s_mov_b32 m0, s14
	s_nop 0
	global_load_lds_dwordx4 v[140:141], off
	v_lshl_add_u64 v[140:141], s[2:3], 0, v[128:129]
	s_add_i32 m0, s14, 0x2000
	s_nop 0
	global_load_lds_dwordx4 v[140:141], off
	v_lshl_add_u64 v[140:141], v[212:213], 0, s[60:61]
	s_mov_b32 m0, s88
	s_nop 0
	global_load_lds_dwordx4 v[140:141], off
	v_lshl_add_u64 v[140:141], v[214:215], 0, s[60:61]
	s_mov_b32 m0, s89
	s_nop 0
	global_load_lds_dwordx4 v[140:141], off
	s_waitcnt vmcnt(8) lgkmcnt(0)
	s_barrier
	v_mfma_f32_16x16x32_bf16 v[60:63], v[146:149], v[178:181], v[60:63]
	v_mfma_f32_16x16x32_bf16 v[60:63], v[150:153], v[182:185], v[60:63]
	v_mfma_f32_16x16x32_bf16 v[44:47], v[146:149], v[186:189], v[44:47]
	v_mfma_f32_16x16x32_bf16 v[44:47], v[150:153], v[190:193], v[44:47]
	v_mfma_f32_16x16x32_bf16 v[28:31], v[146:149], v[194:197], v[28:31]
	v_mfma_f32_16x16x32_bf16 v[28:31], v[150:153], v[198:201], v[28:31]
	v_mfma_f32_16x16x32_bf16 v[12:15], v[146:149], v[202:205], v[12:15]
	v_mfma_f32_16x16x32_bf16 v[12:15], v[150:153], v[206:209], v[12:15]
	v_mfma_f32_16x16x32_bf16 v[56:59], v[154:157], v[178:181], v[56:59]
	v_mfma_f32_16x16x32_bf16 v[56:59], v[158:161], v[182:185], v[56:59]
	v_mfma_f32_16x16x32_bf16 v[40:43], v[154:157], v[186:189], v[40:43]
	v_mfma_f32_16x16x32_bf16 v[40:43], v[158:161], v[190:193], v[40:43]
	v_mfma_f32_16x16x32_bf16 v[24:27], v[154:157], v[194:197], v[24:27]
	v_mfma_f32_16x16x32_bf16 v[24:27], v[158:161], v[198:201], v[24:27]
	v_mfma_f32_16x16x32_bf16 v[8:11], v[154:157], v[202:205], v[8:11]
	v_mfma_f32_16x16x32_bf16 v[8:11], v[158:161], v[206:209], v[8:11]
	v_mfma_f32_16x16x32_bf16 v[52:55], v[162:165], v[178:181], v[52:55]
	v_mfma_f32_16x16x32_bf16 v[52:55], v[166:169], v[182:185], v[52:55]
	v_mfma_f32_16x16x32_bf16 v[36:39], v[162:165], v[186:189], v[36:39]
	v_mfma_f32_16x16x32_bf16 v[36:39], v[166:169], v[190:193], v[36:39]
	v_mfma_f32_16x16x32_bf16 v[20:23], v[162:165], v[194:197], v[20:23]
	v_mfma_f32_16x16x32_bf16 v[20:23], v[166:169], v[198:201], v[20:23]
	v_mfma_f32_16x16x32_bf16 v[4:7], v[162:165], v[202:205], v[4:7]
	v_mfma_f32_16x16x32_bf16 v[4:7], v[166:169], v[206:209], v[4:7]
	v_mfma_f32_16x16x32_bf16 v[48:51], v[170:173], v[178:181], v[48:51]
	v_mfma_f32_16x16x32_bf16 v[48:51], v[174:177], v[182:185], v[48:51]
	v_mfma_f32_16x16x32_bf16 v[32:35], v[170:173], v[186:189], v[32:35]
	v_mfma_f32_16x16x32_bf16 v[32:35], v[174:177], v[190:193], v[32:35]
	v_mfma_f32_16x16x32_bf16 v[16:19], v[170:173], v[194:197], v[16:19]
	v_mfma_f32_16x16x32_bf16 v[16:19], v[174:177], v[198:201], v[16:19]
	v_mfma_f32_16x16x32_bf16 v[0:3], v[170:173], v[202:205], v[0:3]
	v_mfma_f32_16x16x32_bf16 v[0:3], v[174:177], v[206:209], v[0:3]
	s_barrier
	s_add_i32 s95, s95, 2
	s_add_u32 s74, s74, 0x100
	s_addc_u32 s94, s94, 0
	s_cmp_gt_u32 s95, 9
	s_mov_b64 s[14:15], s[16:17]
	s_cbranch_scc0 .LBB0_1326

.LBB0_1516:
	s_add_u32 s52, s88, 0xfffe0080
	s_addc_u32 s53, s89, -1
	s_add_i32 s58, 0, 0x10000
	s_cmp_eq_u32 vcc_hi, 4
	s_cselect_b32 s55, s17, s53
	s_cselect_b32 s54, s42, s52
	s_cselect_b32 s53, s15, vcc_lo
	s_cselect_b32 s52, s72, s74
	s_add_i32 s81, 0, 0x14000
	v_add_u32_e32 v36, s58, v161
	v_add_u32_e32 v158, s81, v161
	ds_read_b128 v[16:19], v36
	ds_read_b128 v[20:23], v36 offset:1024
	ds_read_b128 v[32:35], v36 offset:2048
	ds_read_b128 v[36:39], v36 offset:3072
	ds_read_b128 v[154:157], v158
	ds_read_b128 v[164:167], v158 offset:1024
	ds_read_b128 v[168:171], v158 offset:2048
	ds_read_b128 v[174:177], v158 offset:3072
	v_lshl_add_u64 v[158:159], s[88:89], 0, v[150:151]
	s_add_i32 m0, s76, 0xc000
	ds_read_b128 v[178:181], v163
	ds_read_b128 v[182:185], v163 offset:1024
	ds_read_b128 v[186:189], v163 offset:2048
	ds_read_b128 v[190:193], v163 offset:3072
	ds_read_b128 v[194:197], v163 offset:4096
	ds_read_b128 v[198:201], v163 offset:5120
	ds_read_b128 v[202:205], v163 offset:6144
	ds_read_b128 v[206:209], v163 offset:7168
	global_load_lds_dwordx4 v[158:159], off
	v_lshl_add_u64 v[158:159], s[88:89], 0, v[152:153]
	s_add_i32 m0, s76, 0xe000
	s_nop 0
	global_load_lds_dwordx4 v[158:159], off
	s_waitcnt vmcnt(8) lgkmcnt(0)
	s_barrier
	v_mfma_f32_16x16x32_bf16 v[140:143], v[16:19], v[178:181], v[140:143]
	v_mfma_f32_16x16x32_bf16 v[140:143], v[20:23], v[182:185], v[140:143]
	v_mfma_f32_16x16x32_bf16 v[124:127], v[16:19], v[186:189], v[124:127]
	v_mfma_f32_16x16x32_bf16 v[124:127], v[20:23], v[190:193], v[124:127]
	v_mfma_f32_16x16x32_bf16 v[108:111], v[16:19], v[194:197], v[108:111]
	v_mfma_f32_16x16x32_bf16 v[108:111], v[20:23], v[198:201], v[108:111]
	v_mfma_f32_16x16x32_bf16 v[92:95], v[16:19], v[202:205], v[92:95]
	v_mfma_f32_16x16x32_bf16 v[92:95], v[20:23], v[206:209], v[92:95]
	v_mfma_f32_16x16x32_bf16 v[136:139], v[32:35], v[178:181], v[136:139]
	v_mfma_f32_16x16x32_bf16 v[136:139], v[36:39], v[182:185], v[136:139]
	v_mfma_f32_16x16x32_bf16 v[120:123], v[32:35], v[186:189], v[120:123]
	v_mfma_f32_16x16x32_bf16 v[120:123], v[36:39], v[190:193], v[120:123]
	v_mfma_f32_16x16x32_bf16 v[104:107], v[32:35], v[194:197], v[104:107]
	v_mfma_f32_16x16x32_bf16 v[104:107], v[36:39], v[198:201], v[104:107]
	v_mfma_f32_16x16x32_bf16 v[88:91], v[32:35], v[202:205], v[88:91]
	v_mfma_f32_16x16x32_bf16 v[88:91], v[36:39], v[206:209], v[88:91]
	v_mfma_f32_16x16x32_bf16 v[132:135], v[154:157], v[178:181], v[132:135]
	v_mfma_f32_16x16x32_bf16 v[132:135], v[164:167], v[182:185], v[132:135]
	v_mfma_f32_16x16x32_bf16 v[116:119], v[154:157], v[186:189], v[116:119]
	v_mfma_f32_16x16x32_bf16 v[116:119], v[164:167], v[190:193], v[116:119]
	v_mfma_f32_16x16x32_bf16 v[100:103], v[154:157], v[194:197], v[100:103]
	v_mfma_f32_16x16x32_bf16 v[100:103], v[164:167], v[198:201], v[100:103]
	v_mfma_f32_16x16x32_bf16 v[84:87], v[154:157], v[202:205], v[84:87]
	v_mfma_f32_16x16x32_bf16 v[84:87], v[164:167], v[206:209], v[84:87]
	v_mfma_f32_16x16x32_bf16 v[128:131], v[168:171], v[178:181], v[128:131]
	v_mfma_f32_16x16x32_bf16 v[128:131], v[174:177], v[182:185], v[128:131]
	v_mfma_f32_16x16x32_bf16 v[112:115], v[168:171], v[186:189], v[112:115]
	v_mfma_f32_16x16x32_bf16 v[112:115], v[174:177], v[190:193], v[112:115]
	v_mfma_f32_16x16x32_bf16 v[96:99], v[168:171], v[194:197], v[96:99]
	v_mfma_f32_16x16x32_bf16 v[96:99], v[174:177], v[198:201], v[96:99]
	v_mfma_f32_16x16x32_bf16 v[80:83], v[168:171], v[202:205], v[80:83]
	v_mfma_f32_16x16x32_bf16 v[80:83], v[174:177], v[206:209], v[80:83]
	s_barrier
	s_add_i32 s58, s58, s50
	v_lshl_add_u64 v[158:159], s[52:53], 0, v[216:217]
	s_mov_b32 m0, s58
	ds_read_b128 v[178:181], v163 offset:16384
	ds_read_b128 v[182:185], v163 offset:17408
	ds_read_b128 v[186:189], v163 offset:18432
	ds_read_b128 v[190:193], v163 offset:19456
	ds_read_b128 v[194:197], v163 offset:20480
	ds_read_b128 v[198:201], v163 offset:21504
	ds_read_b128 v[202:205], v163 offset:22528
	ds_read_b128 v[206:209], v163 offset:23552
	global_load_lds_dwordx4 v[158:159], off
	s_add_i32 m0, s58, 0x2000
	s_add_u32 s58, s52, 0x20000
	v_lshl_add_u64 v[210:211], s[52:53], 0, v[148:149]
	s_addc_u32 s59, s53, 0
	s_add_i32 s81, s81, s50
	global_load_lds_dwordx4 v[210:211], off
	v_lshl_add_u64 v[212:213], s[58:59], 0, v[216:217]
	s_mov_b32 m0, s81
	v_lshl_add_u64 v[214:215], s[54:55], 0, v[146:147]
	global_load_lds_dwordx4 v[212:213], off
	v_lshl_add_u64 v[212:213], s[58:59], 0, v[148:149]
	s_add_i32 m0, s81, 0x2000
	s_nop 0
	global_load_lds_dwordx4 v[212:213], off
	v_lshl_add_u64 v[212:213], s[54:55], 0, v[144:145]
	s_mov_b32 m0, s76
	s_nop 0
	global_load_lds_dwordx4 v[212:213], off
	s_mov_b32 m0, s87
	s_nop 0
	global_load_lds_dwordx4 v[214:215], off
	s_waitcnt vmcnt(8) lgkmcnt(0)
	s_barrier
	v_mfma_f32_16x16x32_bf16 v[76:79], v[16:19], v[178:181], v[76:79]
	v_mfma_f32_16x16x32_bf16 v[76:79], v[20:23], v[182:185], v[76:79]
	v_mfma_f32_16x16x32_bf16 v[60:63], v[16:19], v[186:189], v[60:63]
	v_mfma_f32_16x16x32_bf16 v[60:63], v[20:23], v[190:193], v[60:63]
	v_mfma_f32_16x16x32_bf16 v[44:47], v[16:19], v[194:197], v[44:47]
	v_mfma_f32_16x16x32_bf16 v[44:47], v[20:23], v[198:201], v[44:47]
	v_mfma_f32_16x16x32_bf16 v[12:15], v[16:19], v[202:205], v[12:15]
	v_mfma_f32_16x16x32_bf16 v[12:15], v[20:23], v[206:209], v[12:15]
	v_mfma_f32_16x16x32_bf16 v[72:75], v[32:35], v[178:181], v[72:75]
	v_mfma_f32_16x16x32_bf16 v[72:75], v[36:39], v[182:185], v[72:75]
	v_mfma_f32_16x16x32_bf16 v[56:59], v[32:35], v[186:189], v[56:59]
	v_mfma_f32_16x16x32_bf16 v[56:59], v[36:39], v[190:193], v[56:59]
	v_mfma_f32_16x16x32_bf16 v[40:43], v[32:35], v[194:197], v[40:43]
	v_mfma_f32_16x16x32_bf16 v[40:43], v[36:39], v[198:201], v[40:43]
	v_mfma_f32_16x16x32_bf16 v[8:11], v[32:35], v[202:205], v[8:11]
	v_mfma_f32_16x16x32_bf16 v[8:11], v[36:39], v[206:209], v[8:11]
	v_mfma_f32_16x16x32_bf16 v[28:31], v[154:157], v[194:197], v[28:31]
	v_mfma_f32_16x16x32_bf16 v[24:27], v[168:171], v[194:197], v[24:27]
	v_mfma_f32_16x16x32_bf16 v[0:3], v[154:157], v[202:205], v[0:3]
	v_mfma_f32_16x16x32_bf16 v[4:7], v[168:171], v[202:205], v[4:7]
	v_mfma_f32_16x16x32_bf16 v[16:19], v[154:157], v[178:181], v[68:71]
	v_mfma_f32_16x16x32_bf16 v[20:23], v[168:171], v[178:181], v[64:67]
	v_mfma_f32_16x16x32_bf16 v[32:35], v[154:157], v[186:189], v[52:55]
	v_mfma_f32_16x16x32_bf16 v[36:39], v[168:171], v[186:189], v[48:51]
	v_mfma_f32_16x16x32_bf16 v[28:31], v[164:167], v[198:201], v[28:31]
	v_mfma_f32_16x16x32_bf16 v[24:27], v[174:177], v[198:201], v[24:27]
	v_mfma_f32_16x16x32_bf16 v[0:3], v[164:167], v[206:209], v[0:3]
	v_mfma_f32_16x16x32_bf16 v[4:7], v[174:177], v[206:209], v[4:7]
	v_mfma_f32_16x16x32_bf16 v[16:19], v[164:167], v[182:185], v[16:19]
	v_mfma_f32_16x16x32_bf16 v[20:23], v[174:177], v[182:185], v[20:23]
	v_mfma_f32_16x16x32_bf16 v[32:35], v[164:167], v[190:193], v[32:35]
	v_mfma_f32_16x16x32_bf16 v[36:39], v[174:177], v[190:193], v[36:39]
	s_barrier
	s_add_i32 s58, 0, 0x18000
	s_add_i32 s59, 0, 0x1c000
	v_add_u32_e32 v68, s58, v161
	v_add_u32_e32 v173, s59, v161
	ds_read_b128 v[48:51], v68
	ds_read_b128 v[52:55], v68 offset:1024
	ds_read_b128 v[64:67], v68 offset:2048
	ds_read_b128 v[68:71], v68 offset:3072
	ds_read_b128 v[154:157], v173
	ds_read_b128 v[164:167], v173 offset:1024
	ds_read_b128 v[168:171], v173 offset:2048
	ds_read_b128 v[174:177], v173 offset:3072
	s_add_u32 s54, s54, 0x20000
	s_addc_u32 s55, s55, 0
	s_mov_b32 m0, s25
	v_lshl_add_u64 v[218:219], s[54:55], 0, v[144:145]
	ds_read_b128 v[178:181], v163 offset:32768
	ds_read_b128 v[182:185], v163 offset:33792
	ds_read_b128 v[186:189], v163 offset:34816
	ds_read_b128 v[190:193], v163 offset:35840
	ds_read_b128 v[194:197], v163 offset:36864
	ds_read_b128 v[198:201], v163 offset:37888
	ds_read_b128 v[202:205], v163 offset:38912
	ds_read_b128 v[206:209], v163 offset:39936
	global_load_lds_dwordx4 v[218:219], off
	v_lshl_add_u64 v[218:219], s[54:55], 0, v[146:147]
	s_mov_b32 m0, s65
	s_nop 0
	global_load_lds_dwordx4 v[218:219], off
	s_waitcnt vmcnt(8) lgkmcnt(0)
	s_barrier
	v_mfma_f32_16x16x32_bf16 v[140:143], v[48:51], v[178:181], v[140:143]
	v_mfma_f32_16x16x32_bf16 v[140:143], v[52:55], v[182:185], v[140:143]
	v_mfma_f32_16x16x32_bf16 v[124:127], v[48:51], v[186:189], v[124:127]
	v_mfma_f32_16x16x32_bf16 v[124:127], v[52:55], v[190:193], v[124:127]
	v_mfma_f32_16x16x32_bf16 v[108:111], v[48:51], v[194:197], v[108:111]
	v_mfma_f32_16x16x32_bf16 v[108:111], v[52:55], v[198:201], v[108:111]
	v_mfma_f32_16x16x32_bf16 v[92:95], v[48:51], v[202:205], v[92:95]
	v_mfma_f32_16x16x32_bf16 v[92:95], v[52:55], v[206:209], v[92:95]
	v_mfma_f32_16x16x32_bf16 v[136:139], v[64:67], v[178:181], v[136:139]
	v_mfma_f32_16x16x32_bf16 v[136:139], v[68:71], v[182:185], v[136:139]
	v_mfma_f32_16x16x32_bf16 v[120:123], v[64:67], v[186:189], v[120:123]
	v_mfma_f32_16x16x32_bf16 v[120:123], v[68:71], v[190:193], v[120:123]
	v_mfma_f32_16x16x32_bf16 v[104:107], v[64:67], v[194:197], v[104:107]
	v_mfma_f32_16x16x32_bf16 v[104:107], v[68:71], v[198:201], v[104:107]
	v_mfma_f32_16x16x32_bf16 v[88:91], v[64:67], v[202:205], v[88:91]
	v_mfma_f32_16x16x32_bf16 v[88:91], v[68:71], v[206:209], v[88:91]
	v_mfma_f32_16x16x32_bf16 v[132:135], v[154:157], v[178:181], v[132:135]
	v_mfma_f32_16x16x32_bf16 v[132:135], v[164:167], v[182:185], v[132:135]
	v_mfma_f32_16x16x32_bf16 v[116:119], v[154:157], v[186:189], v[116:119]
	v_mfma_f32_16x16x32_bf16 v[116:119], v[164:167], v[190:193], v[116:119]
	v_mfma_f32_16x16x32_bf16 v[100:103], v[154:157], v[194:197], v[100:103]
	v_mfma_f32_16x16x32_bf16 v[100:103], v[164:167], v[198:201], v[100:103]
	v_mfma_f32_16x16x32_bf16 v[84:87], v[154:157], v[202:205], v[84:87]
	v_mfma_f32_16x16x32_bf16 v[84:87], v[164:167], v[206:209], v[84:87]
	v_mfma_f32_16x16x32_bf16 v[128:131], v[168:171], v[178:181], v[128:131]
	v_mfma_f32_16x16x32_bf16 v[128:131], v[174:177], v[182:185], v[128:131]
	v_mfma_f32_16x16x32_bf16 v[112:115], v[168:171], v[186:189], v[112:115]
	v_mfma_f32_16x16x32_bf16 v[112:115], v[174:177], v[190:193], v[112:115]
	v_mfma_f32_16x16x32_bf16 v[96:99], v[168:171], v[194:197], v[96:99]
	v_mfma_f32_16x16x32_bf16 v[96:99], v[174:177], v[198:201], v[96:99]
	v_mfma_f32_16x16x32_bf16 v[80:83], v[168:171], v[202:205], v[80:83]
	v_mfma_f32_16x16x32_bf16 v[80:83], v[174:177], v[206:209], v[80:83]
	s_barrier
	s_add_i32 s54, s58, s50
	v_lshl_add_u64 v[158:159], v[158:159], 0, s[60:61]
	s_mov_b32 m0, s54
	ds_read_b128 v[178:181], v163 offset:49152
	ds_read_b128 v[182:185], v163 offset:50176
	ds_read_b128 v[186:189], v163 offset:51200
	ds_read_b128 v[190:193], v163 offset:52224
	ds_read_b128 v[194:197], v163 offset:53248
	ds_read_b128 v[198:201], v163 offset:54272
	ds_read_b128 v[202:205], v163 offset:55296
	ds_read_b128 v[206:209], v163 offset:56320
	global_load_lds_dwordx4 v[158:159], off
	s_add_i32 m0, s54, 0x2000
	s_add_u32 s52, s52, 0x20080
	v_lshl_add_u64 v[158:159], v[210:211], 0, s[60:61]
	s_addc_u32 s53, s53, 0
	s_add_i32 s54, s59, s50
	global_load_lds_dwordx4 v[158:159], off
	v_lshl_add_u64 v[158:159], s[52:53], 0, v[216:217]
	s_mov_b32 m0, s54
	s_nop 0
	global_load_lds_dwordx4 v[158:159], off
	v_lshl_add_u64 v[158:159], s[52:53], 0, v[148:149]
	s_add_i32 m0, s54, 0x2000
	s_nop 0
	global_load_lds_dwordx4 v[158:159], off
	v_lshl_add_u64 v[158:159], v[212:213], 0, s[60:61]
	s_mov_b32 m0, s85
	s_nop 0
	global_load_lds_dwordx4 v[158:159], off
	v_lshl_add_u64 v[158:159], v[214:215], 0, s[60:61]
	s_mov_b32 m0, s21
	s_nop 0
	global_load_lds_dwordx4 v[158:159], off
	s_waitcnt vmcnt(8) lgkmcnt(0)
	s_barrier
	v_mfma_f32_16x16x32_bf16 v[76:79], v[48:51], v[178:181], v[76:79]
	v_mfma_f32_16x16x32_bf16 v[76:79], v[52:55], v[182:185], v[76:79]
	v_mfma_f32_16x16x32_bf16 v[60:63], v[48:51], v[186:189], v[60:63]
	v_mfma_f32_16x16x32_bf16 v[60:63], v[52:55], v[190:193], v[60:63]
	v_mfma_f32_16x16x32_bf16 v[44:47], v[48:51], v[194:197], v[44:47]
	v_mfma_f32_16x16x32_bf16 v[44:47], v[52:55], v[198:201], v[44:47]
	v_mfma_f32_16x16x32_bf16 v[12:15], v[48:51], v[202:205], v[12:15]
	v_mfma_f32_16x16x32_bf16 v[12:15], v[52:55], v[206:209], v[12:15]
	v_mfma_f32_16x16x32_bf16 v[72:75], v[64:67], v[178:181], v[72:75]
	v_mfma_f32_16x16x32_bf16 v[72:75], v[68:71], v[182:185], v[72:75]
	v_mfma_f32_16x16x32_bf16 v[56:59], v[64:67], v[186:189], v[56:59]
	v_mfma_f32_16x16x32_bf16 v[56:59], v[68:71], v[190:193], v[56:59]
	v_mfma_f32_16x16x32_bf16 v[40:43], v[64:67], v[194:197], v[40:43]
	v_mfma_f32_16x16x32_bf16 v[40:43], v[68:71], v[198:201], v[40:43]
	v_mfma_f32_16x16x32_bf16 v[8:11], v[64:67], v[202:205], v[8:11]
	v_mfma_f32_16x16x32_bf16 v[8:11], v[68:71], v[206:209], v[8:11]
	v_mfma_f32_16x16x32_bf16 v[16:19], v[154:157], v[178:181], v[16:19]
	v_mfma_f32_16x16x32_bf16 v[68:71], v[164:167], v[182:185], v[16:19]
	v_mfma_f32_16x16x32_bf16 v[16:19], v[168:171], v[178:181], v[20:23]
	v_mfma_f32_16x16x32_bf16 v[64:67], v[174:177], v[182:185], v[16:19]
	v_mfma_f32_16x16x32_bf16 v[16:19], v[154:157], v[186:189], v[32:35]
	v_mfma_f32_16x16x32_bf16 v[52:55], v[164:167], v[190:193], v[16:19]
	v_mfma_f32_16x16x32_bf16 v[16:19], v[168:171], v[186:189], v[36:39]
	v_mfma_f32_16x16x32_bf16 v[48:51], v[174:177], v[190:193], v[16:19]
	v_mfma_f32_16x16x32_bf16 v[16:19], v[154:157], v[194:197], v[28:31]
	v_mfma_f32_16x16x32_bf16 v[28:31], v[164:167], v[198:201], v[16:19]
	v_mfma_f32_16x16x32_bf16 v[16:19], v[168:171], v[194:197], v[24:27]
	v_mfma_f32_16x16x32_bf16 v[0:3], v[154:157], v[202:205], v[0:3]
	v_mfma_f32_16x16x32_bf16 v[4:7], v[168:171], v[202:205], v[4:7]
	v_mfma_f32_16x16x32_bf16 v[24:27], v[174:177], v[198:201], v[16:19]
	v_mfma_f32_16x16x32_bf16 v[0:3], v[164:167], v[206:209], v[0:3]
	v_mfma_f32_16x16x32_bf16 v[4:7], v[174:177], v[206:209], v[4:7]
	s_barrier
	s_add_i32 vcc_hi, vcc_hi, 2
	s_add_u32 s88, s88, 0x100
	s_addc_u32 s89, s89, 0
	s_add_u32 s74, s74, 0x100
	s_addc_u32 vcc_lo, vcc_lo, 0
	s_cmp_gt_u32 vcc_hi, 5
	s_cbranch_scc0 .LBB0_1516
	s_and_b64 vcc, exec, s[38:39]
	s_cbranch_vccz .LBB0_1519
	s_barrier

.LBB0_1663:
	s_ashr_i32 s17, s16, 31
	s_lshl_b64 s[18:19], s[16:17], 20
	s_add_u32 s18, s27, s18
	s_addc_u32 s19, s31, s19
	s_and_b64 s[22:23], s[4:5], exec
	s_cselect_b32 s17, s19, s53
	s_cselect_b32 s96, s18, s52
	s_ashr_i32 s15, s14, 31
	s_lshl_b64 s[22:23], s[14:15], 20
	s_add_u32 s22, s36, s22
	s_addc_u32 s23, s41, s23
	s_and_b64 s[54:55], s[4:5], exec
	s_cselect_b32 s15, s23, s93
	s_cselect_b32 s97, s22, s92
	s_add_u32 s90, s52, 0x80080
	s_addc_u32 s91, s53, 0
	s_add_u32 s92, s92, 0x100
	v_mov_b32_e32 v0, 0
	s_addc_u32 s93, s93, 0
	s_mov_b32 vcc_lo, -2
	s_add_u32 s52, s90, 0xfff80080
	s_addc_u32 s53, s91, -1
	s_add_i32 s58, 0, 0x10000
	s_cmp_eq_u32 vcc_lo, 28
	s_cselect_b32 s55, s17, s53
	s_cselect_b32 s54, s96, s52
	s_cselect_b32 s53, s15, s93
	s_cselect_b32 s52, s97, s92
	s_add_i32 s81, 0, 0x14000
	v_add_u32_e32 v140, s58, v163
	v_add_u32_e32 v170, s81, v163
	ds_read_b128 v[128:131], v140
	ds_read_b128 v[132:135], v140 offset:1024
	ds_read_b128 v[136:139], v140 offset:2048
	ds_read_b128 v[140:143], v140 offset:3072
	ds_read_b128 v[154:157], v170
	ds_read_b128 v[158:161], v170 offset:1024
	ds_read_b128 v[166:169], v170 offset:2048
	ds_read_b128 v[174:177], v170 offset:3072
	v_lshl_add_u64 v[170:171], s[90:91], 0, v[150:151]
	s_add_i32 m0, s76, 0xc000
	ds_read_b128 v[178:181], v165
	ds_read_b128 v[182:185], v165 offset:1024
	ds_read_b128 v[186:189], v165 offset:2048
	ds_read_b128 v[190:193], v165 offset:3072
	ds_read_b128 v[194:197], v165 offset:4096
	ds_read_b128 v[198:201], v165 offset:5120
	ds_read_b128 v[202:205], v165 offset:6144
	ds_read_b128 v[206:209], v165 offset:7168
	global_load_lds_dwordx4 v[170:171], off
	v_lshl_add_u64 v[170:171], s[90:91], 0, v[152:153]
	s_add_i32 m0, s76, 0xe000
	s_nop 0
	global_load_lds_dwordx4 v[170:171], off
	s_waitcnt vmcnt(8) lgkmcnt(0)
	s_barrier
	v_mfma_f32_16x16x32_bf16 v[124:127], v[128:131], v[178:181], 0
	v_mfma_f32_16x16x32_bf16 v[124:127], v[132:135], v[182:185], v[124:127]
	v_mfma_f32_16x16x32_bf16 v[116:119], v[128:131], v[186:189], 0
	v_mfma_f32_16x16x32_bf16 v[116:119], v[132:135], v[190:193], v[116:119]
	v_mfma_f32_16x16x32_bf16 v[96:99], v[128:131], v[194:197], 0
	v_mfma_f32_16x16x32_bf16 v[96:99], v[132:135], v[198:201], v[96:99]
	v_mfma_f32_16x16x32_bf16 v[80:83], v[128:131], v[202:205], 0
	v_mfma_f32_16x16x32_bf16 v[80:83], v[132:135], v[206:209], v[80:83]
	v_mfma_f32_16x16x32_bf16 v[120:123], v[136:139], v[178:181], 0
	v_mfma_f32_16x16x32_bf16 v[120:123], v[140:143], v[182:185], v[120:123]
	v_mfma_f32_16x16x32_bf16 v[112:115], v[136:139], v[186:189], 0
	v_mfma_f32_16x16x32_bf16 v[112:115], v[140:143], v[190:193], v[112:115]
	v_mfma_f32_16x16x32_bf16 v[88:91], v[136:139], v[194:197], 0
	v_mfma_f32_16x16x32_bf16 v[88:91], v[140:143], v[198:201], v[88:91]
	v_mfma_f32_16x16x32_bf16 v[72:75], v[136:139], v[202:205], 0
	v_mfma_f32_16x16x32_bf16 v[72:75], v[140:143], v[206:209], v[72:75]
	v_mfma_f32_16x16x32_bf16 v[108:111], v[154:157], v[178:181], 0
	v_mfma_f32_16x16x32_bf16 v[108:111], v[158:161], v[182:185], v[108:111]
	v_mfma_f32_16x16x32_bf16 v[100:103], v[154:157], v[186:189], 0
	v_mfma_f32_16x16x32_bf16 v[100:103], v[158:161], v[190:193], v[100:103]
	v_mfma_f32_16x16x32_bf16 v[84:87], v[154:157], v[194:197], 0
	v_mfma_f32_16x16x32_bf16 v[84:87], v[158:161], v[198:201], v[84:87]
	v_mfma_f32_16x16x32_bf16 v[68:71], v[154:157], v[202:205], 0
	v_mfma_f32_16x16x32_bf16 v[68:71], v[158:161], v[206:209], v[68:71]
	v_mfma_f32_16x16x32_bf16 v[104:107], v[166:169], v[178:181], 0
	v_mfma_f32_16x16x32_bf16 v[104:107], v[174:177], v[182:185], v[104:107]
	v_mfma_f32_16x16x32_bf16 v[92:95], v[166:169], v[186:189], 0
	v_mfma_f32_16x16x32_bf16 v[92:95], v[174:177], v[190:193], v[92:95]
	v_mfma_f32_16x16x32_bf16 v[76:79], v[166:169], v[194:197], 0
	v_mfma_f32_16x16x32_bf16 v[76:79], v[174:177], v[198:201], v[76:79]
	v_mfma_f32_16x16x32_bf16 v[64:67], v[166:169], v[202:205], 0
	v_mfma_f32_16x16x32_bf16 v[64:67], v[174:177], v[206:209], v[64:67]
	s_barrier
	s_add_i32 s58, s58, s50
	v_lshl_add_u64 v[170:171], s[52:53], 0, v[216:217]
	s_mov_b32 m0, s58
	ds_read_b128 v[178:181], v165 offset:16384
	ds_read_b128 v[182:185], v165 offset:17408
	ds_read_b128 v[186:189], v165 offset:18432
	ds_read_b128 v[190:193], v165 offset:19456
	ds_read_b128 v[194:197], v165 offset:20480
	ds_read_b128 v[198:201], v165 offset:21504
	ds_read_b128 v[202:205], v165 offset:22528
	ds_read_b128 v[206:209], v165 offset:23552
	global_load_lds_dwordx4 v[170:171], off
	s_add_i32 m0, s58, 0x2000
	s_add_u32 s58, s52, 0x80000
	v_lshl_add_u64 v[210:211], s[52:53], 0, v[148:149]
	s_addc_u32 s59, s53, 0
	s_add_i32 s81, s81, s50
	global_load_lds_dwordx4 v[210:211], off
	v_lshl_add_u64 v[212:213], s[58:59], 0, v[216:217]
	s_mov_b32 m0, s81
	v_lshl_add_u64 v[214:215], s[54:55], 0, v[146:147]
	global_load_lds_dwordx4 v[212:213], off
	v_lshl_add_u64 v[212:213], s[58:59], 0, v[148:149]
	s_add_i32 m0, s81, 0x2000
	s_nop 0
	global_load_lds_dwordx4 v[212:213], off
	v_lshl_add_u64 v[212:213], s[54:55], 0, v[144:145]
	s_mov_b32 m0, s76
	s_nop 0
	global_load_lds_dwordx4 v[212:213], off
	s_mov_b32 m0, s45
	s_nop 0
	global_load_lds_dwordx4 v[214:215], off
	s_waitcnt vmcnt(8) lgkmcnt(0)
	s_barrier
	v_mfma_f32_16x16x32_bf16 v[60:63], v[128:131], v[178:181], 0
	v_mfma_f32_16x16x32_bf16 v[60:63], v[132:135], v[182:185], v[60:63]
	v_mfma_f32_16x16x32_bf16 v[48:51], v[128:131], v[186:189], 0
	v_mfma_f32_16x16x32_bf16 v[48:51], v[132:135], v[190:193], v[48:51]
	v_mfma_f32_16x16x32_bf16 v[32:35], v[128:131], v[194:197], 0
	v_mfma_f32_16x16x32_bf16 v[32:35], v[132:135], v[198:201], v[32:35]
	v_mfma_f32_16x16x32_bf16 v[16:19], v[128:131], v[202:205], 0
	v_mfma_f32_16x16x32_bf16 v[16:19], v[132:135], v[206:209], v[16:19]
	v_mfma_f32_16x16x32_bf16 v[56:59], v[136:139], v[178:181], 0
	v_mfma_f32_16x16x32_bf16 v[56:59], v[140:143], v[182:185], v[56:59]
	v_mfma_f32_16x16x32_bf16 v[40:43], v[136:139], v[186:189], 0
	v_mfma_f32_16x16x32_bf16 v[40:43], v[140:143], v[190:193], v[40:43]
	v_mfma_f32_16x16x32_bf16 v[24:27], v[136:139], v[194:197], 0
	v_mfma_f32_16x16x32_bf16 v[24:27], v[140:143], v[198:201], v[24:27]
	v_mfma_f32_16x16x32_bf16 v[8:11], v[136:139], v[202:205], 0
	v_mfma_f32_16x16x32_bf16 v[8:11], v[140:143], v[206:209], v[8:11]
	v_mfma_f32_16x16x32_bf16 v[52:55], v[154:157], v[178:181], 0
	v_mfma_f32_16x16x32_bf16 v[52:55], v[158:161], v[182:185], v[52:55]
	v_mfma_f32_16x16x32_bf16 v[36:39], v[154:157], v[186:189], 0
	v_mfma_f32_16x16x32_bf16 v[36:39], v[158:161], v[190:193], v[36:39]
	v_mfma_f32_16x16x32_bf16 v[20:23], v[154:157], v[194:197], 0
	v_mfma_f32_16x16x32_bf16 v[20:23], v[158:161], v[198:201], v[20:23]
	v_mfma_f32_16x16x32_bf16 v[4:7], v[154:157], v[202:205], 0
	v_mfma_f32_16x16x32_bf16 v[4:7], v[158:161], v[206:209], v[4:7]
	v_mfma_f32_16x16x32_bf16 v[44:47], v[166:169], v[178:181], 0
	v_mfma_f32_16x16x32_bf16 v[44:47], v[174:177], v[182:185], v[44:47]
	v_mfma_f32_16x16x32_bf16 v[28:31], v[166:169], v[186:189], 0
	v_mfma_f32_16x16x32_bf16 v[28:31], v[174:177], v[190:193], v[28:31]
	v_mfma_f32_16x16x32_bf16 v[12:15], v[166:169], v[194:197], 0
	v_mfma_f32_16x16x32_bf16 v[12:15], v[174:177], v[198:201], v[12:15]
	v_mfma_f32_16x16x32_bf16 v[0:3], v[166:169], v[202:205], 0
	v_mfma_f32_16x16x32_bf16 v[0:3], v[174:177], v[206:209], v[0:3]
	s_barrier
	s_add_i32 s58, 0, 0x18000
	s_add_i32 s59, 0, 0x1c000
	v_add_u32_e32 v140, s58, v163
	v_add_u32_e32 v173, s59, v163
	ds_read_b128 v[128:131], v140
	ds_read_b128 v[132:135], v140 offset:1024
	ds_read_b128 v[136:139], v140 offset:2048
	ds_read_b128 v[140:143], v140 offset:3072
	ds_read_b128 v[154:157], v173
	ds_read_b128 v[158:161], v173 offset:1024
	ds_read_b128 v[166:169], v173 offset:2048
	ds_read_b128 v[174:177], v173 offset:3072
	s_add_u32 s54, s54, 0x80000
	s_addc_u32 s55, s55, 0
	s_mov_b32 m0, s65
	v_lshl_add_u64 v[218:219], s[54:55], 0, v[144:145]
	ds_read_b128 v[178:181], v165 offset:32768
	ds_read_b128 v[182:185], v165 offset:33792
	ds_read_b128 v[186:189], v165 offset:34816
	ds_read_b128 v[190:193], v165 offset:35840
	ds_read_b128 v[194:197], v165 offset:36864
	ds_read_b128 v[198:201], v165 offset:37888
	ds_read_b128 v[202:205], v165 offset:38912
	ds_read_b128 v[206:209], v165 offset:39936
	global_load_lds_dwordx4 v[218:219], off
	v_lshl_add_u64 v[218:219], s[54:55], 0, v[146:147]
	s_mov_b32 m0, s72
	s_nop 0
	global_load_lds_dwordx4 v[218:219], off
	s_waitcnt vmcnt(8) lgkmcnt(0)
	s_barrier
	v_mfma_f32_16x16x32_bf16 v[124:127], v[128:131], v[178:181], v[124:127]
	v_mfma_f32_16x16x32_bf16 v[124:127], v[132:135], v[182:185], v[124:127]
	v_mfma_f32_16x16x32_bf16 v[116:119], v[128:131], v[186:189], v[116:119]
	v_mfma_f32_16x16x32_bf16 v[116:119], v[132:135], v[190:193], v[116:119]
	v_mfma_f32_16x16x32_bf16 v[96:99], v[128:131], v[194:197], v[96:99]
	v_mfma_f32_16x16x32_bf16 v[96:99], v[132:135], v[198:201], v[96:99]
	v_mfma_f32_16x16x32_bf16 v[80:83], v[128:131], v[202:205], v[80:83]
	v_mfma_f32_16x16x32_bf16 v[80:83], v[132:135], v[206:209], v[80:83]
	v_mfma_f32_16x16x32_bf16 v[120:123], v[136:139], v[178:181], v[120:123]
	v_mfma_f32_16x16x32_bf16 v[120:123], v[140:143], v[182:185], v[120:123]
	v_mfma_f32_16x16x32_bf16 v[112:115], v[136:139], v[186:189], v[112:115]
	v_mfma_f32_16x16x32_bf16 v[112:115], v[140:143], v[190:193], v[112:115]
	v_mfma_f32_16x16x32_bf16 v[88:91], v[136:139], v[194:197], v[88:91]
	v_mfma_f32_16x16x32_bf16 v[88:91], v[140:143], v[198:201], v[88:91]
	v_mfma_f32_16x16x32_bf16 v[72:75], v[136:139], v[202:205], v[72:75]
	v_mfma_f32_16x16x32_bf16 v[72:75], v[140:143], v[206:209], v[72:75]
	v_mfma_f32_16x16x32_bf16 v[108:111], v[154:157], v[178:181], v[108:111]
	v_mfma_f32_16x16x32_bf16 v[108:111], v[158:161], v[182:185], v[108:111]
	v_mfma_f32_16x16x32_bf16 v[100:103], v[154:157], v[186:189], v[100:103]
	v_mfma_f32_16x16x32_bf16 v[100:103], v[158:161], v[190:193], v[100:103]
	v_mfma_f32_16x16x32_bf16 v[84:87], v[154:157], v[194:197], v[84:87]
	v_mfma_f32_16x16x32_bf16 v[84:87], v[158:161], v[198:201], v[84:87]
	v_mfma_f32_16x16x32_bf16 v[68:71], v[154:157], v[202:205], v[68:71]
	v_mfma_f32_16x16x32_bf16 v[68:71], v[158:161], v[206:209], v[68:71]
	v_mfma_f32_16x16x32_bf16 v[104:107], v[166:169], v[178:181], v[104:107]
	v_mfma_f32_16x16x32_bf16 v[104:107], v[174:177], v[182:185], v[104:107]
	v_mfma_f32_16x16x32_bf16 v[92:95], v[166:169], v[186:189], v[92:95]
	v_mfma_f32_16x16x32_bf16 v[92:95], v[174:177], v[190:193], v[92:95]
	v_mfma_f32_16x16x32_bf16 v[76:79], v[166:169], v[194:197], v[76:79]
	v_mfma_f32_16x16x32_bf16 v[76:79], v[174:177], v[198:201], v[76:79]
	v_mfma_f32_16x16x32_bf16 v[64:67], v[166:169], v[202:205], v[64:67]
	v_mfma_f32_16x16x32_bf16 v[64:67], v[174:177], v[206:209], v[64:67]
	s_barrier
	s_add_i32 s54, s58, s50
	v_lshl_add_u64 v[170:171], v[170:171], 0, s[60:61]
	s_mov_b32 m0, s54
	ds_read_b128 v[178:181], v165 offset:49152
	ds_read_b128 v[182:185], v165 offset:50176
	ds_read_b128 v[186:189], v165 offset:51200
	ds_read_b128 v[190:193], v165 offset:52224
	ds_read_b128 v[194:197], v165 offset:53248
	ds_read_b128 v[198:201], v165 offset:54272
	ds_read_b128 v[202:205], v165 offset:55296
	ds_read_b128 v[206:209], v165 offset:56320
	global_load_lds_dwordx4 v[170:171], off
	s_add_i32 m0, s54, 0x2000
	s_add_u32 s52, s52, 0x80080
	v_lshl_add_u64 v[170:171], v[210:211], 0, s[60:61]
	s_addc_u32 s53, s53, 0
	s_add_i32 s54, s59, s50
	global_load_lds_dwordx4 v[170:171], off
	v_lshl_add_u64 v[170:171], s[52:53], 0, v[216:217]
	s_mov_b32 m0, s54
	s_nop 0
	global_load_lds_dwordx4 v[170:171], off
	v_lshl_add_u64 v[170:171], s[52:53], 0, v[148:149]
	s_add_i32 m0, s54, 0x2000
	s_nop 0
	global_load_lds_dwordx4 v[170:171], off
	v_lshl_add_u64 v[170:171], v[212:213], 0, s[60:61]
	s_mov_b32 m0, s87
	s_nop 0
	global_load_lds_dwordx4 v[170:171], off
	v_lshl_add_u64 v[170:171], v[214:215], 0, s[60:61]
	s_mov_b32 m0, s89
	s_nop 0
	global_load_lds_dwordx4 v[170:171], off
	s_waitcnt vmcnt(8) lgkmcnt(0)
	s_barrier
	v_mfma_f32_16x16x32_bf16 v[60:63], v[128:131], v[178:181], v[60:63]
	v_mfma_f32_16x16x32_bf16 v[60:63], v[132:135], v[182:185], v[60:63]
	v_mfma_f32_16x16x32_bf16 v[48:51], v[128:131], v[186:189], v[48:51]
	v_mfma_f32_16x16x32_bf16 v[48:51], v[132:135], v[190:193], v[48:51]
	v_mfma_f32_16x16x32_bf16 v[32:35], v[128:131], v[194:197], v[32:35]
	v_mfma_f32_16x16x32_bf16 v[32:35], v[132:135], v[198:201], v[32:35]
	v_mfma_f32_16x16x32_bf16 v[16:19], v[128:131], v[202:205], v[16:19]
	v_mfma_f32_16x16x32_bf16 v[16:19], v[132:135], v[206:209], v[16:19]
	v_mfma_f32_16x16x32_bf16 v[56:59], v[136:139], v[178:181], v[56:59]
	v_mfma_f32_16x16x32_bf16 v[56:59], v[140:143], v[182:185], v[56:59]
	v_mfma_f32_16x16x32_bf16 v[40:43], v[136:139], v[186:189], v[40:43]
	v_mfma_f32_16x16x32_bf16 v[40:43], v[140:143], v[190:193], v[40:43]
	v_mfma_f32_16x16x32_bf16 v[24:27], v[136:139], v[194:197], v[24:27]
	v_mfma_f32_16x16x32_bf16 v[24:27], v[140:143], v[198:201], v[24:27]
	v_mfma_f32_16x16x32_bf16 v[8:11], v[136:139], v[202:205], v[8:11]
	v_mfma_f32_16x16x32_bf16 v[8:11], v[140:143], v[206:209], v[8:11]
	v_mfma_f32_16x16x32_bf16 v[52:55], v[154:157], v[178:181], v[52:55]
	v_mfma_f32_16x16x32_bf16 v[52:55], v[158:161], v[182:185], v[52:55]
	v_mfma_f32_16x16x32_bf16 v[36:39], v[154:157], v[186:189], v[36:39]
	v_mfma_f32_16x16x32_bf16 v[36:39], v[158:161], v[190:193], v[36:39]
	v_mfma_f32_16x16x32_bf16 v[20:23], v[154:157], v[194:197], v[20:23]
	v_mfma_f32_16x16x32_bf16 v[20:23], v[158:161], v[198:201], v[20:23]
	v_mfma_f32_16x16x32_bf16 v[4:7], v[154:157], v[202:205], v[4:7]
	v_mfma_f32_16x16x32_bf16 v[4:7], v[158:161], v[206:209], v[4:7]
	v_mfma_f32_16x16x32_bf16 v[44:47], v[166:169], v[178:181], v[44:47]
	v_mfma_f32_16x16x32_bf16 v[44:47], v[174:177], v[182:185], v[44:47]
	v_mfma_f32_16x16x32_bf16 v[28:31], v[166:169], v[186:189], v[28:31]
	v_mfma_f32_16x16x32_bf16 v[28:31], v[174:177], v[190:193], v[28:31]
	v_mfma_f32_16x16x32_bf16 v[12:15], v[166:169], v[194:197], v[12:15]
	v_mfma_f32_16x16x32_bf16 v[12:15], v[174:177], v[198:201], v[12:15]
	v_mfma_f32_16x16x32_bf16 v[0:3], v[166:169], v[202:205], v[0:3]
	v_mfma_f32_16x16x32_bf16 v[0:3], v[174:177], v[206:209], v[0:3]
	s_barrier
	s_add_i32 vcc_lo, vcc_lo, 2
	s_add_u32 s90, s90, 0x100
	s_addc_u32 s91, s91, 0
	s_add_u32 s92, s92, 0x100
	s_addc_u32 s93, s93, 0
	s_cmp_gt_u32 vcc_lo, 29
	s_cbranch_scc0 .LBB0_1664
	s_branch .Lzexit_5
.LBB0_1664:
	s_add_u32 s52, s90, 0xfff80080
	s_addc_u32 s53, s91, -1
	s_add_i32 s58, 0, 0x10000
	s_cmp_eq_u32 vcc_lo, 28
	s_cselect_b32 s55, s17, s53
	s_cselect_b32 s54, s96, s52
	s_cselect_b32 s53, s15, s93
	s_cselect_b32 s52, s97, s92
	s_add_i32 s81, 0, 0x14000
	v_add_u32_e32 v140, s58, v163
	v_add_u32_e32 v170, s81, v163
	ds_read_b128 v[128:131], v140
	ds_read_b128 v[132:135], v140 offset:1024
	ds_read_b128 v[136:139], v140 offset:2048
	ds_read_b128 v[140:143], v140 offset:3072
	ds_read_b128 v[154:157], v170
	ds_read_b128 v[158:161], v170 offset:1024
	ds_read_b128 v[166:169], v170 offset:2048
	ds_read_b128 v[174:177], v170 offset:3072
	v_lshl_add_u64 v[170:171], s[90:91], 0, v[150:151]
	s_add_i32 m0, s76, 0xc000
	ds_read_b128 v[178:181], v165
	ds_read_b128 v[182:185], v165 offset:1024
	ds_read_b128 v[186:189], v165 offset:2048
	ds_read_b128 v[190:193], v165 offset:3072
	ds_read_b128 v[194:197], v165 offset:4096
	ds_read_b128 v[198:201], v165 offset:5120
	ds_read_b128 v[202:205], v165 offset:6144
	ds_read_b128 v[206:209], v165 offset:7168
	global_load_lds_dwordx4 v[170:171], off
	v_lshl_add_u64 v[170:171], s[90:91], 0, v[152:153]
	s_add_i32 m0, s76, 0xe000
	s_nop 0
	global_load_lds_dwordx4 v[170:171], off
	s_waitcnt vmcnt(8) lgkmcnt(0)
	s_barrier
	v_mfma_f32_16x16x32_bf16 v[124:127], v[128:131], v[178:181], v[124:127]
	v_mfma_f32_16x16x32_bf16 v[124:127], v[132:135], v[182:185], v[124:127]
	v_mfma_f32_16x16x32_bf16 v[116:119], v[128:131], v[186:189], v[116:119]
	v_mfma_f32_16x16x32_bf16 v[116:119], v[132:135], v[190:193], v[116:119]
	v_mfma_f32_16x16x32_bf16 v[96:99], v[128:131], v[194:197], v[96:99]
	v_mfma_f32_16x16x32_bf16 v[96:99], v[132:135], v[198:201], v[96:99]
	v_mfma_f32_16x16x32_bf16 v[80:83], v[128:131], v[202:205], v[80:83]
	v_mfma_f32_16x16x32_bf16 v[80:83], v[132:135], v[206:209], v[80:83]
	v_mfma_f32_16x16x32_bf16 v[120:123], v[136:139], v[178:181], v[120:123]
	v_mfma_f32_16x16x32_bf16 v[120:123], v[140:143], v[182:185], v[120:123]
	v_mfma_f32_16x16x32_bf16 v[112:115], v[136:139], v[186:189], v[112:115]
	v_mfma_f32_16x16x32_bf16 v[112:115], v[140:143], v[190:193], v[112:115]
	v_mfma_f32_16x16x32_bf16 v[88:91], v[136:139], v[194:197], v[88:91]
	v_mfma_f32_16x16x32_bf16 v[88:91], v[140:143], v[198:201], v[88:91]
	v_mfma_f32_16x16x32_bf16 v[72:75], v[136:139], v[202:205], v[72:75]
	v_mfma_f32_16x16x32_bf16 v[72:75], v[140:143], v[206:209], v[72:75]
	v_mfma_f32_16x16x32_bf16 v[108:111], v[154:157], v[178:181], v[108:111]
	v_mfma_f32_16x16x32_bf16 v[108:111], v[158:161], v[182:185], v[108:111]
	v_mfma_f32_16x16x32_bf16 v[100:103], v[154:157], v[186:189], v[100:103]
	v_mfma_f32_16x16x32_bf16 v[100:103], v[158:161], v[190:193], v[100:103]
	v_mfma_f32_16x16x32_bf16 v[84:87], v[154:157], v[194:197], v[84:87]
	v_mfma_f32_16x16x32_bf16 v[84:87], v[158:161], v[198:201], v[84:87]
	v_mfma_f32_16x16x32_bf16 v[68:71], v[154:157], v[202:205], v[68:71]
	v_mfma_f32_16x16x32_bf16 v[68:71], v[158:161], v[206:209], v[68:71]
	v_mfma_f32_16x16x32_bf16 v[104:107], v[166:169], v[178:181], v[104:107]
	v_mfma_f32_16x16x32_bf16 v[104:107], v[174:177], v[182:185], v[104:107]
	v_mfma_f32_16x16x32_bf16 v[92:95], v[166:169], v[186:189], v[92:95]
	v_mfma_f32_16x16x32_bf16 v[92:95], v[174:177], v[190:193], v[92:95]
	v_mfma_f32_16x16x32_bf16 v[76:79], v[166:169], v[194:197], v[76:79]
	v_mfma_f32_16x16x32_bf16 v[76:79], v[174:177], v[198:201], v[76:79]
	v_mfma_f32_16x16x32_bf16 v[64:67], v[166:169], v[202:205], v[64:67]
	v_mfma_f32_16x16x32_bf16 v[64:67], v[174:177], v[206:209], v[64:67]
	s_barrier
	s_add_i32 s58, s58, s50
	v_lshl_add_u64 v[170:171], s[52:53], 0, v[216:217]
	s_mov_b32 m0, s58
	ds_read_b128 v[178:181], v165 offset:16384
	ds_read_b128 v[182:185], v165 offset:17408
	ds_read_b128 v[186:189], v165 offset:18432
	ds_read_b128 v[190:193], v165 offset:19456
	ds_read_b128 v[194:197], v165 offset:20480
	ds_read_b128 v[198:201], v165 offset:21504
	ds_read_b128 v[202:205], v165 offset:22528
	ds_read_b128 v[206:209], v165 offset:23552
	global_load_lds_dwordx4 v[170:171], off
	s_add_i32 m0, s58, 0x2000
	s_add_u32 s58, s52, 0x80000
	v_lshl_add_u64 v[210:211], s[52:53], 0, v[148:149]
	s_addc_u32 s59, s53, 0
	s_add_i32 s81, s81, s50
	global_load_lds_dwordx4 v[210:211], off
	v_lshl_add_u64 v[212:213], s[58:59], 0, v[216:217]
	s_mov_b32 m0, s81
	v_lshl_add_u64 v[214:215], s[54:55], 0, v[146:147]
	global_load_lds_dwordx4 v[212:213], off
	v_lshl_add_u64 v[212:213], s[58:59], 0, v[148:149]
	s_add_i32 m0, s81, 0x2000
	s_nop 0
	global_load_lds_dwordx4 v[212:213], off
	v_lshl_add_u64 v[212:213], s[54:55], 0, v[144:145]
	s_mov_b32 m0, s76
	s_nop 0
	global_load_lds_dwordx4 v[212:213], off
	s_mov_b32 m0, s45
	s_nop 0
	global_load_lds_dwordx4 v[214:215], off
	s_waitcnt vmcnt(8) lgkmcnt(0)
	s_barrier
	v_mfma_f32_16x16x32_bf16 v[60:63], v[128:131], v[178:181], v[60:63]
	v_mfma_f32_16x16x32_bf16 v[60:63], v[132:135], v[182:185], v[60:63]
	v_mfma_f32_16x16x32_bf16 v[48:51], v[128:131], v[186:189], v[48:51]
	v_mfma_f32_16x16x32_bf16 v[48:51], v[132:135], v[190:193], v[48:51]
	v_mfma_f32_16x16x32_bf16 v[32:35], v[128:131], v[194:197], v[32:35]
	v_mfma_f32_16x16x32_bf16 v[32:35], v[132:135], v[198:201], v[32:35]
	v_mfma_f32_16x16x32_bf16 v[16:19], v[128:131], v[202:205], v[16:19]
	v_mfma_f32_16x16x32_bf16 v[16:19], v[132:135], v[206:209], v[16:19]
	v_mfma_f32_16x16x32_bf16 v[56:59], v[136:139], v[178:181], v[56:59]
	v_mfma_f32_16x16x32_bf16 v[56:59], v[140:143], v[182:185], v[56:59]
	v_mfma_f32_16x16x32_bf16 v[40:43], v[136:139], v[186:189], v[40:43]
	v_mfma_f32_16x16x32_bf16 v[40:43], v[140:143], v[190:193], v[40:43]
	v_mfma_f32_16x16x32_bf16 v[24:27], v[136:139], v[194:197], v[24:27]
	v_mfma_f32_16x16x32_bf16 v[24:27], v[140:143], v[198:201], v[24:27]
	v_mfma_f32_16x16x32_bf16 v[8:11], v[136:139], v[202:205], v[8:11]
	v_mfma_f32_16x16x32_bf16 v[8:11], v[140:143], v[206:209], v[8:11]
	v_mfma_f32_16x16x32_bf16 v[52:55], v[154:157], v[178:181], v[52:55]
	v_mfma_f32_16x16x32_bf16 v[52:55], v[158:161], v[182:185], v[52:55]
	v_mfma_f32_16x16x32_bf16 v[36:39], v[154:157], v[186:189], v[36:39]
	v_mfma_f32_16x16x32_bf16 v[36:39], v[158:161], v[190:193], v[36:39]
	v_mfma_f32_16x16x32_bf16 v[20:23], v[154:157], v[194:197], v[20:23]
	v_mfma_f32_16x16x32_bf16 v[20:23], v[158:161], v[198:201], v[20:23]
	v_mfma_f32_16x16x32_bf16 v[4:7], v[154:157], v[202:205], v[4:7]
	v_mfma_f32_16x16x32_bf16 v[4:7], v[158:161], v[206:209], v[4:7]
	v_mfma_f32_16x16x32_bf16 v[44:47], v[166:169], v[178:181], v[44:47]
	v_mfma_f32_16x16x32_bf16 v[44:47], v[174:177], v[182:185], v[44:47]
	v_mfma_f32_16x16x32_bf16 v[28:31], v[166:169], v[186:189], v[28:31]
	v_mfma_f32_16x16x32_bf16 v[28:31], v[174:177], v[190:193], v[28:31]
	v_mfma_f32_16x16x32_bf16 v[12:15], v[166:169], v[194:197], v[12:15]
	v_mfma_f32_16x16x32_bf16 v[12:15], v[174:177], v[198:201], v[12:15]
	v_mfma_f32_16x16x32_bf16 v[0:3], v[166:169], v[202:205], v[0:3]
	v_mfma_f32_16x16x32_bf16 v[0:3], v[174:177], v[206:209], v[0:3]
	s_barrier
	s_add_i32 s58, 0, 0x18000
	s_add_i32 s59, 0, 0x1c000
	v_add_u32_e32 v140, s58, v163
	v_add_u32_e32 v173, s59, v163
	ds_read_b128 v[128:131], v140
	ds_read_b128 v[132:135], v140 offset:1024
	ds_read_b128 v[136:139], v140 offset:2048
	ds_read_b128 v[140:143], v140 offset:3072
	ds_read_b128 v[154:157], v173
	ds_read_b128 v[158:161], v173 offset:1024
	ds_read_b128 v[166:169], v173 offset:2048
	ds_read_b128 v[174:177], v173 offset:3072
	s_add_u32 s54, s54, 0x80000
	s_addc_u32 s55, s55, 0
	s_mov_b32 m0, s65
	v_lshl_add_u64 v[218:219], s[54:55], 0, v[144:145]
	ds_read_b128 v[178:181], v165 offset:32768
	ds_read_b128 v[182:185], v165 offset:33792
	ds_read_b128 v[186:189], v165 offset:34816
	ds_read_b128 v[190:193], v165 offset:35840
	ds_read_b128 v[194:197], v165 offset:36864
	ds_read_b128 v[198:201], v165 offset:37888
	ds_read_b128 v[202:205], v165 offset:38912
	ds_read_b128 v[206:209], v165 offset:39936
	global_load_lds_dwordx4 v[218:219], off
	v_lshl_add_u64 v[218:219], s[54:55], 0, v[146:147]
	s_mov_b32 m0, s72
	s_nop 0
	global_load_lds_dwordx4 v[218:219], off
	s_waitcnt vmcnt(8) lgkmcnt(0)
	s_barrier
	v_mfma_f32_16x16x32_bf16 v[124:127], v[128:131], v[178:181], v[124:127]
	v_mfma_f32_16x16x32_bf16 v[124:127], v[132:135], v[182:185], v[124:127]
	v_mfma_f32_16x16x32_bf16 v[116:119], v[128:131], v[186:189], v[116:119]
	v_mfma_f32_16x16x32_bf16 v[116:119], v[132:135], v[190:193], v[116:119]
	v_mfma_f32_16x16x32_bf16 v[96:99], v[128:131], v[194:197], v[96:99]
	v_mfma_f32_16x16x32_bf16 v[96:99], v[132:135], v[198:201], v[96:99]
	v_mfma_f32_16x16x32_bf16 v[80:83], v[128:131], v[202:205], v[80:83]
	v_mfma_f32_16x16x32_bf16 v[80:83], v[132:135], v[206:209], v[80:83]
	v_mfma_f32_16x16x32_bf16 v[120:123], v[136:139], v[178:181], v[120:123]
	v_mfma_f32_16x16x32_bf16 v[120:123], v[140:143], v[182:185], v[120:123]
	v_mfma_f32_16x16x32_bf16 v[112:115], v[136:139], v[186:189], v[112:115]
	v_mfma_f32_16x16x32_bf16 v[112:115], v[140:143], v[190:193], v[112:115]
	v_mfma_f32_16x16x32_bf16 v[88:91], v[136:139], v[194:197], v[88:91]
	v_mfma_f32_16x16x32_bf16 v[88:91], v[140:143], v[198:201], v[88:91]
	v_mfma_f32_16x16x32_bf16 v[72:75], v[136:139], v[202:205], v[72:75]
	v_mfma_f32_16x16x32_bf16 v[72:75], v[140:143], v[206:209], v[72:75]
	v_mfma_f32_16x16x32_bf16 v[108:111], v[154:157], v[178:181], v[108:111]
	v_mfma_f32_16x16x32_bf16 v[108:111], v[158:161], v[182:185], v[108:111]
	v_mfma_f32_16x16x32_bf16 v[100:103], v[154:157], v[186:189], v[100:103]
	v_mfma_f32_16x16x32_bf16 v[100:103], v[158:161], v[190:193], v[100:103]
	v_mfma_f32_16x16x32_bf16 v[84:87], v[154:157], v[194:197], v[84:87]
	v_mfma_f32_16x16x32_bf16 v[84:87], v[158:161], v[198:201], v[84:87]
	v_mfma_f32_16x16x32_bf16 v[68:71], v[154:157], v[202:205], v[68:71]
	v_mfma_f32_16x16x32_bf16 v[68:71], v[158:161], v[206:209], v[68:71]
	v_mfma_f32_16x16x32_bf16 v[104:107], v[166:169], v[178:181], v[104:107]
	v_mfma_f32_16x16x32_bf16 v[104:107], v[174:177], v[182:185], v[104:107]
	v_mfma_f32_16x16x32_bf16 v[92:95], v[166:169], v[186:189], v[92:95]
	v_mfma_f32_16x16x32_bf16 v[92:95], v[174:177], v[190:193], v[92:95]
	v_mfma_f32_16x16x32_bf16 v[76:79], v[166:169], v[194:197], v[76:79]
	v_mfma_f32_16x16x32_bf16 v[76:79], v[174:177], v[198:201], v[76:79]
	v_mfma_f32_16x16x32_bf16 v[64:67], v[166:169], v[202:205], v[64:67]
	v_mfma_f32_16x16x32_bf16 v[64:67], v[174:177], v[206:209], v[64:67]
	s_barrier
	s_add_i32 s54, s58, s50
	v_lshl_add_u64 v[170:171], v[170:171], 0, s[60:61]
	s_mov_b32 m0, s54
	ds_read_b128 v[178:181], v165 offset:49152
	ds_read_b128 v[182:185], v165 offset:50176
	ds_read_b128 v[186:189], v165 offset:51200
	ds_read_b128 v[190:193], v165 offset:52224
	ds_read_b128 v[194:197], v165 offset:53248
	ds_read_b128 v[198:201], v165 offset:54272
	ds_read_b128 v[202:205], v165 offset:55296
	ds_read_b128 v[206:209], v165 offset:56320
	global_load_lds_dwordx4 v[170:171], off
	s_add_i32 m0, s54, 0x2000
	s_add_u32 s52, s52, 0x80080
	v_lshl_add_u64 v[170:171], v[210:211], 0, s[60:61]
	s_addc_u32 s53, s53, 0
	s_add_i32 s54, s59, s50
	global_load_lds_dwordx4 v[170:171], off
	v_lshl_add_u64 v[170:171], s[52:53], 0, v[216:217]
	s_mov_b32 m0, s54
	s_nop 0
	global_load_lds_dwordx4 v[170:171], off
	v_lshl_add_u64 v[170:171], s[52:53], 0, v[148:149]
	s_add_i32 m0, s54, 0x2000
	s_nop 0
	global_load_lds_dwordx4 v[170:171], off
	v_lshl_add_u64 v[170:171], v[212:213], 0, s[60:61]
	s_mov_b32 m0, s87
	s_nop 0
	global_load_lds_dwordx4 v[170:171], off
	v_lshl_add_u64 v[170:171], v[214:215], 0, s[60:61]
	s_mov_b32 m0, s89
	s_nop 0
	global_load_lds_dwordx4 v[170:171], off
	s_waitcnt vmcnt(8) lgkmcnt(0)
	s_barrier
	v_mfma_f32_16x16x32_bf16 v[60:63], v[128:131], v[178:181], v[60:63]
	v_mfma_f32_16x16x32_bf16 v[60:63], v[132:135], v[182:185], v[60:63]
	v_mfma_f32_16x16x32_bf16 v[48:51], v[128:131], v[186:189], v[48:51]
	v_mfma_f32_16x16x32_bf16 v[48:51], v[132:135], v[190:193], v[48:51]
	v_mfma_f32_16x16x32_bf16 v[32:35], v[128:131], v[194:197], v[32:35]
	v_mfma_f32_16x16x32_bf16 v[32:35], v[132:135], v[198:201], v[32:35]
	v_mfma_f32_16x16x32_bf16 v[16:19], v[128:131], v[202:205], v[16:19]
	v_mfma_f32_16x16x32_bf16 v[16:19], v[132:135], v[206:209], v[16:19]
	v_mfma_f32_16x16x32_bf16 v[56:59], v[136:139], v[178:181], v[56:59]
	v_mfma_f32_16x16x32_bf16 v[56:59], v[140:143], v[182:185], v[56:59]
	v_mfma_f32_16x16x32_bf16 v[40:43], v[136:139], v[186:189], v[40:43]
	v_mfma_f32_16x16x32_bf16 v[40:43], v[140:143], v[190:193], v[40:43]
	v_mfma_f32_16x16x32_bf16 v[24:27], v[136:139], v[194:197], v[24:27]
	v_mfma_f32_16x16x32_bf16 v[24:27], v[140:143], v[198:201], v[24:27]
	v_mfma_f32_16x16x32_bf16 v[8:11], v[136:139], v[202:205], v[8:11]
	v_mfma_f32_16x16x32_bf16 v[8:11], v[140:143], v[206:209], v[8:11]
	v_mfma_f32_16x16x32_bf16 v[52:55], v[154:157], v[178:181], v[52:55]
	v_mfma_f32_16x16x32_bf16 v[52:55], v[158:161], v[182:185], v[52:55]
	v_mfma_f32_16x16x32_bf16 v[36:39], v[154:157], v[186:189], v[36:39]
	v_mfma_f32_16x16x32_bf16 v[36:39], v[158:161], v[190:193], v[36:39]
	v_mfma_f32_16x16x32_bf16 v[20:23], v[154:157], v[194:197], v[20:23]
	v_mfma_f32_16x16x32_bf16 v[20:23], v[158:161], v[198:201], v[20:23]
	v_mfma_f32_16x16x32_bf16 v[4:7], v[154:157], v[202:205], v[4:7]
	v_mfma_f32_16x16x32_bf16 v[4:7], v[158:161], v[206:209], v[4:7]
	v_mfma_f32_16x16x32_bf16 v[44:47], v[166:169], v[178:181], v[44:47]
	v_mfma_f32_16x16x32_bf16 v[44:47], v[174:177], v[182:185], v[44:47]
	v_mfma_f32_16x16x32_bf16 v[28:31], v[166:169], v[186:189], v[28:31]
	v_mfma_f32_16x16x32_bf16 v[28:31], v[174:177], v[190:193], v[28:31]
	v_mfma_f32_16x16x32_bf16 v[12:15], v[166:169], v[194:197], v[12:15]
	v_mfma_f32_16x16x32_bf16 v[12:15], v[174:177], v[198:201], v[12:15]
	v_mfma_f32_16x16x32_bf16 v[0:3], v[166:169], v[202:205], v[0:3]
	v_mfma_f32_16x16x32_bf16 v[0:3], v[174:177], v[206:209], v[0:3]
	s_barrier
	s_add_i32 vcc_lo, vcc_lo, 2
	s_add_u32 s90, s90, 0x100
	s_addc_u32 s91, s91, 0
	s_add_u32 s92, s92, 0x100
	s_addc_u32 s93, s93, 0
	s_cmp_gt_u32 vcc_lo, 29
	s_cbranch_scc0 .LBB0_1664

.LBB0_1930:
	s_ashr_i32 s13, s12, 31
	s_lshl_b64 s[14:15], s[12:13], 20
	s_add_u32 s14, s41, s14
	s_addc_u32 s15, s42, s15
	s_and_b64 s[16:17], s[4:5], exec
	s_cselect_b32 s13, s15, s23
	s_cselect_b32 s91, s14, s22
	s_ashr_i32 s11, s10, 31
	s_lshl_b64 s[16:17], s[10:11], 20
	s_add_u32 s16, s45, s16
	s_addc_u32 s17, s65, s17
	s_and_b64 s[54:55], s[4:5], exec
	s_cselect_b32 s11, s17, s53
	s_cselect_b32 s92, s16, s52
	s_add_u32 s22, s22, 0x80080
	s_addc_u32 s23, s23, 0
	s_add_u32 s93, s52, 0x100
	v_mov_b32_e32 v4, 0
	s_addc_u32 s94, s53, 0
	s_mov_b32 s95, -2
	s_add_u32 s52, s22, 0xfff80080
	s_addc_u32 s53, s23, -1
	s_add_i32 s58, 0, 0x10000
	s_cmp_eq_u32 s95, 28
	s_cselect_b32 s55, s13, s53
	s_cselect_b32 s54, s91, s52
	v_add_u32_e32 v138, s58, v141
	s_cselect_b32 s53, s11, s94
	s_cselect_b32 s52, s92, s93
	s_add_i32 s81, 0, 0x14000
	ds_read_b128 v[144:147], v138
	ds_read_b128 v[148:151], v138 offset:1024
	ds_read_b128 v[152:155], v138 offset:2048
	ds_read_b128 v[156:159], v138 offset:3072
	v_add_u32_e32 v138, s81, v141
	ds_read_b128 v[160:163], v138
	ds_read_b128 v[164:167], v138 offset:1024
	ds_read_b128 v[168:171], v138 offset:2048
	ds_read_b128 v[174:177], v138 offset:3072
	v_lshl_add_u64 v[138:139], s[22:23], 0, v[134:135]
	s_add_i32 m0, s76, 0xc000
	ds_read_b128 v[178:181], v143
	ds_read_b128 v[182:185], v143 offset:1024
	ds_read_b128 v[186:189], v143 offset:2048
	ds_read_b128 v[190:193], v143 offset:3072
	ds_read_b128 v[194:197], v143 offset:4096
	ds_read_b128 v[198:201], v143 offset:5120
	ds_read_b128 v[202:205], v143 offset:6144
	ds_read_b128 v[206:209], v143 offset:7168
	global_load_lds_dwordx4 v[138:139], off
	v_lshl_add_u64 v[138:139], s[22:23], 0, v[136:137]
	s_add_i32 m0, s76, 0xe000
	s_nop 0
	global_load_lds_dwordx4 v[138:139], off
	s_waitcnt vmcnt(8) lgkmcnt(0)
	s_barrier
	v_mfma_f32_16x16x32_bf16 v[120:123], v[144:147], v[178:181], 0
	v_mfma_f32_16x16x32_bf16 v[120:123], v[148:151], v[182:185], v[120:123]
	v_mfma_f32_16x16x32_bf16 v[104:107], v[144:147], v[186:189], 0
	v_mfma_f32_16x16x32_bf16 v[104:107], v[148:151], v[190:193], v[104:107]
	v_mfma_f32_16x16x32_bf16 v[88:91], v[144:147], v[194:197], 0
	v_mfma_f32_16x16x32_bf16 v[88:91], v[148:151], v[198:201], v[88:91]
	v_mfma_f32_16x16x32_bf16 v[72:75], v[144:147], v[202:205], 0
	v_mfma_f32_16x16x32_bf16 v[72:75], v[148:151], v[206:209], v[72:75]
	v_mfma_f32_16x16x32_bf16 v[112:115], v[152:155], v[178:181], 0
	v_mfma_f32_16x16x32_bf16 v[112:115], v[156:159], v[182:185], v[112:115]
	v_mfma_f32_16x16x32_bf16 v[96:99], v[152:155], v[186:189], 0
	v_mfma_f32_16x16x32_bf16 v[96:99], v[156:159], v[190:193], v[96:99]
	v_mfma_f32_16x16x32_bf16 v[80:83], v[152:155], v[194:197], 0
	v_mfma_f32_16x16x32_bf16 v[80:83], v[156:159], v[198:201], v[80:83]
	v_mfma_f32_16x16x32_bf16 v[64:67], v[152:155], v[202:205], 0
	v_mfma_f32_16x16x32_bf16 v[64:67], v[156:159], v[206:209], v[64:67]
	v_mfma_f32_16x16x32_bf16 v[124:127], v[160:163], v[178:181], 0
	v_mfma_f32_16x16x32_bf16 v[124:127], v[164:167], v[182:185], v[124:127]
	v_mfma_f32_16x16x32_bf16 v[108:111], v[160:163], v[186:189], 0
	v_mfma_f32_16x16x32_bf16 v[108:111], v[164:167], v[190:193], v[108:111]
	v_mfma_f32_16x16x32_bf16 v[92:95], v[160:163], v[194:197], 0
	v_mfma_f32_16x16x32_bf16 v[92:95], v[164:167], v[198:201], v[92:95]
	v_mfma_f32_16x16x32_bf16 v[76:79], v[160:163], v[202:205], 0
	v_mfma_f32_16x16x32_bf16 v[76:79], v[164:167], v[206:209], v[76:79]
	v_mfma_f32_16x16x32_bf16 v[116:119], v[168:171], v[178:181], 0
	v_mfma_f32_16x16x32_bf16 v[116:119], v[174:177], v[182:185], v[116:119]
	v_mfma_f32_16x16x32_bf16 v[100:103], v[168:171], v[186:189], 0
	v_mfma_f32_16x16x32_bf16 v[100:103], v[174:177], v[190:193], v[100:103]
	v_mfma_f32_16x16x32_bf16 v[84:87], v[168:171], v[194:197], 0
	v_mfma_f32_16x16x32_bf16 v[84:87], v[174:177], v[198:201], v[84:87]
	v_mfma_f32_16x16x32_bf16 v[68:71], v[168:171], v[202:205], 0
	v_mfma_f32_16x16x32_bf16 v[68:71], v[174:177], v[206:209], v[68:71]
	s_barrier
	s_add_i32 s58, s58, s50
	v_lshl_add_u64 v[138:139], s[52:53], 0, v[216:217]
	s_mov_b32 m0, s58
	ds_read_b128 v[178:181], v143 offset:16384
	ds_read_b128 v[182:185], v143 offset:17408
	ds_read_b128 v[186:189], v143 offset:18432
	ds_read_b128 v[190:193], v143 offset:19456
	ds_read_b128 v[194:197], v143 offset:20480
	ds_read_b128 v[198:201], v143 offset:21504
	ds_read_b128 v[202:205], v143 offset:22528
	ds_read_b128 v[206:209], v143 offset:23552
	global_load_lds_dwordx4 v[138:139], off
	s_add_i32 m0, s58, 0x2000
	s_add_u32 s58, s52, 0x80000
	v_lshl_add_u64 v[210:211], s[52:53], 0, v[132:133]
	s_addc_u32 s59, s53, 0
	s_add_i32 s81, s81, s50
	global_load_lds_dwordx4 v[210:211], off
	v_lshl_add_u64 v[212:213], s[58:59], 0, v[216:217]
	s_mov_b32 m0, s81
	v_lshl_add_u64 v[214:215], s[54:55], 0, v[130:131]
	global_load_lds_dwordx4 v[212:213], off
	v_lshl_add_u64 v[212:213], s[58:59], 0, v[132:133]
	s_add_i32 m0, s81, 0x2000
	s_nop 0
	global_load_lds_dwordx4 v[212:213], off
	v_lshl_add_u64 v[212:213], s[54:55], 0, v[128:129]
	s_mov_b32 m0, s76
	s_nop 0
	global_load_lds_dwordx4 v[212:213], off
	s_mov_b32 m0, s74
	s_nop 0
	global_load_lds_dwordx4 v[214:215], off
	s_waitcnt vmcnt(8) lgkmcnt(0)
	s_barrier
	v_mfma_f32_16x16x32_bf16 v[56:59], v[144:147], v[178:181], 0
	v_mfma_f32_16x16x32_bf16 v[56:59], v[148:151], v[182:185], v[56:59]
	v_mfma_f32_16x16x32_bf16 v[40:43], v[144:147], v[186:189], 0
	v_mfma_f32_16x16x32_bf16 v[40:43], v[148:151], v[190:193], v[40:43]
	v_mfma_f32_16x16x32_bf16 v[24:27], v[144:147], v[194:197], 0
	v_mfma_f32_16x16x32_bf16 v[24:27], v[148:151], v[198:201], v[24:27]
	v_mfma_f32_16x16x32_bf16 v[8:11], v[144:147], v[202:205], 0
	v_mfma_f32_16x16x32_bf16 v[8:11], v[148:151], v[206:209], v[8:11]
	v_mfma_f32_16x16x32_bf16 v[48:51], v[152:155], v[178:181], 0
	v_mfma_f32_16x16x32_bf16 v[48:51], v[156:159], v[182:185], v[48:51]
	v_mfma_f32_16x16x32_bf16 v[32:35], v[152:155], v[186:189], 0
	v_mfma_f32_16x16x32_bf16 v[32:35], v[156:159], v[190:193], v[32:35]
	v_mfma_f32_16x16x32_bf16 v[16:19], v[152:155], v[194:197], 0
	v_mfma_f32_16x16x32_bf16 v[16:19], v[156:159], v[198:201], v[16:19]
	v_mfma_f32_16x16x32_bf16 v[0:3], v[152:155], v[202:205], 0
	v_mfma_f32_16x16x32_bf16 v[0:3], v[156:159], v[206:209], v[0:3]
	v_mfma_f32_16x16x32_bf16 v[60:63], v[160:163], v[178:181], 0
	v_mfma_f32_16x16x32_bf16 v[60:63], v[164:167], v[182:185], v[60:63]
	v_mfma_f32_16x16x32_bf16 v[44:47], v[160:163], v[186:189], 0
	v_mfma_f32_16x16x32_bf16 v[44:47], v[164:167], v[190:193], v[44:47]
	v_mfma_f32_16x16x32_bf16 v[28:31], v[160:163], v[194:197], 0
	v_mfma_f32_16x16x32_bf16 v[28:31], v[164:167], v[198:201], v[28:31]
	v_mfma_f32_16x16x32_bf16 v[12:15], v[160:163], v[202:205], 0
	v_mfma_f32_16x16x32_bf16 v[12:15], v[164:167], v[206:209], v[12:15]
	v_mfma_f32_16x16x32_bf16 v[52:55], v[168:171], v[178:181], 0
	v_mfma_f32_16x16x32_bf16 v[52:55], v[174:177], v[182:185], v[52:55]
	v_mfma_f32_16x16x32_bf16 v[36:39], v[168:171], v[186:189], 0
	v_mfma_f32_16x16x32_bf16 v[36:39], v[174:177], v[190:193], v[36:39]
	v_mfma_f32_16x16x32_bf16 v[20:23], v[168:171], v[194:197], 0
	v_mfma_f32_16x16x32_bf16 v[20:23], v[174:177], v[198:201], v[20:23]
	v_mfma_f32_16x16x32_bf16 v[4:7], v[168:171], v[202:205], 0
	v_mfma_f32_16x16x32_bf16 v[4:7], v[174:177], v[206:209], v[4:7]
	s_barrier
	s_add_i32 s58, 0, 0x18000
	s_add_i32 s59, 0, 0x1c000
	v_add_u32_e32 v156, s58, v141
	v_add_u32_e32 v173, s59, v141
	ds_read_b128 v[144:147], v156
	ds_read_b128 v[148:151], v156 offset:1024
	ds_read_b128 v[152:155], v156 offset:2048
	ds_read_b128 v[156:159], v156 offset:3072
	ds_read_b128 v[160:163], v173
	ds_read_b128 v[164:167], v173 offset:1024
	ds_read_b128 v[168:171], v173 offset:2048
	ds_read_b128 v[174:177], v173 offset:3072
	s_add_u32 s54, s54, 0x80000
	s_addc_u32 s55, s55, 0
	s_mov_b32 m0, s85
	v_lshl_add_u64 v[218:219], s[54:55], 0, v[128:129]
	ds_read_b128 v[178:181], v143 offset:32768
	ds_read_b128 v[182:185], v143 offset:33792
	ds_read_b128 v[186:189], v143 offset:34816
	ds_read_b128 v[190:193], v143 offset:35840
	ds_read_b128 v[194:197], v143 offset:36864
	ds_read_b128 v[198:201], v143 offset:37888
	ds_read_b128 v[202:205], v143 offset:38912
	ds_read_b128 v[206:209], v143 offset:39936
	global_load_lds_dwordx4 v[218:219], off
	v_lshl_add_u64 v[218:219], s[54:55], 0, v[130:131]
	s_mov_b32 m0, s86
	s_nop 0
	global_load_lds_dwordx4 v[218:219], off
	s_waitcnt vmcnt(8) lgkmcnt(0)
	s_barrier
	v_mfma_f32_16x16x32_bf16 v[120:123], v[144:147], v[178:181], v[120:123]
	v_mfma_f32_16x16x32_bf16 v[120:123], v[148:151], v[182:185], v[120:123]
	v_mfma_f32_16x16x32_bf16 v[104:107], v[144:147], v[186:189], v[104:107]
	v_mfma_f32_16x16x32_bf16 v[104:107], v[148:151], v[190:193], v[104:107]
	v_mfma_f32_16x16x32_bf16 v[88:91], v[144:147], v[194:197], v[88:91]
	v_mfma_f32_16x16x32_bf16 v[88:91], v[148:151], v[198:201], v[88:91]
	v_mfma_f32_16x16x32_bf16 v[72:75], v[144:147], v[202:205], v[72:75]
	v_mfma_f32_16x16x32_bf16 v[72:75], v[148:151], v[206:209], v[72:75]
	v_mfma_f32_16x16x32_bf16 v[112:115], v[152:155], v[178:181], v[112:115]
	v_mfma_f32_16x16x32_bf16 v[112:115], v[156:159], v[182:185], v[112:115]
	v_mfma_f32_16x16x32_bf16 v[96:99], v[152:155], v[186:189], v[96:99]
	v_mfma_f32_16x16x32_bf16 v[96:99], v[156:159], v[190:193], v[96:99]
	v_mfma_f32_16x16x32_bf16 v[80:83], v[152:155], v[194:197], v[80:83]
	v_mfma_f32_16x16x32_bf16 v[80:83], v[156:159], v[198:201], v[80:83]
	v_mfma_f32_16x16x32_bf16 v[64:67], v[152:155], v[202:205], v[64:67]
	v_mfma_f32_16x16x32_bf16 v[64:67], v[156:159], v[206:209], v[64:67]
	v_mfma_f32_16x16x32_bf16 v[124:127], v[160:163], v[178:181], v[124:127]
	v_mfma_f32_16x16x32_bf16 v[124:127], v[164:167], v[182:185], v[124:127]
	v_mfma_f32_16x16x32_bf16 v[108:111], v[160:163], v[186:189], v[108:111]
	v_mfma_f32_16x16x32_bf16 v[108:111], v[164:167], v[190:193], v[108:111]
	v_mfma_f32_16x16x32_bf16 v[92:95], v[160:163], v[194:197], v[92:95]
	v_mfma_f32_16x16x32_bf16 v[92:95], v[164:167], v[198:201], v[92:95]
	v_mfma_f32_16x16x32_bf16 v[76:79], v[160:163], v[202:205], v[76:79]
	v_mfma_f32_16x16x32_bf16 v[76:79], v[164:167], v[206:209], v[76:79]
	v_mfma_f32_16x16x32_bf16 v[116:119], v[168:171], v[178:181], v[116:119]
	v_mfma_f32_16x16x32_bf16 v[116:119], v[174:177], v[182:185], v[116:119]
	v_mfma_f32_16x16x32_bf16 v[100:103], v[168:171], v[186:189], v[100:103]
	v_mfma_f32_16x16x32_bf16 v[100:103], v[174:177], v[190:193], v[100:103]
	v_mfma_f32_16x16x32_bf16 v[84:87], v[168:171], v[194:197], v[84:87]
	v_mfma_f32_16x16x32_bf16 v[84:87], v[174:177], v[198:201], v[84:87]
	v_mfma_f32_16x16x32_bf16 v[68:71], v[168:171], v[202:205], v[68:71]
	v_mfma_f32_16x16x32_bf16 v[68:71], v[174:177], v[206:209], v[68:71]
	s_barrier
	s_add_i32 s54, s58, s50
	v_lshl_add_u64 v[138:139], v[138:139], 0, s[60:61]
	s_mov_b32 m0, s54
	ds_read_b128 v[178:181], v143 offset:49152
	ds_read_b128 v[182:185], v143 offset:50176
	ds_read_b128 v[186:189], v143 offset:51200
	ds_read_b128 v[190:193], v143 offset:52224
	ds_read_b128 v[194:197], v143 offset:53248
	ds_read_b128 v[198:201], v143 offset:54272
	ds_read_b128 v[202:205], v143 offset:55296
	ds_read_b128 v[206:209], v143 offset:56320
	global_load_lds_dwordx4 v[138:139], off
	s_add_i32 m0, s54, 0x2000
	s_add_u32 s52, s52, 0x80080
	v_lshl_add_u64 v[138:139], v[210:211], 0, s[60:61]
	s_addc_u32 s53, s53, 0
	s_add_i32 s54, s59, s50
	global_load_lds_dwordx4 v[138:139], off
	v_lshl_add_u64 v[138:139], s[52:53], 0, v[216:217]
	s_mov_b32 m0, s54
	s_nop 0
	global_load_lds_dwordx4 v[138:139], off
	v_lshl_add_u64 v[138:139], s[52:53], 0, v[132:133]
	s_add_i32 m0, s54, 0x2000
	s_nop 0
	global_load_lds_dwordx4 v[138:139], off
	v_lshl_add_u64 v[138:139], v[212:213], 0, s[60:61]
	s_mov_b32 m0, s87
	s_nop 0
	global_load_lds_dwordx4 v[138:139], off
	v_lshl_add_u64 v[138:139], v[214:215], 0, s[60:61]
	s_mov_b32 m0, s88
	s_nop 0
	global_load_lds_dwordx4 v[138:139], off
	s_waitcnt vmcnt(8) lgkmcnt(0)
	s_barrier
	v_mfma_f32_16x16x32_bf16 v[56:59], v[144:147], v[178:181], v[56:59]
	v_mfma_f32_16x16x32_bf16 v[56:59], v[148:151], v[182:185], v[56:59]
	v_mfma_f32_16x16x32_bf16 v[40:43], v[144:147], v[186:189], v[40:43]
	v_mfma_f32_16x16x32_bf16 v[40:43], v[148:151], v[190:193], v[40:43]
	v_mfma_f32_16x16x32_bf16 v[24:27], v[144:147], v[194:197], v[24:27]
	v_mfma_f32_16x16x32_bf16 v[24:27], v[148:151], v[198:201], v[24:27]
	v_mfma_f32_16x16x32_bf16 v[8:11], v[144:147], v[202:205], v[8:11]
	v_mfma_f32_16x16x32_bf16 v[8:11], v[148:151], v[206:209], v[8:11]
	v_mfma_f32_16x16x32_bf16 v[48:51], v[152:155], v[178:181], v[48:51]
	v_mfma_f32_16x16x32_bf16 v[48:51], v[156:159], v[182:185], v[48:51]
	v_mfma_f32_16x16x32_bf16 v[32:35], v[152:155], v[186:189], v[32:35]
	v_mfma_f32_16x16x32_bf16 v[32:35], v[156:159], v[190:193], v[32:35]
	v_mfma_f32_16x16x32_bf16 v[16:19], v[152:155], v[194:197], v[16:19]
	v_mfma_f32_16x16x32_bf16 v[16:19], v[156:159], v[198:201], v[16:19]
	v_mfma_f32_16x16x32_bf16 v[0:3], v[152:155], v[202:205], v[0:3]
	v_mfma_f32_16x16x32_bf16 v[0:3], v[156:159], v[206:209], v[0:3]
	v_mfma_f32_16x16x32_bf16 v[60:63], v[160:163], v[178:181], v[60:63]
	v_mfma_f32_16x16x32_bf16 v[60:63], v[164:167], v[182:185], v[60:63]
	v_mfma_f32_16x16x32_bf16 v[44:47], v[160:163], v[186:189], v[44:47]
	v_mfma_f32_16x16x32_bf16 v[44:47], v[164:167], v[190:193], v[44:47]
	v_mfma_f32_16x16x32_bf16 v[28:31], v[160:163], v[194:197], v[28:31]
	v_mfma_f32_16x16x32_bf16 v[28:31], v[164:167], v[198:201], v[28:31]
	v_mfma_f32_16x16x32_bf16 v[12:15], v[160:163], v[202:205], v[12:15]
	v_mfma_f32_16x16x32_bf16 v[12:15], v[164:167], v[206:209], v[12:15]
	v_mfma_f32_16x16x32_bf16 v[52:55], v[168:171], v[178:181], v[52:55]
	v_mfma_f32_16x16x32_bf16 v[52:55], v[174:177], v[182:185], v[52:55]
	v_mfma_f32_16x16x32_bf16 v[36:39], v[168:171], v[186:189], v[36:39]
	v_mfma_f32_16x16x32_bf16 v[36:39], v[174:177], v[190:193], v[36:39]
	v_mfma_f32_16x16x32_bf16 v[20:23], v[168:171], v[194:197], v[20:23]
	v_mfma_f32_16x16x32_bf16 v[20:23], v[174:177], v[198:201], v[20:23]
	v_mfma_f32_16x16x32_bf16 v[4:7], v[168:171], v[202:205], v[4:7]
	v_mfma_f32_16x16x32_bf16 v[4:7], v[174:177], v[206:209], v[4:7]
	s_barrier
	s_add_i32 s95, s95, 2
	s_add_u32 s22, s22, 0x100
	s_addc_u32 s23, s23, 0
	s_add_u32 s93, s93, 0x100
	s_addc_u32 s94, s94, 0
	s_cmp_gt_u32 s95, 29
	s_cbranch_scc0 .LBB0_1931
	s_branch .Lzexit_6
.LBB0_1931:
	s_add_u32 s52, s22, 0xfff80080
	s_addc_u32 s53, s23, -1
	s_add_i32 s58, 0, 0x10000
	s_cmp_eq_u32 s95, 28
	s_cselect_b32 s55, s13, s53
	s_cselect_b32 s54, s91, s52
	v_add_u32_e32 v138, s58, v141
	s_cselect_b32 s53, s11, s94
	s_cselect_b32 s52, s92, s93
	s_add_i32 s81, 0, 0x14000
	ds_read_b128 v[144:147], v138
	ds_read_b128 v[148:151], v138 offset:1024
	ds_read_b128 v[152:155], v138 offset:2048
	ds_read_b128 v[156:159], v138 offset:3072
	v_add_u32_e32 v138, s81, v141
	ds_read_b128 v[160:163], v138
	ds_read_b128 v[164:167], v138 offset:1024
	ds_read_b128 v[168:171], v138 offset:2048
	ds_read_b128 v[174:177], v138 offset:3072
	v_lshl_add_u64 v[138:139], s[22:23], 0, v[134:135]
	s_add_i32 m0, s76, 0xc000
	ds_read_b128 v[178:181], v143
	ds_read_b128 v[182:185], v143 offset:1024
	ds_read_b128 v[186:189], v143 offset:2048
	ds_read_b128 v[190:193], v143 offset:3072
	ds_read_b128 v[194:197], v143 offset:4096
	ds_read_b128 v[198:201], v143 offset:5120
	ds_read_b128 v[202:205], v143 offset:6144
	ds_read_b128 v[206:209], v143 offset:7168
	global_load_lds_dwordx4 v[138:139], off
	v_lshl_add_u64 v[138:139], s[22:23], 0, v[136:137]
	s_add_i32 m0, s76, 0xe000
	s_nop 0
	global_load_lds_dwordx4 v[138:139], off
	s_waitcnt vmcnt(8) lgkmcnt(0)
	s_barrier
	v_mfma_f32_16x16x32_bf16 v[120:123], v[144:147], v[178:181], v[120:123]
	v_mfma_f32_16x16x32_bf16 v[120:123], v[148:151], v[182:185], v[120:123]
	v_mfma_f32_16x16x32_bf16 v[104:107], v[144:147], v[186:189], v[104:107]
	v_mfma_f32_16x16x32_bf16 v[104:107], v[148:151], v[190:193], v[104:107]
	v_mfma_f32_16x16x32_bf16 v[88:91], v[144:147], v[194:197], v[88:91]
	v_mfma_f32_16x16x32_bf16 v[88:91], v[148:151], v[198:201], v[88:91]
	v_mfma_f32_16x16x32_bf16 v[72:75], v[144:147], v[202:205], v[72:75]
	v_mfma_f32_16x16x32_bf16 v[72:75], v[148:151], v[206:209], v[72:75]
	v_mfma_f32_16x16x32_bf16 v[112:115], v[152:155], v[178:181], v[112:115]
	v_mfma_f32_16x16x32_bf16 v[112:115], v[156:159], v[182:185], v[112:115]
	v_mfma_f32_16x16x32_bf16 v[96:99], v[152:155], v[186:189], v[96:99]
	v_mfma_f32_16x16x32_bf16 v[96:99], v[156:159], v[190:193], v[96:99]
	v_mfma_f32_16x16x32_bf16 v[80:83], v[152:155], v[194:197], v[80:83]
	v_mfma_f32_16x16x32_bf16 v[80:83], v[156:159], v[198:201], v[80:83]
	v_mfma_f32_16x16x32_bf16 v[64:67], v[152:155], v[202:205], v[64:67]
	v_mfma_f32_16x16x32_bf16 v[64:67], v[156:159], v[206:209], v[64:67]
	v_mfma_f32_16x16x32_bf16 v[124:127], v[160:163], v[178:181], v[124:127]
	v_mfma_f32_16x16x32_bf16 v[124:127], v[164:167], v[182:185], v[124:127]
	v_mfma_f32_16x16x32_bf16 v[108:111], v[160:163], v[186:189], v[108:111]
	v_mfma_f32_16x16x32_bf16 v[108:111], v[164:167], v[190:193], v[108:111]
	v_mfma_f32_16x16x32_bf16 v[92:95], v[160:163], v[194:197], v[92:95]
	v_mfma_f32_16x16x32_bf16 v[92:95], v[164:167], v[198:201], v[92:95]
	v_mfma_f32_16x16x32_bf16 v[76:79], v[160:163], v[202:205], v[76:79]
	v_mfma_f32_16x16x32_bf16 v[76:79], v[164:167], v[206:209], v[76:79]
	v_mfma_f32_16x16x32_bf16 v[116:119], v[168:171], v[178:181], v[116:119]
	v_mfma_f32_16x16x32_bf16 v[116:119], v[174:177], v[182:185], v[116:119]
	v_mfma_f32_16x16x32_bf16 v[100:103], v[168:171], v[186:189], v[100:103]
	v_mfma_f32_16x16x32_bf16 v[100:103], v[174:177], v[190:193], v[100:103]
	v_mfma_f32_16x16x32_bf16 v[84:87], v[168:171], v[194:197], v[84:87]
	v_mfma_f32_16x16x32_bf16 v[84:87], v[174:177], v[198:201], v[84:87]
	v_mfma_f32_16x16x32_bf16 v[68:71], v[168:171], v[202:205], v[68:71]
	v_mfma_f32_16x16x32_bf16 v[68:71], v[174:177], v[206:209], v[68:71]
	s_barrier
	s_add_i32 s58, s58, s50
	v_lshl_add_u64 v[138:139], s[52:53], 0, v[216:217]
	s_mov_b32 m0, s58
	ds_read_b128 v[178:181], v143 offset:16384
	ds_read_b128 v[182:185], v143 offset:17408
	ds_read_b128 v[186:189], v143 offset:18432
	ds_read_b128 v[190:193], v143 offset:19456
	ds_read_b128 v[194:197], v143 offset:20480
	ds_read_b128 v[198:201], v143 offset:21504
	ds_read_b128 v[202:205], v143 offset:22528
	ds_read_b128 v[206:209], v143 offset:23552
	global_load_lds_dwordx4 v[138:139], off
	s_add_i32 m0, s58, 0x2000
	s_add_u32 s58, s52, 0x80000
	v_lshl_add_u64 v[210:211], s[52:53], 0, v[132:133]
	s_addc_u32 s59, s53, 0
	s_add_i32 s81, s81, s50
	global_load_lds_dwordx4 v[210:211], off
	v_lshl_add_u64 v[212:213], s[58:59], 0, v[216:217]
	s_mov_b32 m0, s81
	v_lshl_add_u64 v[214:215], s[54:55], 0, v[130:131]
	global_load_lds_dwordx4 v[212:213], off
	v_lshl_add_u64 v[212:213], s[58:59], 0, v[132:133]
	s_add_i32 m0, s81, 0x2000
	s_nop 0
	global_load_lds_dwordx4 v[212:213], off
	v_lshl_add_u64 v[212:213], s[54:55], 0, v[128:129]
	s_mov_b32 m0, s76
	s_nop 0
	global_load_lds_dwordx4 v[212:213], off
	s_mov_b32 m0, s74
	s_nop 0
	global_load_lds_dwordx4 v[214:215], off
	s_waitcnt vmcnt(8) lgkmcnt(0)
	s_barrier
	v_mfma_f32_16x16x32_bf16 v[56:59], v[144:147], v[178:181], v[56:59]
	v_mfma_f32_16x16x32_bf16 v[56:59], v[148:151], v[182:185], v[56:59]
	v_mfma_f32_16x16x32_bf16 v[40:43], v[144:147], v[186:189], v[40:43]
	v_mfma_f32_16x16x32_bf16 v[40:43], v[148:151], v[190:193], v[40:43]
	v_mfma_f32_16x16x32_bf16 v[24:27], v[144:147], v[194:197], v[24:27]
	v_mfma_f32_16x16x32_bf16 v[24:27], v[148:151], v[198:201], v[24:27]
	v_mfma_f32_16x16x32_bf16 v[8:11], v[144:147], v[202:205], v[8:11]
	v_mfma_f32_16x16x32_bf16 v[8:11], v[148:151], v[206:209], v[8:11]
	v_mfma_f32_16x16x32_bf16 v[48:51], v[152:155], v[178:181], v[48:51]
	v_mfma_f32_16x16x32_bf16 v[48:51], v[156:159], v[182:185], v[48:51]
	v_mfma_f32_16x16x32_bf16 v[32:35], v[152:155], v[186:189], v[32:35]
	v_mfma_f32_16x16x32_bf16 v[32:35], v[156:159], v[190:193], v[32:35]
	v_mfma_f32_16x16x32_bf16 v[16:19], v[152:155], v[194:197], v[16:19]
	v_mfma_f32_16x16x32_bf16 v[16:19], v[156:159], v[198:201], v[16:19]
	v_mfma_f32_16x16x32_bf16 v[0:3], v[152:155], v[202:205], v[0:3]
	v_mfma_f32_16x16x32_bf16 v[0:3], v[156:159], v[206:209], v[0:3]
	v_mfma_f32_16x16x32_bf16 v[60:63], v[160:163], v[178:181], v[60:63]
	v_mfma_f32_16x16x32_bf16 v[60:63], v[164:167], v[182:185], v[60:63]
	v_mfma_f32_16x16x32_bf16 v[44:47], v[160:163], v[186:189], v[44:47]
	v_mfma_f32_16x16x32_bf16 v[44:47], v[164:167], v[190:193], v[44:47]
	v_mfma_f32_16x16x32_bf16 v[28:31], v[160:163], v[194:197], v[28:31]
	v_mfma_f32_16x16x32_bf16 v[28:31], v[164:167], v[198:201], v[28:31]
	v_mfma_f32_16x16x32_bf16 v[12:15], v[160:163], v[202:205], v[12:15]
	v_mfma_f32_16x16x32_bf16 v[12:15], v[164:167], v[206:209], v[12:15]
	v_mfma_f32_16x16x32_bf16 v[52:55], v[168:171], v[178:181], v[52:55]
	v_mfma_f32_16x16x32_bf16 v[52:55], v[174:177], v[182:185], v[52:55]
	v_mfma_f32_16x16x32_bf16 v[36:39], v[168:171], v[186:189], v[36:39]
	v_mfma_f32_16x16x32_bf16 v[36:39], v[174:177], v[190:193], v[36:39]
	v_mfma_f32_16x16x32_bf16 v[20:23], v[168:171], v[194:197], v[20:23]
	v_mfma_f32_16x16x32_bf16 v[20:23], v[174:177], v[198:201], v[20:23]
	v_mfma_f32_16x16x32_bf16 v[4:7], v[168:171], v[202:205], v[4:7]
	v_mfma_f32_16x16x32_bf16 v[4:7], v[174:177], v[206:209], v[4:7]
	s_barrier
	s_add_i32 s58, 0, 0x18000
	s_add_i32 s59, 0, 0x1c000
	v_add_u32_e32 v156, s58, v141
	v_add_u32_e32 v173, s59, v141
	ds_read_b128 v[144:147], v156
	ds_read_b128 v[148:151], v156 offset:1024
	ds_read_b128 v[152:155], v156 offset:2048
	ds_read_b128 v[156:159], v156 offset:3072
	ds_read_b128 v[160:163], v173
	ds_read_b128 v[164:167], v173 offset:1024
	ds_read_b128 v[168:171], v173 offset:2048
	ds_read_b128 v[174:177], v173 offset:3072
	s_add_u32 s54, s54, 0x80000
	s_addc_u32 s55, s55, 0
	s_mov_b32 m0, s85
	v_lshl_add_u64 v[218:219], s[54:55], 0, v[128:129]
	ds_read_b128 v[178:181], v143 offset:32768
	ds_read_b128 v[182:185], v143 offset:33792
	ds_read_b128 v[186:189], v143 offset:34816
	ds_read_b128 v[190:193], v143 offset:35840
	ds_read_b128 v[194:197], v143 offset:36864
	ds_read_b128 v[198:201], v143 offset:37888
	ds_read_b128 v[202:205], v143 offset:38912
	ds_read_b128 v[206:209], v143 offset:39936
	global_load_lds_dwordx4 v[218:219], off
	v_lshl_add_u64 v[218:219], s[54:55], 0, v[130:131]
	s_mov_b32 m0, s86
	s_nop 0
	global_load_lds_dwordx4 v[218:219], off
	s_waitcnt vmcnt(8) lgkmcnt(0)
	s_barrier
	v_mfma_f32_16x16x32_bf16 v[120:123], v[144:147], v[178:181], v[120:123]
	v_mfma_f32_16x16x32_bf16 v[120:123], v[148:151], v[182:185], v[120:123]
	v_mfma_f32_16x16x32_bf16 v[104:107], v[144:147], v[186:189], v[104:107]
	v_mfma_f32_16x16x32_bf16 v[104:107], v[148:151], v[190:193], v[104:107]
	v_mfma_f32_16x16x32_bf16 v[88:91], v[144:147], v[194:197], v[88:91]
	v_mfma_f32_16x16x32_bf16 v[88:91], v[148:151], v[198:201], v[88:91]
	v_mfma_f32_16x16x32_bf16 v[72:75], v[144:147], v[202:205], v[72:75]
	v_mfma_f32_16x16x32_bf16 v[72:75], v[148:151], v[206:209], v[72:75]
	v_mfma_f32_16x16x32_bf16 v[112:115], v[152:155], v[178:181], v[112:115]
	v_mfma_f32_16x16x32_bf16 v[112:115], v[156:159], v[182:185], v[112:115]
	v_mfma_f32_16x16x32_bf16 v[96:99], v[152:155], v[186:189], v[96:99]
	v_mfma_f32_16x16x32_bf16 v[96:99], v[156:159], v[190:193], v[96:99]
	v_mfma_f32_16x16x32_bf16 v[80:83], v[152:155], v[194:197], v[80:83]
	v_mfma_f32_16x16x32_bf16 v[80:83], v[156:159], v[198:201], v[80:83]
	v_mfma_f32_16x16x32_bf16 v[64:67], v[152:155], v[202:205], v[64:67]
	v_mfma_f32_16x16x32_bf16 v[64:67], v[156:159], v[206:209], v[64:67]
	v_mfma_f32_16x16x32_bf16 v[124:127], v[160:163], v[178:181], v[124:127]
	v_mfma_f32_16x16x32_bf16 v[124:127], v[164:167], v[182:185], v[124:127]
	v_mfma_f32_16x16x32_bf16 v[108:111], v[160:163], v[186:189], v[108:111]
	v_mfma_f32_16x16x32_bf16 v[108:111], v[164:167], v[190:193], v[108:111]
	v_mfma_f32_16x16x32_bf16 v[92:95], v[160:163], v[194:197], v[92:95]
	v_mfma_f32_16x16x32_bf16 v[92:95], v[164:167], v[198:201], v[92:95]
	v_mfma_f32_16x16x32_bf16 v[76:79], v[160:163], v[202:205], v[76:79]
	v_mfma_f32_16x16x32_bf16 v[76:79], v[164:167], v[206:209], v[76:79]
	v_mfma_f32_16x16x32_bf16 v[116:119], v[168:171], v[178:181], v[116:119]
	v_mfma_f32_16x16x32_bf16 v[116:119], v[174:177], v[182:185], v[116:119]
	v_mfma_f32_16x16x32_bf16 v[100:103], v[168:171], v[186:189], v[100:103]
	v_mfma_f32_16x16x32_bf16 v[100:103], v[174:177], v[190:193], v[100:103]
	v_mfma_f32_16x16x32_bf16 v[84:87], v[168:171], v[194:197], v[84:87]
	v_mfma_f32_16x16x32_bf16 v[84:87], v[174:177], v[198:201], v[84:87]
	v_mfma_f32_16x16x32_bf16 v[68:71], v[168:171], v[202:205], v[68:71]
	v_mfma_f32_16x16x32_bf16 v[68:71], v[174:177], v[206:209], v[68:71]
	s_barrier
	s_add_i32 s54, s58, s50
	v_lshl_add_u64 v[138:139], v[138:139], 0, s[60:61]
	s_mov_b32 m0, s54
	ds_read_b128 v[178:181], v143 offset:49152
	ds_read_b128 v[182:185], v143 offset:50176
	ds_read_b128 v[186:189], v143 offset:51200
	ds_read_b128 v[190:193], v143 offset:52224
	ds_read_b128 v[194:197], v143 offset:53248
	ds_read_b128 v[198:201], v143 offset:54272
	ds_read_b128 v[202:205], v143 offset:55296
	ds_read_b128 v[206:209], v143 offset:56320
	global_load_lds_dwordx4 v[138:139], off
	s_add_i32 m0, s54, 0x2000
	s_add_u32 s52, s52, 0x80080
	v_lshl_add_u64 v[138:139], v[210:211], 0, s[60:61]
	s_addc_u32 s53, s53, 0
	s_add_i32 s54, s59, s50
	global_load_lds_dwordx4 v[138:139], off
	v_lshl_add_u64 v[138:139], s[52:53], 0, v[216:217]
	s_mov_b32 m0, s54
	s_nop 0
	global_load_lds_dwordx4 v[138:139], off
	v_lshl_add_u64 v[138:139], s[52:53], 0, v[132:133]
	s_add_i32 m0, s54, 0x2000
	s_nop 0
	global_load_lds_dwordx4 v[138:139], off
	v_lshl_add_u64 v[138:139], v[212:213], 0, s[60:61]
	s_mov_b32 m0, s87
	s_nop 0
	global_load_lds_dwordx4 v[138:139], off
	v_lshl_add_u64 v[138:139], v[214:215], 0, s[60:61]
	s_mov_b32 m0, s88
	s_nop 0
	global_load_lds_dwordx4 v[138:139], off
	s_waitcnt vmcnt(8) lgkmcnt(0)
	s_barrier
	v_mfma_f32_16x16x32_bf16 v[56:59], v[144:147], v[178:181], v[56:59]
	v_mfma_f32_16x16x32_bf16 v[56:59], v[148:151], v[182:185], v[56:59]
	v_mfma_f32_16x16x32_bf16 v[40:43], v[144:147], v[186:189], v[40:43]
	v_mfma_f32_16x16x32_bf16 v[40:43], v[148:151], v[190:193], v[40:43]
	v_mfma_f32_16x16x32_bf16 v[24:27], v[144:147], v[194:197], v[24:27]
	v_mfma_f32_16x16x32_bf16 v[24:27], v[148:151], v[198:201], v[24:27]
	v_mfma_f32_16x16x32_bf16 v[8:11], v[144:147], v[202:205], v[8:11]
	v_mfma_f32_16x16x32_bf16 v[8:11], v[148:151], v[206:209], v[8:11]
	v_mfma_f32_16x16x32_bf16 v[48:51], v[152:155], v[178:181], v[48:51]
	v_mfma_f32_16x16x32_bf16 v[48:51], v[156:159], v[182:185], v[48:51]
	v_mfma_f32_16x16x32_bf16 v[32:35], v[152:155], v[186:189], v[32:35]
	v_mfma_f32_16x16x32_bf16 v[32:35], v[156:159], v[190:193], v[32:35]
	v_mfma_f32_16x16x32_bf16 v[16:19], v[152:155], v[194:197], v[16:19]
	v_mfma_f32_16x16x32_bf16 v[16:19], v[156:159], v[198:201], v[16:19]
	v_mfma_f32_16x16x32_bf16 v[0:3], v[152:155], v[202:205], v[0:3]
	v_mfma_f32_16x16x32_bf16 v[0:3], v[156:159], v[206:209], v[0:3]
	v_mfma_f32_16x16x32_bf16 v[60:63], v[160:163], v[178:181], v[60:63]
	v_mfma_f32_16x16x32_bf16 v[60:63], v[164:167], v[182:185], v[60:63]
	v_mfma_f32_16x16x32_bf16 v[44:47], v[160:163], v[186:189], v[44:47]
	v_mfma_f32_16x16x32_bf16 v[44:47], v[164:167], v[190:193], v[44:47]
	v_mfma_f32_16x16x32_bf16 v[28:31], v[160:163], v[194:197], v[28:31]
	v_mfma_f32_16x16x32_bf16 v[28:31], v[164:167], v[198:201], v[28:31]
	v_mfma_f32_16x16x32_bf16 v[12:15], v[160:163], v[202:205], v[12:15]
	v_mfma_f32_16x16x32_bf16 v[12:15], v[164:167], v[206:209], v[12:15]
	v_mfma_f32_16x16x32_bf16 v[52:55], v[168:171], v[178:181], v[52:55]
	v_mfma_f32_16x16x32_bf16 v[52:55], v[174:177], v[182:185], v[52:55]
	v_mfma_f32_16x16x32_bf16 v[36:39], v[168:171], v[186:189], v[36:39]
	v_mfma_f32_16x16x32_bf16 v[36:39], v[174:177], v[190:193], v[36:39]
	v_mfma_f32_16x16x32_bf16 v[20:23], v[168:171], v[194:197], v[20:23]
	v_mfma_f32_16x16x32_bf16 v[20:23], v[174:177], v[198:201], v[20:23]
	v_mfma_f32_16x16x32_bf16 v[4:7], v[168:171], v[202:205], v[4:7]
	v_mfma_f32_16x16x32_bf16 v[4:7], v[174:177], v[206:209], v[4:7]
	s_barrier
	s_add_i32 s95, s95, 2
	s_add_u32 s22, s22, 0x100
	s_addc_u32 s23, s23, 0
	s_add_u32 s93, s93, 0x100
	s_addc_u32 s94, s94, 0
	s_cmp_gt_u32 s95, 29
	s_cbranch_scc0 .LBB0_1931

.LBB0_2080:
	s_add_u32 s93, s22, 0x100
	v_mov_b32_e32 v0, 0
	s_addc_u32 s94, s23, 0
	s_mov_b32 s95, -2
	s_add_u32 s22, s18, 0x100
	s_addc_u32 s23, s19, 0
	s_add_i32 s58, 0, 0x10000
	s_cmpk_eq_i32 s95, 0x54
	s_cselect_b32 s55, s7, s23
	s_cselect_b32 s54, s6, s22
	s_cselect_b32 s53, s17, s94
	s_cselect_b32 s52, s16, s93
	s_add_i32 s59, 0, 0x14000
	v_add_u32_e32 v140, s58, v195
	v_add_u32_e32 v166, s59, v195
	ds_read_b128 v[128:131], v140
	ds_read_b128 v[132:135], v140 offset:1024
	ds_read_b128 v[136:139], v140 offset:2048
	ds_read_b128 v[140:143], v140 offset:3072
	ds_read_b128 v[144:147], v166
	ds_read_b128 v[148:151], v166 offset:1024
	ds_read_b128 v[152:155], v166 offset:2048
	ds_read_b128 v[166:169], v166 offset:3072
	v_lshl_add_u64 v[206:207], s[18:19], 0, v[162:163]
	s_add_i32 m0, s76, 0xc000
	ds_read_b128 v[170:173], v197
	ds_read_b128 v[174:177], v197 offset:1024
	ds_read_b128 v[178:181], v197 offset:2048
	ds_read_b128 v[182:185], v197 offset:3072
	ds_read_b128 v[186:189], v197 offset:4096
	ds_read_b128 v[190:193], v197 offset:5120
	ds_read_b128 v[198:201], v197 offset:6144
	ds_read_b128 v[202:205], v197 offset:7168
	global_load_lds_dwordx4 v[206:207], off
	v_lshl_add_u64 v[206:207], s[18:19], 0, v[164:165]
	s_add_i32 m0, s76, 0xe000
	s_nop 0
	global_load_lds_dwordx4 v[206:207], off
	s_waitcnt vmcnt(8) lgkmcnt(0)
	s_barrier
	v_mfma_f32_16x16x32_bf16 v[124:127], v[128:131], v[170:173], 0
	v_mfma_f32_16x16x32_bf16 v[124:127], v[132:135], v[174:177], v[124:127]
	v_mfma_f32_16x16x32_bf16 v[108:111], v[128:131], v[178:181], 0
	v_mfma_f32_16x16x32_bf16 v[108:111], v[132:135], v[182:185], v[108:111]
	v_mfma_f32_16x16x32_bf16 v[92:95], v[128:131], v[186:189], 0
	v_mfma_f32_16x16x32_bf16 v[92:95], v[132:135], v[190:193], v[92:95]
	v_mfma_f32_16x16x32_bf16 v[76:79], v[128:131], v[198:201], 0
	v_mfma_f32_16x16x32_bf16 v[76:79], v[132:135], v[202:205], v[76:79]
	v_mfma_f32_16x16x32_bf16 v[120:123], v[136:139], v[170:173], 0
	v_mfma_f32_16x16x32_bf16 v[120:123], v[140:143], v[174:177], v[120:123]
	v_mfma_f32_16x16x32_bf16 v[104:107], v[136:139], v[178:181], 0
	v_mfma_f32_16x16x32_bf16 v[104:107], v[140:143], v[182:185], v[104:107]
	v_mfma_f32_16x16x32_bf16 v[88:91], v[136:139], v[186:189], 0
	v_mfma_f32_16x16x32_bf16 v[88:91], v[140:143], v[190:193], v[88:91]
	v_mfma_f32_16x16x32_bf16 v[72:75], v[136:139], v[198:201], 0
	v_mfma_f32_16x16x32_bf16 v[72:75], v[140:143], v[202:205], v[72:75]
	v_mfma_f32_16x16x32_bf16 v[116:119], v[144:147], v[170:173], 0
	v_mfma_f32_16x16x32_bf16 v[116:119], v[148:151], v[174:177], v[116:119]
	v_mfma_f32_16x16x32_bf16 v[100:103], v[144:147], v[178:181], 0
	v_mfma_f32_16x16x32_bf16 v[100:103], v[148:151], v[182:185], v[100:103]
	v_mfma_f32_16x16x32_bf16 v[84:87], v[144:147], v[186:189], 0
	v_mfma_f32_16x16x32_bf16 v[84:87], v[148:151], v[190:193], v[84:87]
	v_mfma_f32_16x16x32_bf16 v[68:71], v[144:147], v[198:201], 0
	v_mfma_f32_16x16x32_bf16 v[68:71], v[148:151], v[202:205], v[68:71]
	v_mfma_f32_16x16x32_bf16 v[112:115], v[152:155], v[170:173], 0
	v_mfma_f32_16x16x32_bf16 v[112:115], v[166:169], v[174:177], v[112:115]
	v_mfma_f32_16x16x32_bf16 v[96:99], v[152:155], v[178:181], 0
	v_mfma_f32_16x16x32_bf16 v[96:99], v[166:169], v[182:185], v[96:99]
	v_mfma_f32_16x16x32_bf16 v[80:83], v[152:155], v[186:189], 0
	v_mfma_f32_16x16x32_bf16 v[80:83], v[166:169], v[190:193], v[80:83]
	v_mfma_f32_16x16x32_bf16 v[64:67], v[152:155], v[198:201], 0
	v_mfma_f32_16x16x32_bf16 v[64:67], v[166:169], v[202:205], v[64:67]
	s_barrier
	s_add_i32 s18, s58, s50
	v_lshl_add_u64 v[206:207], s[52:53], 0, v[216:217]
	s_mov_b32 m0, s18
	ds_read_b128 v[170:173], v197 offset:16384
	ds_read_b128 v[174:177], v197 offset:17408
	ds_read_b128 v[178:181], v197 offset:18432
	ds_read_b128 v[182:185], v197 offset:19456
	ds_read_b128 v[186:189], v197 offset:20480
	ds_read_b128 v[190:193], v197 offset:21504
	ds_read_b128 v[198:201], v197 offset:22528
	ds_read_b128 v[202:205], v197 offset:23552
	global_load_lds_dwordx4 v[206:207], off
	s_add_i32 m0, s18, 0x2000
	s_add_u32 s18, s52, 0x164000
	v_lshl_add_u64 v[208:209], s[52:53], 0, v[160:161]
	s_addc_u32 s19, s53, 0
	s_add_i32 s58, s59, s50
	global_load_lds_dwordx4 v[208:209], off
	v_lshl_add_u64 v[210:211], s[18:19], 0, v[216:217]
	s_mov_b32 m0, s58
	v_lshl_add_u64 v[212:213], s[54:55], 0, v[158:159]
	global_load_lds_dwordx4 v[210:211], off
	v_lshl_add_u64 v[210:211], s[18:19], 0, v[160:161]
	s_add_i32 m0, s58, 0x2000
	s_nop 0
	global_load_lds_dwordx4 v[210:211], off
	v_lshl_add_u64 v[210:211], s[54:55], 0, v[156:157]
	s_mov_b32 m0, s76
	s_nop 0
	global_load_lds_dwordx4 v[210:211], off
	s_mov_b32 m0, s45
	s_nop 0
	global_load_lds_dwordx4 v[212:213], off
	s_waitcnt vmcnt(8) lgkmcnt(0)
	s_barrier
	v_mfma_f32_16x16x32_bf16 v[60:63], v[128:131], v[170:173], 0
	v_mfma_f32_16x16x32_bf16 v[60:63], v[132:135], v[174:177], v[60:63]
	v_mfma_f32_16x16x32_bf16 v[44:47], v[128:131], v[178:181], 0
	v_mfma_f32_16x16x32_bf16 v[44:47], v[132:135], v[182:185], v[44:47]
	v_mfma_f32_16x16x32_bf16 v[28:31], v[128:131], v[186:189], 0
	v_mfma_f32_16x16x32_bf16 v[28:31], v[132:135], v[190:193], v[28:31]
	v_mfma_f32_16x16x32_bf16 v[12:15], v[128:131], v[198:201], 0
	v_mfma_f32_16x16x32_bf16 v[12:15], v[132:135], v[202:205], v[12:15]
	v_mfma_f32_16x16x32_bf16 v[56:59], v[136:139], v[170:173], 0
	v_mfma_f32_16x16x32_bf16 v[56:59], v[140:143], v[174:177], v[56:59]
	v_mfma_f32_16x16x32_bf16 v[40:43], v[136:139], v[178:181], 0
	v_mfma_f32_16x16x32_bf16 v[40:43], v[140:143], v[182:185], v[40:43]
	v_mfma_f32_16x16x32_bf16 v[24:27], v[136:139], v[186:189], 0
	v_mfma_f32_16x16x32_bf16 v[24:27], v[140:143], v[190:193], v[24:27]
	v_mfma_f32_16x16x32_bf16 v[8:11], v[136:139], v[198:201], 0
	v_mfma_f32_16x16x32_bf16 v[8:11], v[140:143], v[202:205], v[8:11]
	v_mfma_f32_16x16x32_bf16 v[52:55], v[144:147], v[170:173], 0
	v_mfma_f32_16x16x32_bf16 v[52:55], v[148:151], v[174:177], v[52:55]
	v_mfma_f32_16x16x32_bf16 v[36:39], v[144:147], v[178:181], 0
	v_mfma_f32_16x16x32_bf16 v[36:39], v[148:151], v[182:185], v[36:39]
	v_mfma_f32_16x16x32_bf16 v[20:23], v[144:147], v[186:189], 0
	v_mfma_f32_16x16x32_bf16 v[20:23], v[148:151], v[190:193], v[20:23]
	v_mfma_f32_16x16x32_bf16 v[4:7], v[144:147], v[198:201], 0
	v_mfma_f32_16x16x32_bf16 v[4:7], v[148:151], v[202:205], v[4:7]
	v_mfma_f32_16x16x32_bf16 v[48:51], v[152:155], v[170:173], 0
	v_mfma_f32_16x16x32_bf16 v[48:51], v[166:169], v[174:177], v[48:51]
	v_mfma_f32_16x16x32_bf16 v[32:35], v[152:155], v[178:181], 0
	v_mfma_f32_16x16x32_bf16 v[32:35], v[166:169], v[182:185], v[32:35]
	v_mfma_f32_16x16x32_bf16 v[16:19], v[152:155], v[186:189], 0
	v_mfma_f32_16x16x32_bf16 v[16:19], v[166:169], v[190:193], v[16:19]
	v_mfma_f32_16x16x32_bf16 v[0:3], v[152:155], v[198:201], 0
	v_mfma_f32_16x16x32_bf16 v[0:3], v[166:169], v[202:205], v[0:3]
	s_barrier
	s_add_i32 s58, 0, 0x18000
	s_add_i32 s59, 0, 0x1c000
	v_add_u32_e32 v140, s58, v195
	v_add_u32_e32 v166, s59, v195
	ds_read_b128 v[128:131], v140
	ds_read_b128 v[132:135], v140 offset:1024
	ds_read_b128 v[136:139], v140 offset:2048
	ds_read_b128 v[140:143], v140 offset:3072
	ds_read_b128 v[144:147], v166
	ds_read_b128 v[148:151], v166 offset:1024
	ds_read_b128 v[152:155], v166 offset:2048
	ds_read_b128 v[166:169], v166 offset:3072
	s_add_u32 s18, s54, 0x164000
	s_addc_u32 s19, s55, 0
	s_mov_b32 m0, s64
	v_lshl_add_u64 v[214:215], s[18:19], 0, v[156:157]
	ds_read_b128 v[170:173], v197 offset:32768
	ds_read_b128 v[174:177], v197 offset:33792
	ds_read_b128 v[178:181], v197 offset:34816
	ds_read_b128 v[182:185], v197 offset:35840
	ds_read_b128 v[186:189], v197 offset:36864
	ds_read_b128 v[190:193], v197 offset:37888
	ds_read_b128 v[198:201], v197 offset:38912
	ds_read_b128 v[202:205], v197 offset:39936
	global_load_lds_dwordx4 v[214:215], off
	v_lshl_add_u64 v[214:215], s[18:19], 0, v[158:159]
	s_mov_b32 m0, s65
	s_nop 0
	global_load_lds_dwordx4 v[214:215], off
	s_waitcnt vmcnt(8) lgkmcnt(0)
	s_barrier
	v_mfma_f32_16x16x32_bf16 v[124:127], v[128:131], v[170:173], v[124:127]
	v_mfma_f32_16x16x32_bf16 v[124:127], v[132:135], v[174:177], v[124:127]
	v_mfma_f32_16x16x32_bf16 v[108:111], v[128:131], v[178:181], v[108:111]
	v_mfma_f32_16x16x32_bf16 v[108:111], v[132:135], v[182:185], v[108:111]
	v_mfma_f32_16x16x32_bf16 v[92:95], v[128:131], v[186:189], v[92:95]
	v_mfma_f32_16x16x32_bf16 v[92:95], v[132:135], v[190:193], v[92:95]
	v_mfma_f32_16x16x32_bf16 v[76:79], v[128:131], v[198:201], v[76:79]
	v_mfma_f32_16x16x32_bf16 v[76:79], v[132:135], v[202:205], v[76:79]
	v_mfma_f32_16x16x32_bf16 v[120:123], v[136:139], v[170:173], v[120:123]
	v_mfma_f32_16x16x32_bf16 v[120:123], v[140:143], v[174:177], v[120:123]
	v_mfma_f32_16x16x32_bf16 v[104:107], v[136:139], v[178:181], v[104:107]
	v_mfma_f32_16x16x32_bf16 v[104:107], v[140:143], v[182:185], v[104:107]
	v_mfma_f32_16x16x32_bf16 v[88:91], v[136:139], v[186:189], v[88:91]
	v_mfma_f32_16x16x32_bf16 v[88:91], v[140:143], v[190:193], v[88:91]
	v_mfma_f32_16x16x32_bf16 v[72:75], v[136:139], v[198:201], v[72:75]
	v_mfma_f32_16x16x32_bf16 v[72:75], v[140:143], v[202:205], v[72:75]
	v_mfma_f32_16x16x32_bf16 v[116:119], v[144:147], v[170:173], v[116:119]
	v_mfma_f32_16x16x32_bf16 v[116:119], v[148:151], v[174:177], v[116:119]
	v_mfma_f32_16x16x32_bf16 v[100:103], v[144:147], v[178:181], v[100:103]
	v_mfma_f32_16x16x32_bf16 v[100:103], v[148:151], v[182:185], v[100:103]
	v_mfma_f32_16x16x32_bf16 v[84:87], v[144:147], v[186:189], v[84:87]
	v_mfma_f32_16x16x32_bf16 v[84:87], v[148:151], v[190:193], v[84:87]
	v_mfma_f32_16x16x32_bf16 v[68:71], v[144:147], v[198:201], v[68:71]
	v_mfma_f32_16x16x32_bf16 v[68:71], v[148:151], v[202:205], v[68:71]
	v_mfma_f32_16x16x32_bf16 v[112:115], v[152:155], v[170:173], v[112:115]
	v_mfma_f32_16x16x32_bf16 v[112:115], v[166:169], v[174:177], v[112:115]
	v_mfma_f32_16x16x32_bf16 v[96:99], v[152:155], v[178:181], v[96:99]
	v_mfma_f32_16x16x32_bf16 v[96:99], v[166:169], v[182:185], v[96:99]
	v_mfma_f32_16x16x32_bf16 v[80:83], v[152:155], v[186:189], v[80:83]
	v_mfma_f32_16x16x32_bf16 v[80:83], v[166:169], v[190:193], v[80:83]
	v_mfma_f32_16x16x32_bf16 v[64:67], v[152:155], v[198:201], v[64:67]
	v_mfma_f32_16x16x32_bf16 v[64:67], v[166:169], v[202:205], v[64:67]
	s_barrier
	s_add_i32 s18, s58, s50
	v_lshl_add_u64 v[206:207], v[206:207], 0, s[60:61]
	s_mov_b32 m0, s18
	ds_read_b128 v[170:173], v197 offset:49152
	ds_read_b128 v[174:177], v197 offset:50176
	ds_read_b128 v[178:181], v197 offset:51200
	ds_read_b128 v[182:185], v197 offset:52224
	ds_read_b128 v[186:189], v197 offset:53248
	ds_read_b128 v[190:193], v197 offset:54272
	ds_read_b128 v[198:201], v197 offset:55296
	ds_read_b128 v[202:205], v197 offset:56320
	global_load_lds_dwordx4 v[206:207], off
	s_add_i32 m0, s18, 0x2000
	s_add_u32 s18, s52, 0x164080
	v_lshl_add_u64 v[206:207], v[208:209], 0, s[60:61]
	s_addc_u32 s19, s53, 0
	s_add_i32 s52, s59, s50
	global_load_lds_dwordx4 v[206:207], off
	v_lshl_add_u64 v[206:207], s[18:19], 0, v[216:217]
	s_mov_b32 m0, s52
	s_nop 0
	global_load_lds_dwordx4 v[206:207], off
	v_lshl_add_u64 v[206:207], s[18:19], 0, v[160:161]
	s_add_i32 m0, s52, 0x2000
	s_nop 0
	global_load_lds_dwordx4 v[206:207], off
	v_lshl_add_u64 v[206:207], v[210:211], 0, s[60:61]
	s_mov_b32 m0, s85
	s_nop 0
	global_load_lds_dwordx4 v[206:207], off
	v_lshl_add_u64 v[206:207], v[212:213], 0, s[60:61]
	s_mov_b32 m0, s86
	s_nop 0
	global_load_lds_dwordx4 v[206:207], off
	s_waitcnt vmcnt(8) lgkmcnt(0)
	s_barrier
	v_mfma_f32_16x16x32_bf16 v[60:63], v[128:131], v[170:173], v[60:63]
	v_mfma_f32_16x16x32_bf16 v[60:63], v[132:135], v[174:177], v[60:63]
	v_mfma_f32_16x16x32_bf16 v[44:47], v[128:131], v[178:181], v[44:47]
	v_mfma_f32_16x16x32_bf16 v[44:47], v[132:135], v[182:185], v[44:47]
	v_mfma_f32_16x16x32_bf16 v[28:31], v[128:131], v[186:189], v[28:31]
	v_mfma_f32_16x16x32_bf16 v[28:31], v[132:135], v[190:193], v[28:31]
	v_mfma_f32_16x16x32_bf16 v[12:15], v[128:131], v[198:201], v[12:15]
	v_mfma_f32_16x16x32_bf16 v[12:15], v[132:135], v[202:205], v[12:15]
	v_mfma_f32_16x16x32_bf16 v[56:59], v[136:139], v[170:173], v[56:59]
	v_mfma_f32_16x16x32_bf16 v[56:59], v[140:143], v[174:177], v[56:59]
	v_mfma_f32_16x16x32_bf16 v[40:43], v[136:139], v[178:181], v[40:43]
	v_mfma_f32_16x16x32_bf16 v[40:43], v[140:143], v[182:185], v[40:43]
	v_mfma_f32_16x16x32_bf16 v[24:27], v[136:139], v[186:189], v[24:27]
	v_mfma_f32_16x16x32_bf16 v[24:27], v[140:143], v[190:193], v[24:27]
	v_mfma_f32_16x16x32_bf16 v[8:11], v[136:139], v[198:201], v[8:11]
	v_mfma_f32_16x16x32_bf16 v[8:11], v[140:143], v[202:205], v[8:11]
	v_mfma_f32_16x16x32_bf16 v[52:55], v[144:147], v[170:173], v[52:55]
	v_mfma_f32_16x16x32_bf16 v[52:55], v[148:151], v[174:177], v[52:55]
	v_mfma_f32_16x16x32_bf16 v[36:39], v[144:147], v[178:181], v[36:39]
	v_mfma_f32_16x16x32_bf16 v[36:39], v[148:151], v[182:185], v[36:39]
	v_mfma_f32_16x16x32_bf16 v[20:23], v[144:147], v[186:189], v[20:23]
	v_mfma_f32_16x16x32_bf16 v[20:23], v[148:151], v[190:193], v[20:23]
	v_mfma_f32_16x16x32_bf16 v[4:7], v[144:147], v[198:201], v[4:7]
	v_mfma_f32_16x16x32_bf16 v[4:7], v[148:151], v[202:205], v[4:7]
	v_mfma_f32_16x16x32_bf16 v[48:51], v[152:155], v[170:173], v[48:51]
	v_mfma_f32_16x16x32_bf16 v[48:51], v[166:169], v[174:177], v[48:51]
	v_mfma_f32_16x16x32_bf16 v[32:35], v[152:155], v[178:181], v[32:35]
	v_mfma_f32_16x16x32_bf16 v[32:35], v[166:169], v[182:185], v[32:35]
	v_mfma_f32_16x16x32_bf16 v[16:19], v[152:155], v[186:189], v[16:19]
	v_mfma_f32_16x16x32_bf16 v[16:19], v[166:169], v[190:193], v[16:19]
	v_mfma_f32_16x16x32_bf16 v[0:3], v[152:155], v[198:201], v[0:3]
	v_mfma_f32_16x16x32_bf16 v[0:3], v[166:169], v[202:205], v[0:3]
	s_barrier
	s_add_i32 s95, s95, 2
	s_add_u32 s93, s93, 0x100
	s_addc_u32 s94, s94, 0
	s_cmpk_gt_u32 s95, 0x55
	s_mov_b64 s[18:19], s[22:23]
	s_cbranch_scc0 .LBB0_2081
	s_branch .Lzexit_7
.LBB0_2081:
	s_add_u32 s22, s18, 0x100
	s_addc_u32 s23, s19, 0
	s_add_i32 s58, 0, 0x10000
	s_cmpk_eq_i32 s95, 0x54
	s_cselect_b32 s55, s7, s23
	s_cselect_b32 s54, s6, s22
	s_cselect_b32 s53, s17, s94
	s_cselect_b32 s52, s16, s93
	s_add_i32 s59, 0, 0x14000
	v_add_u32_e32 v140, s58, v195
	v_add_u32_e32 v166, s59, v195
	ds_read_b128 v[128:131], v140
	ds_read_b128 v[132:135], v140 offset:1024
	ds_read_b128 v[136:139], v140 offset:2048
	ds_read_b128 v[140:143], v140 offset:3072
	ds_read_b128 v[144:147], v166
	ds_read_b128 v[148:151], v166 offset:1024
	ds_read_b128 v[152:155], v166 offset:2048
	ds_read_b128 v[166:169], v166 offset:3072
	v_lshl_add_u64 v[206:207], s[18:19], 0, v[162:163]
	s_add_i32 m0, s76, 0xc000
	ds_read_b128 v[170:173], v197
	ds_read_b128 v[174:177], v197 offset:1024
	ds_read_b128 v[178:181], v197 offset:2048
	ds_read_b128 v[182:185], v197 offset:3072
	ds_read_b128 v[186:189], v197 offset:4096
	ds_read_b128 v[190:193], v197 offset:5120
	ds_read_b128 v[198:201], v197 offset:6144
	ds_read_b128 v[202:205], v197 offset:7168
	global_load_lds_dwordx4 v[206:207], off
	v_lshl_add_u64 v[206:207], s[18:19], 0, v[164:165]
	s_add_i32 m0, s76, 0xe000
	s_nop 0
	global_load_lds_dwordx4 v[206:207], off
	s_waitcnt vmcnt(8) lgkmcnt(0)
	s_barrier
	v_mfma_f32_16x16x32_bf16 v[124:127], v[128:131], v[170:173], v[124:127]
	v_mfma_f32_16x16x32_bf16 v[124:127], v[132:135], v[174:177], v[124:127]
	v_mfma_f32_16x16x32_bf16 v[108:111], v[128:131], v[178:181], v[108:111]
	v_mfma_f32_16x16x32_bf16 v[108:111], v[132:135], v[182:185], v[108:111]
	v_mfma_f32_16x16x32_bf16 v[92:95], v[128:131], v[186:189], v[92:95]
	v_mfma_f32_16x16x32_bf16 v[92:95], v[132:135], v[190:193], v[92:95]
	v_mfma_f32_16x16x32_bf16 v[76:79], v[128:131], v[198:201], v[76:79]
	v_mfma_f32_16x16x32_bf16 v[76:79], v[132:135], v[202:205], v[76:79]
	v_mfma_f32_16x16x32_bf16 v[120:123], v[136:139], v[170:173], v[120:123]
	v_mfma_f32_16x16x32_bf16 v[120:123], v[140:143], v[174:177], v[120:123]
	v_mfma_f32_16x16x32_bf16 v[104:107], v[136:139], v[178:181], v[104:107]
	v_mfma_f32_16x16x32_bf16 v[104:107], v[140:143], v[182:185], v[104:107]
	v_mfma_f32_16x16x32_bf16 v[88:91], v[136:139], v[186:189], v[88:91]
	v_mfma_f32_16x16x32_bf16 v[88:91], v[140:143], v[190:193], v[88:91]
	v_mfma_f32_16x16x32_bf16 v[72:75], v[136:139], v[198:201], v[72:75]
	v_mfma_f32_16x16x32_bf16 v[72:75], v[140:143], v[202:205], v[72:75]
	v_mfma_f32_16x16x32_bf16 v[116:119], v[144:147], v[170:173], v[116:119]
	v_mfma_f32_16x16x32_bf16 v[116:119], v[148:151], v[174:177], v[116:119]
	v_mfma_f32_16x16x32_bf16 v[100:103], v[144:147], v[178:181], v[100:103]
	v_mfma_f32_16x16x32_bf16 v[100:103], v[148:151], v[182:185], v[100:103]
	v_mfma_f32_16x16x32_bf16 v[84:87], v[144:147], v[186:189], v[84:87]
	v_mfma_f32_16x16x32_bf16 v[84:87], v[148:151], v[190:193], v[84:87]
	v_mfma_f32_16x16x32_bf16 v[68:71], v[144:147], v[198:201], v[68:71]
	v_mfma_f32_16x16x32_bf16 v[68:71], v[148:151], v[202:205], v[68:71]
	v_mfma_f32_16x16x32_bf16 v[112:115], v[152:155], v[170:173], v[112:115]
	v_mfma_f32_16x16x32_bf16 v[112:115], v[166:169], v[174:177], v[112:115]
	v_mfma_f32_16x16x32_bf16 v[96:99], v[152:155], v[178:181], v[96:99]
	v_mfma_f32_16x16x32_bf16 v[96:99], v[166:169], v[182:185], v[96:99]
	v_mfma_f32_16x16x32_bf16 v[80:83], v[152:155], v[186:189], v[80:83]
	v_mfma_f32_16x16x32_bf16 v[80:83], v[166:169], v[190:193], v[80:83]
	v_mfma_f32_16x16x32_bf16 v[64:67], v[152:155], v[198:201], v[64:67]
	v_mfma_f32_16x16x32_bf16 v[64:67], v[166:169], v[202:205], v[64:67]
	s_barrier
	s_add_i32 s18, s58, s50
	v_lshl_add_u64 v[206:207], s[52:53], 0, v[216:217]
	s_mov_b32 m0, s18
	ds_read_b128 v[170:173], v197 offset:16384
	ds_read_b128 v[174:177], v197 offset:17408
	ds_read_b128 v[178:181], v197 offset:18432
	ds_read_b128 v[182:185], v197 offset:19456
	ds_read_b128 v[186:189], v197 offset:20480
	ds_read_b128 v[190:193], v197 offset:21504
	ds_read_b128 v[198:201], v197 offset:22528
	ds_read_b128 v[202:205], v197 offset:23552
	global_load_lds_dwordx4 v[206:207], off
	s_add_i32 m0, s18, 0x2000
	s_add_u32 s18, s52, 0x164000
	v_lshl_add_u64 v[208:209], s[52:53], 0, v[160:161]
	s_addc_u32 s19, s53, 0
	s_add_i32 s58, s59, s50
	global_load_lds_dwordx4 v[208:209], off
	v_lshl_add_u64 v[210:211], s[18:19], 0, v[216:217]
	s_mov_b32 m0, s58
	v_lshl_add_u64 v[212:213], s[54:55], 0, v[158:159]
	global_load_lds_dwordx4 v[210:211], off
	v_lshl_add_u64 v[210:211], s[18:19], 0, v[160:161]
	s_add_i32 m0, s58, 0x2000
	s_nop 0
	global_load_lds_dwordx4 v[210:211], off
	v_lshl_add_u64 v[210:211], s[54:55], 0, v[156:157]
	s_mov_b32 m0, s76
	s_nop 0
	global_load_lds_dwordx4 v[210:211], off
	s_mov_b32 m0, s45
	s_nop 0
	global_load_lds_dwordx4 v[212:213], off
	s_waitcnt vmcnt(8) lgkmcnt(0)
	s_barrier
	v_mfma_f32_16x16x32_bf16 v[60:63], v[128:131], v[170:173], v[60:63]
	v_mfma_f32_16x16x32_bf16 v[60:63], v[132:135], v[174:177], v[60:63]
	v_mfma_f32_16x16x32_bf16 v[44:47], v[128:131], v[178:181], v[44:47]
	v_mfma_f32_16x16x32_bf16 v[44:47], v[132:135], v[182:185], v[44:47]
	v_mfma_f32_16x16x32_bf16 v[28:31], v[128:131], v[186:189], v[28:31]
	v_mfma_f32_16x16x32_bf16 v[28:31], v[132:135], v[190:193], v[28:31]
	v_mfma_f32_16x16x32_bf16 v[12:15], v[128:131], v[198:201], v[12:15]
	v_mfma_f32_16x16x32_bf16 v[12:15], v[132:135], v[202:205], v[12:15]
	v_mfma_f32_16x16x32_bf16 v[56:59], v[136:139], v[170:173], v[56:59]
	v_mfma_f32_16x16x32_bf16 v[56:59], v[140:143], v[174:177], v[56:59]
	v_mfma_f32_16x16x32_bf16 v[40:43], v[136:139], v[178:181], v[40:43]
	v_mfma_f32_16x16x32_bf16 v[40:43], v[140:143], v[182:185], v[40:43]
	v_mfma_f32_16x16x32_bf16 v[24:27], v[136:139], v[186:189], v[24:27]
	v_mfma_f32_16x16x32_bf16 v[24:27], v[140:143], v[190:193], v[24:27]
	v_mfma_f32_16x16x32_bf16 v[8:11], v[136:139], v[198:201], v[8:11]
	v_mfma_f32_16x16x32_bf16 v[8:11], v[140:143], v[202:205], v[8:11]
	v_mfma_f32_16x16x32_bf16 v[52:55], v[144:147], v[170:173], v[52:55]
	v_mfma_f32_16x16x32_bf16 v[52:55], v[148:151], v[174:177], v[52:55]
	v_mfma_f32_16x16x32_bf16 v[36:39], v[144:147], v[178:181], v[36:39]
	v_mfma_f32_16x16x32_bf16 v[36:39], v[148:151], v[182:185], v[36:39]
	v_mfma_f32_16x16x32_bf16 v[20:23], v[144:147], v[186:189], v[20:23]
	v_mfma_f32_16x16x32_bf16 v[20:23], v[148:151], v[190:193], v[20:23]
	v_mfma_f32_16x16x32_bf16 v[4:7], v[144:147], v[198:201], v[4:7]
	v_mfma_f32_16x16x32_bf16 v[4:7], v[148:151], v[202:205], v[4:7]
	v_mfma_f32_16x16x32_bf16 v[48:51], v[152:155], v[170:173], v[48:51]
	v_mfma_f32_16x16x32_bf16 v[48:51], v[166:169], v[174:177], v[48:51]
	v_mfma_f32_16x16x32_bf16 v[32:35], v[152:155], v[178:181], v[32:35]
	v_mfma_f32_16x16x32_bf16 v[32:35], v[166:169], v[182:185], v[32:35]
	v_mfma_f32_16x16x32_bf16 v[16:19], v[152:155], v[186:189], v[16:19]
	v_mfma_f32_16x16x32_bf16 v[16:19], v[166:169], v[190:193], v[16:19]
	v_mfma_f32_16x16x32_bf16 v[0:3], v[152:155], v[198:201], v[0:3]
	v_mfma_f32_16x16x32_bf16 v[0:3], v[166:169], v[202:205], v[0:3]
	s_barrier
	s_add_i32 s58, 0, 0x18000
	s_add_i32 s59, 0, 0x1c000
	v_add_u32_e32 v140, s58, v195
	v_add_u32_e32 v166, s59, v195
	ds_read_b128 v[128:131], v140
	ds_read_b128 v[132:135], v140 offset:1024
	ds_read_b128 v[136:139], v140 offset:2048
	ds_read_b128 v[140:143], v140 offset:3072
	ds_read_b128 v[144:147], v166
	ds_read_b128 v[148:151], v166 offset:1024
	ds_read_b128 v[152:155], v166 offset:2048
	ds_read_b128 v[166:169], v166 offset:3072
	s_add_u32 s18, s54, 0x164000
	s_addc_u32 s19, s55, 0
	s_mov_b32 m0, s64
	v_lshl_add_u64 v[214:215], s[18:19], 0, v[156:157]
	ds_read_b128 v[170:173], v197 offset:32768
	ds_read_b128 v[174:177], v197 offset:33792
	ds_read_b128 v[178:181], v197 offset:34816
	ds_read_b128 v[182:185], v197 offset:35840
	ds_read_b128 v[186:189], v197 offset:36864
	ds_read_b128 v[190:193], v197 offset:37888
	ds_read_b128 v[198:201], v197 offset:38912
	ds_read_b128 v[202:205], v197 offset:39936
	global_load_lds_dwordx4 v[214:215], off
	v_lshl_add_u64 v[214:215], s[18:19], 0, v[158:159]
	s_mov_b32 m0, s65
	s_nop 0
	global_load_lds_dwordx4 v[214:215], off
	s_waitcnt vmcnt(8) lgkmcnt(0)
	s_barrier
	v_mfma_f32_16x16x32_bf16 v[124:127], v[128:131], v[170:173], v[124:127]
	v_mfma_f32_16x16x32_bf16 v[124:127], v[132:135], v[174:177], v[124:127]
	v_mfma_f32_16x16x32_bf16 v[108:111], v[128:131], v[178:181], v[108:111]
	v_mfma_f32_16x16x32_bf16 v[108:111], v[132:135], v[182:185], v[108:111]
	v_mfma_f32_16x16x32_bf16 v[92:95], v[128:131], v[186:189], v[92:95]
	v_mfma_f32_16x16x32_bf16 v[92:95], v[132:135], v[190:193], v[92:95]
	v_mfma_f32_16x16x32_bf16 v[76:79], v[128:131], v[198:201], v[76:79]
	v_mfma_f32_16x16x32_bf16 v[76:79], v[132:135], v[202:205], v[76:79]
	v_mfma_f32_16x16x32_bf16 v[120:123], v[136:139], v[170:173], v[120:123]
	v_mfma_f32_16x16x32_bf16 v[120:123], v[140:143], v[174:177], v[120:123]
	v_mfma_f32_16x16x32_bf16 v[104:107], v[136:139], v[178:181], v[104:107]
	v_mfma_f32_16x16x32_bf16 v[104:107], v[140:143], v[182:185], v[104:107]
	v_mfma_f32_16x16x32_bf16 v[88:91], v[136:139], v[186:189], v[88:91]
	v_mfma_f32_16x16x32_bf16 v[88:91], v[140:143], v[190:193], v[88:91]
	v_mfma_f32_16x16x32_bf16 v[72:75], v[136:139], v[198:201], v[72:75]
	v_mfma_f32_16x16x32_bf16 v[72:75], v[140:143], v[202:205], v[72:75]
	v_mfma_f32_16x16x32_bf16 v[116:119], v[144:147], v[170:173], v[116:119]
	v_mfma_f32_16x16x32_bf16 v[116:119], v[148:151], v[174:177], v[116:119]
	v_mfma_f32_16x16x32_bf16 v[100:103], v[144:147], v[178:181], v[100:103]
	v_mfma_f32_16x16x32_bf16 v[100:103], v[148:151], v[182:185], v[100:103]
	v_mfma_f32_16x16x32_bf16 v[84:87], v[144:147], v[186:189], v[84:87]
	v_mfma_f32_16x16x32_bf16 v[84:87], v[148:151], v[190:193], v[84:87]
	v_mfma_f32_16x16x32_bf16 v[68:71], v[144:147], v[198:201], v[68:71]
	v_mfma_f32_16x16x32_bf16 v[68:71], v[148:151], v[202:205], v[68:71]
	v_mfma_f32_16x16x32_bf16 v[112:115], v[152:155], v[170:173], v[112:115]
	v_mfma_f32_16x16x32_bf16 v[112:115], v[166:169], v[174:177], v[112:115]
	v_mfma_f32_16x16x32_bf16 v[96:99], v[152:155], v[178:181], v[96:99]
	v_mfma_f32_16x16x32_bf16 v[96:99], v[166:169], v[182:185], v[96:99]
	v_mfma_f32_16x16x32_bf16 v[80:83], v[152:155], v[186:189], v[80:83]
	v_mfma_f32_16x16x32_bf16 v[80:83], v[166:169], v[190:193], v[80:83]
	v_mfma_f32_16x16x32_bf16 v[64:67], v[152:155], v[198:201], v[64:67]
	v_mfma_f32_16x16x32_bf16 v[64:67], v[166:169], v[202:205], v[64:67]
	s_barrier
	s_add_i32 s18, s58, s50
	v_lshl_add_u64 v[206:207], v[206:207], 0, s[60:61]
	s_mov_b32 m0, s18
	ds_read_b128 v[170:173], v197 offset:49152
	ds_read_b128 v[174:177], v197 offset:50176
	ds_read_b128 v[178:181], v197 offset:51200
	ds_read_b128 v[182:185], v197 offset:52224
	ds_read_b128 v[186:189], v197 offset:53248
	ds_read_b128 v[190:193], v197 offset:54272
	ds_read_b128 v[198:201], v197 offset:55296
	ds_read_b128 v[202:205], v197 offset:56320
	global_load_lds_dwordx4 v[206:207], off
	s_add_i32 m0, s18, 0x2000
	s_add_u32 s18, s52, 0x164080
	v_lshl_add_u64 v[206:207], v[208:209], 0, s[60:61]
	s_addc_u32 s19, s53, 0
	s_add_i32 s52, s59, s50
	global_load_lds_dwordx4 v[206:207], off
	v_lshl_add_u64 v[206:207], s[18:19], 0, v[216:217]
	s_mov_b32 m0, s52
	s_nop 0
	global_load_lds_dwordx4 v[206:207], off
	v_lshl_add_u64 v[206:207], s[18:19], 0, v[160:161]
	s_add_i32 m0, s52, 0x2000
	s_nop 0
	global_load_lds_dwordx4 v[206:207], off
	v_lshl_add_u64 v[206:207], v[210:211], 0, s[60:61]
	s_mov_b32 m0, s85
	s_nop 0
	global_load_lds_dwordx4 v[206:207], off
	v_lshl_add_u64 v[206:207], v[212:213], 0, s[60:61]
	s_mov_b32 m0, s86
	s_nop 0
	global_load_lds_dwordx4 v[206:207], off
	s_waitcnt vmcnt(8) lgkmcnt(0)
	s_barrier
	v_mfma_f32_16x16x32_bf16 v[60:63], v[128:131], v[170:173], v[60:63]
	v_mfma_f32_16x16x32_bf16 v[60:63], v[132:135], v[174:177], v[60:63]
	v_mfma_f32_16x16x32_bf16 v[44:47], v[128:131], v[178:181], v[44:47]
	v_mfma_f32_16x16x32_bf16 v[44:47], v[132:135], v[182:185], v[44:47]
	v_mfma_f32_16x16x32_bf16 v[28:31], v[128:131], v[186:189], v[28:31]
	v_mfma_f32_16x16x32_bf16 v[28:31], v[132:135], v[190:193], v[28:31]
	v_mfma_f32_16x16x32_bf16 v[12:15], v[128:131], v[198:201], v[12:15]
	v_mfma_f32_16x16x32_bf16 v[12:15], v[132:135], v[202:205], v[12:15]
	v_mfma_f32_16x16x32_bf16 v[56:59], v[136:139], v[170:173], v[56:59]
	v_mfma_f32_16x16x32_bf16 v[56:59], v[140:143], v[174:177], v[56:59]
	v_mfma_f32_16x16x32_bf16 v[40:43], v[136:139], v[178:181], v[40:43]
	v_mfma_f32_16x16x32_bf16 v[40:43], v[140:143], v[182:185], v[40:43]
	v_mfma_f32_16x16x32_bf16 v[24:27], v[136:139], v[186:189], v[24:27]
	v_mfma_f32_16x16x32_bf16 v[24:27], v[140:143], v[190:193], v[24:27]
	v_mfma_f32_16x16x32_bf16 v[8:11], v[136:139], v[198:201], v[8:11]
	v_mfma_f32_16x16x32_bf16 v[8:11], v[140:143], v[202:205], v[8:11]
	v_mfma_f32_16x16x32_bf16 v[52:55], v[144:147], v[170:173], v[52:55]
	v_mfma_f32_16x16x32_bf16 v[52:55], v[148:151], v[174:177], v[52:55]
	v_mfma_f32_16x16x32_bf16 v[36:39], v[144:147], v[178:181], v[36:39]
	v_mfma_f32_16x16x32_bf16 v[36:39], v[148:151], v[182:185], v[36:39]
	v_mfma_f32_16x16x32_bf16 v[20:23], v[144:147], v[186:189], v[20:23]
	v_mfma_f32_16x16x32_bf16 v[20:23], v[148:151], v[190:193], v[20:23]
	v_mfma_f32_16x16x32_bf16 v[4:7], v[144:147], v[198:201], v[4:7]
	v_mfma_f32_16x16x32_bf16 v[4:7], v[148:151], v[202:205], v[4:7]
	v_mfma_f32_16x16x32_bf16 v[48:51], v[152:155], v[170:173], v[48:51]
	v_mfma_f32_16x16x32_bf16 v[48:51], v[166:169], v[174:177], v[48:51]
	v_mfma_f32_16x16x32_bf16 v[32:35], v[152:155], v[178:181], v[32:35]
	v_mfma_f32_16x16x32_bf16 v[32:35], v[166:169], v[182:185], v[32:35]
	v_mfma_f32_16x16x32_bf16 v[16:19], v[152:155], v[186:189], v[16:19]
	v_mfma_f32_16x16x32_bf16 v[16:19], v[166:169], v[190:193], v[16:19]
	v_mfma_f32_16x16x32_bf16 v[0:3], v[152:155], v[198:201], v[0:3]
	v_mfma_f32_16x16x32_bf16 v[0:3], v[166:169], v[202:205], v[0:3]
	s_barrier
	s_add_i32 s95, s95, 2
	s_add_u32 s93, s93, 0x100
	s_addc_u32 s94, s94, 0
	s_cmpk_gt_u32 s95, 0x55
	s_mov_b64 s[18:19], s[22:23]
	s_cbranch_scc0 .LBB0_2081
